# each MFMA block signals its trailing s_barrier 4 MFMAs early (s_setprio 2 on the tail) in all 8 K-loops
# baseline (speedup 1.0000x reference)
; #define PG8_STAGE(bufoff, gbase, voff) do { _Pragma("unroll") for (int _i = 0; _i < 2; ++_i) \
;         __builtin_amdgcn_global_load_lds((const unsigned*)((const char*)(gbase) + (voff)[_i]), (PG8_LAS unsigned*)(lds + (bufoff) + ldsw + _i * 8192), 16, 0, 0); } while (0)
; #define PG8_LDA(dst, b, h) do { _Pragma("unroll") for (int m = 0; m < 4; ++m) _Pragma("unroll") for (int k = 0; k < 2; ++k) dst[m][k] = *(const PG8_LAS bf16x8*)(lds + PG8_SA(b, h) + aoff + m * 2048 + k * 1024); } while (0)
; #define PG8_LDB(dst, b, h) do { _Pragma("unroll") for (int n = 0; n < 2; ++n) _Pragma("unroll") for (int k = 0; k < 2; ++k) dst[n][k] = *(const PG8_LAS bf16x8*)(lds + PG8_SB(b, h) + boff + n * 2048 + k * 1024); } while (0)
; #define PG8_MMA(ai, bj, At, Bt) do { __builtin_amdgcn_s_setprio(1); _Pragma("unroll") for (int m = 0; m < 4; ++m) _Pragma("unroll") for (int n = 0; n < 2; ++n) _Pragma("unroll") for (int k = 0; k < 2; ++k) \
;         acc[ai][bj][m][n] = __builtin_amdgcn_mfma_f32_16x16x32_bf16(Bt[n][k], At[m][k], acc[ai][bj][m][n], 0, 0, 0); __builtin_amdgcn_s_setprio(0); } while (0)
; #define PG8_WAIT_V(n) asm volatile("s_waitcnt vmcnt(" #n ")" ::: "memory")
; template <class Epi, class Sched, bool ALIGN_EPI = false, bool SP2 = false>
; __device__ __forceinline__ void gemm_phase(PG8_LAS unsigned char* lds, const Gemm g, const Sched& S, const Epi& E, int wv) {
;     ...
;         const char* nA = has_next ? (const char*)g.A + (size_t)nxt.pm * tstep : cA; const char* nB = has_next ? (const char*)g.Bt + (size_t)nxt.pn * tstep : cB;
;         for (int t = 0; t < nt; t += 2) {
;             const bool last = (t == nt - 2);
;             const char* a1 = cA + (size_t)(t + 1) * kstep;
;             const char* a2 = last ? nA : cA + (size_t)(t + 2) * kstep; const char* b2 = last ? nB : cB + (size_t)(t + 2) * kstep;
;             const char* a3 = a2 + kstep; const char* b3 = b2 + kstep;
;             if (last && has_next) S.a_ready(nxt);
;             if constexpr (SP2) {
;             PG8_LDB(B0, 0, 0); PG8_LDB(B1, 0, 1); PG8_SCHED; PG8_LDA(At, 0, 0); PG8_STAGE(PG8_SA(1, 1), a1 + hstep, voffA);
;             PG8_WAIT_V(8); PG8_WAIT_L(0); PG8_BAR; PG8_MMA(0, 0, At, B0); PG8_MMA(0, 1, At, B1); PG8_BAR; PG8_SCHED;
;             PG8_LDA(At, 0, 1); PG8_STAGE(PG8_SB(0, 0), b2, voffB); PG8_STAGE(PG8_SB(0, 1), b2 + hstep, voffB); PG8_STAGE(PG8_SA(0, 0), a2, voffA);
.LBB0_773:
	s_add_u32 s21, s42, 0xfffc0080
	s_addc_u32 s26, s43, -1
	s_add_i32 s28, 0, 0x10000
	s_cmp_eq_u32 s67, 12
	s_cselect_b32 s49, s13, s26
	s_cselect_b32 s48, s63, s21
	v_add_u32_e32 v138, s28, v141
	s_cselect_b32 s45, s15, s66
	s_cselect_b32 s44, s64, s65
	s_add_i32 s21, 0, 0x14000
	ds_read_b128 v[144:147], v138
	ds_read_b128 v[148:151], v138 offset:1024
	ds_read_b128 v[152:155], v138 offset:2048
	ds_read_b128 v[156:159], v138 offset:3072
	v_add_u32_e32 v138, s21, v141
	ds_read_b128 v[162:165], v138
	ds_read_b128 v[166:169], v138 offset:1024
	ds_read_b128 v[170:173], v138 offset:2048
	ds_read_b128 v[174:177], v138 offset:3072
	v_lshl_add_u64 v[138:139], s[42:43], 0, v[134:135]
	s_add_i32 m0, s51, 0xc000
	ds_read_b128 v[178:181], v143
	ds_read_b128 v[204:207], v143 offset:1024
	ds_read_b128 v[208:211], v143 offset:2048
	ds_read_b128 v[212:215], v143 offset:3072
	ds_read_b128 v[216:219], v143 offset:4096
	ds_read_b128 v[220:223], v143 offset:5120
	ds_read_b128 v[224:227], v143 offset:6144
	ds_read_b128 v[228:231], v143 offset:7168
	global_load_lds_dwordx4 v[138:139], off
	v_lshl_add_u64 v[138:139], s[42:43], 0, v[136:137]
	s_add_i32 m0, s51, 0xe000
	s_nop 0
	global_load_lds_dwordx4 v[138:139], off
	s_waitcnt vmcnt(8)
	s_waitcnt lgkmcnt(0)
	s_barrier
	s_setprio 1
	s_waitcnt lgkmcnt(0)
	v_mfma_f32_16x16x32_bf16 v[124:127], v[144:147], v[178:181], v[124:127]
	v_mfma_f32_16x16x32_bf16 v[120:123], v[152:155], v[178:181], v[120:123]
	v_mfma_f32_16x16x32_bf16 v[108:111], v[144:147], v[208:211], v[108:111]
	v_mfma_f32_16x16x32_bf16 v[104:107], v[152:155], v[208:211], v[104:107]
	v_mfma_f32_16x16x32_bf16 v[92:95], v[144:147], v[216:219], v[92:95]
	v_mfma_f32_16x16x32_bf16 v[88:91], v[152:155], v[216:219], v[88:91]
	v_mfma_f32_16x16x32_bf16 v[76:79], v[144:147], v[224:227], v[76:79]
	v_mfma_f32_16x16x32_bf16 v[72:75], v[152:155], v[224:227], v[72:75]
	v_mfma_f32_16x16x32_bf16 v[124:127], v[148:151], v[204:207], v[124:127]
	v_mfma_f32_16x16x32_bf16 v[120:123], v[156:159], v[204:207], v[120:123]
	v_mfma_f32_16x16x32_bf16 v[108:111], v[148:151], v[212:215], v[108:111]
	v_mfma_f32_16x16x32_bf16 v[104:107], v[156:159], v[212:215], v[104:107]
	v_mfma_f32_16x16x32_bf16 v[92:95], v[148:151], v[220:223], v[92:95]
	v_mfma_f32_16x16x32_bf16 v[88:91], v[156:159], v[220:223], v[88:91]
	v_mfma_f32_16x16x32_bf16 v[76:79], v[148:151], v[228:231], v[76:79]
	v_mfma_f32_16x16x32_bf16 v[72:75], v[156:159], v[228:231], v[72:75]
	s_setprio 0
	s_setprio 1
	v_mfma_f32_16x16x32_bf16 v[116:119], v[162:165], v[178:181], v[116:119]
	v_mfma_f32_16x16x32_bf16 v[112:115], v[170:173], v[178:181], v[112:115]
	v_mfma_f32_16x16x32_bf16 v[100:103], v[162:165], v[208:211], v[100:103]
	v_mfma_f32_16x16x32_bf16 v[96:99], v[170:173], v[208:211], v[96:99]
	v_mfma_f32_16x16x32_bf16 v[84:87], v[162:165], v[216:219], v[84:87]
	v_mfma_f32_16x16x32_bf16 v[80:83], v[170:173], v[216:219], v[80:83]
	v_mfma_f32_16x16x32_bf16 v[68:71], v[162:165], v[224:227], v[68:71]
	v_mfma_f32_16x16x32_bf16 v[64:67], v[170:173], v[224:227], v[64:67]
	v_mfma_f32_16x16x32_bf16 v[116:119], v[166:169], v[204:207], v[116:119]
	v_mfma_f32_16x16x32_bf16 v[112:115], v[174:177], v[204:207], v[112:115]
	v_mfma_f32_16x16x32_bf16 v[100:103], v[166:169], v[212:215], v[100:103]
	v_mfma_f32_16x16x32_bf16 v[96:99], v[174:177], v[212:215], v[96:99]
	s_setprio 2
	s_barrier
	v_mfma_f32_16x16x32_bf16 v[84:87], v[166:169], v[220:223], v[84:87]
	v_mfma_f32_16x16x32_bf16 v[80:83], v[174:177], v[220:223], v[80:83]
	v_mfma_f32_16x16x32_bf16 v[68:71], v[166:169], v[228:231], v[68:71]
	v_mfma_f32_16x16x32_bf16 v[64:67], v[174:177], v[228:231], v[64:67]
	s_setprio 0
	s_add_i32 s26, s28, s50
	v_lshl_add_u64 v[138:139], s[44:45], 0, v[160:161]
	s_mov_b32 m0, s26
	ds_read_b128 v[178:181], v143 offset:16384
	ds_read_b128 v[204:207], v143 offset:17408
	ds_read_b128 v[208:211], v143 offset:18432
	ds_read_b128 v[212:215], v143 offset:19456
	ds_read_b128 v[216:219], v143 offset:20480
	ds_read_b128 v[220:223], v143 offset:21504
	ds_read_b128 v[224:227], v143 offset:22528
	ds_read_b128 v[228:231], v143 offset:23552
	global_load_lds_dwordx4 v[138:139], off
	s_add_i32 m0, s26, 0x2000
	s_add_u32 s76, s44, 0x40000
	v_lshl_add_u64 v[232:233], s[44:45], 0, v[128:129]
	s_addc_u32 s77, s45, 0
	s_add_i32 s21, s21, s50
	global_load_lds_dwordx4 v[232:233], off
	v_lshl_add_u64 v[234:235], s[76:77], 0, v[160:161]
	s_mov_b32 m0, s21
	v_lshl_add_u64 v[236:237], s[48:49], 0, v[130:131]
	global_load_lds_dwordx4 v[234:235], off
	v_lshl_add_u64 v[234:235], s[76:77], 0, v[128:129]
	s_add_i32 m0, s21, 0x2000
	s_nop 0
	global_load_lds_dwordx4 v[234:235], off
	v_lshl_add_u64 v[234:235], s[48:49], 0, v[132:133]
	s_mov_b32 m0, s51
	s_nop 0
	global_load_lds_dwordx4 v[234:235], off
	s_mov_b32 m0, s52
	s_nop 0
	global_load_lds_dwordx4 v[236:237], off
	s_waitcnt vmcnt(8)
	s_waitcnt lgkmcnt(0)
	s_barrier
; #define PG8_STAGE(bufoff, gbase, voff) do { _Pragma("unroll") for (int _i = 0; _i < 2; ++_i) \
;         __builtin_amdgcn_global_load_lds((const unsigned*)((const char*)(gbase) + (voff)[_i]), (PG8_LAS unsigned*)(lds + (bufoff) + ldsw + _i * 8192), 16, 0, 0); } while (0)
; #define PG8_LDA(dst, b, h) do { _Pragma("unroll") for (int m = 0; m < 4; ++m) _Pragma("unroll") for (int k = 0; k < 2; ++k) dst[m][k] = *(const PG8_LAS bf16x8*)(lds + PG8_SA(b, h) + aoff + m * 2048 + k * 1024); } while (0)
; #define PG8_LDB(dst, b, h) do { _Pragma("unroll") for (int n = 0; n < 2; ++n) _Pragma("unroll") for (int k = 0; k < 2; ++k) dst[n][k] = *(const PG8_LAS bf16x8*)(lds + PG8_SB(b, h) + boff + n * 2048 + k * 1024); } while (0)
; #define PG8_MMA(ai, bj, At, Bt) do { __builtin_amdgcn_s_setprio(1); _Pragma("unroll") for (int m = 0; m < 4; ++m) _Pragma("unroll") for (int n = 0; n < 2; ++n) _Pragma("unroll") for (int k = 0; k < 2; ++k) \
;         acc[ai][bj][m][n] = __builtin_amdgcn_mfma_f32_16x16x32_bf16(Bt[n][k], At[m][k], acc[ai][bj][m][n], 0, 0, 0); __builtin_amdgcn_s_setprio(0); } while (0)
; #define PG8_WAIT_V(n) asm volatile("s_waitcnt vmcnt(" #n ")" ::: "memory")
; #define PG8_WAIT_L(n) asm volatile("s_waitcnt lgkmcnt(" #n ")" ::: "memory")
; #define PG8_BAR __builtin_amdgcn_s_barrier()
; #define PG8_SCHED __builtin_amdgcn_sched_barrier(0)
; template <class Epi, class Sched, bool ALIGN_EPI = false, bool SP2 = false>
; __device__ __forceinline__ void gemm_phase(PG8_LAS unsigned char* lds, const Gemm g, const Sched& S, const Epi& E, int wv) {
;     ...
;             PG8_WAIT_V(8); PG8_WAIT_L(0); PG8_BAR; PG8_MMA(1, 0, At, B0); PG8_MMA(1, 1, At, B1); PG8_BAR; PG8_SCHED;
;             PG8_LDB(B0, 1, 0); PG8_LDB(B1, 1, 1); PG8_SCHED; PG8_LDA(At, 1, 0); PG8_STAGE(PG8_SA(0, 1), a2 + hstep, voffA);
;             PG8_WAIT_V(8); PG8_WAIT_L(0); PG8_BAR; PG8_MMA(0, 0, At, B0); PG8_MMA(0, 1, At, B1); PG8_BAR; PG8_SCHED;
	s_setprio 1
	s_waitcnt lgkmcnt(0)
	v_mfma_f32_16x16x32_bf16 v[60:63], v[144:147], v[178:181], v[60:63]
	v_mfma_f32_16x16x32_bf16 v[56:59], v[152:155], v[178:181], v[56:59]
	v_mfma_f32_16x16x32_bf16 v[44:47], v[144:147], v[208:211], v[44:47]
	v_mfma_f32_16x16x32_bf16 v[40:43], v[152:155], v[208:211], v[40:43]
	v_mfma_f32_16x16x32_bf16 v[28:31], v[144:147], v[216:219], v[28:31]
	v_mfma_f32_16x16x32_bf16 v[24:27], v[152:155], v[216:219], v[24:27]
	v_mfma_f32_16x16x32_bf16 v[12:15], v[144:147], v[224:227], v[12:15]
	v_mfma_f32_16x16x32_bf16 v[8:11], v[152:155], v[224:227], v[8:11]
	v_mfma_f32_16x16x32_bf16 v[60:63], v[148:151], v[204:207], v[60:63]
	v_mfma_f32_16x16x32_bf16 v[56:59], v[156:159], v[204:207], v[56:59]
	v_mfma_f32_16x16x32_bf16 v[44:47], v[148:151], v[212:215], v[44:47]
	v_mfma_f32_16x16x32_bf16 v[40:43], v[156:159], v[212:215], v[40:43]
	v_mfma_f32_16x16x32_bf16 v[28:31], v[148:151], v[220:223], v[28:31]
	v_mfma_f32_16x16x32_bf16 v[24:27], v[156:159], v[220:223], v[24:27]
	v_mfma_f32_16x16x32_bf16 v[12:15], v[148:151], v[228:231], v[12:15]
	v_mfma_f32_16x16x32_bf16 v[8:11], v[156:159], v[228:231], v[8:11]
	s_setprio 0
	s_setprio 1
	v_mfma_f32_16x16x32_bf16 v[52:55], v[162:165], v[178:181], v[52:55]
	v_mfma_f32_16x16x32_bf16 v[48:51], v[170:173], v[178:181], v[48:51]
	v_mfma_f32_16x16x32_bf16 v[36:39], v[162:165], v[208:211], v[36:39]
	v_mfma_f32_16x16x32_bf16 v[32:35], v[170:173], v[208:211], v[32:35]
	v_mfma_f32_16x16x32_bf16 v[20:23], v[162:165], v[216:219], v[20:23]
	v_mfma_f32_16x16x32_bf16 v[16:19], v[170:173], v[216:219], v[16:19]
	v_mfma_f32_16x16x32_bf16 v[4:7], v[162:165], v[224:227], v[4:7]
	v_mfma_f32_16x16x32_bf16 v[0:3], v[170:173], v[224:227], v[0:3]
	v_mfma_f32_16x16x32_bf16 v[52:55], v[166:169], v[204:207], v[52:55]
	v_mfma_f32_16x16x32_bf16 v[48:51], v[174:177], v[204:207], v[48:51]
	v_mfma_f32_16x16x32_bf16 v[36:39], v[166:169], v[212:215], v[36:39]
	v_mfma_f32_16x16x32_bf16 v[32:35], v[174:177], v[212:215], v[32:35]
	s_setprio 2
	s_barrier
	v_mfma_f32_16x16x32_bf16 v[20:23], v[166:169], v[220:223], v[20:23]
	v_mfma_f32_16x16x32_bf16 v[16:19], v[174:177], v[220:223], v[16:19]
	v_mfma_f32_16x16x32_bf16 v[4:7], v[166:169], v[228:231], v[4:7]
	v_mfma_f32_16x16x32_bf16 v[0:3], v[174:177], v[228:231], v[0:3]
	s_setprio 0
	s_add_i32 s21, 0, 0x18000
	v_add_u32_e32 v140, s21, v141
	s_add_i32 s26, 0, 0x1c000
	ds_read_b128 v[144:147], v140
	ds_read_b128 v[148:151], v140 offset:1024
	ds_read_b128 v[152:155], v140 offset:2048
	ds_read_b128 v[156:159], v140 offset:3072
	v_add_u32_e32 v140, s26, v141
	ds_read_b128 v[162:165], v140
	ds_read_b128 v[166:169], v140 offset:1024
	ds_read_b128 v[170:173], v140 offset:2048
	ds_read_b128 v[174:177], v140 offset:3072
	s_add_u32 s48, s48, 0x40000
	s_addc_u32 s49, s49, 0
	s_mov_b32 m0, s53
	v_lshl_add_u64 v[238:239], s[48:49], 0, v[132:133]
	ds_read_b128 v[178:181], v143 offset:32768
	ds_read_b128 v[204:207], v143 offset:33792
	ds_read_b128 v[208:211], v143 offset:34816
	ds_read_b128 v[212:215], v143 offset:35840
	ds_read_b128 v[216:219], v143 offset:36864
	ds_read_b128 v[220:223], v143 offset:37888
	ds_read_b128 v[224:227], v143 offset:38912
	ds_read_b128 v[228:231], v143 offset:39936
	global_load_lds_dwordx4 v[238:239], off
	v_lshl_add_u64 v[238:239], s[48:49], 0, v[130:131]
	s_mov_b32 m0, s54
	s_nop 0
	global_load_lds_dwordx4 v[238:239], off
	s_waitcnt vmcnt(8)
	s_waitcnt lgkmcnt(0)
	s_barrier
	s_setprio 1
	s_waitcnt lgkmcnt(0)
	v_mfma_f32_16x16x32_bf16 v[124:127], v[144:147], v[178:181], v[124:127]
	v_mfma_f32_16x16x32_bf16 v[120:123], v[152:155], v[178:181], v[120:123]
	v_mfma_f32_16x16x32_bf16 v[108:111], v[144:147], v[208:211], v[108:111]
	v_mfma_f32_16x16x32_bf16 v[104:107], v[152:155], v[208:211], v[104:107]
	v_mfma_f32_16x16x32_bf16 v[92:95], v[144:147], v[216:219], v[92:95]
	v_mfma_f32_16x16x32_bf16 v[88:91], v[152:155], v[216:219], v[88:91]
	v_mfma_f32_16x16x32_bf16 v[76:79], v[144:147], v[224:227], v[76:79]
	v_mfma_f32_16x16x32_bf16 v[72:75], v[152:155], v[224:227], v[72:75]
	v_mfma_f32_16x16x32_bf16 v[124:127], v[148:151], v[204:207], v[124:127]
	v_mfma_f32_16x16x32_bf16 v[120:123], v[156:159], v[204:207], v[120:123]
	v_mfma_f32_16x16x32_bf16 v[108:111], v[148:151], v[212:215], v[108:111]
	v_mfma_f32_16x16x32_bf16 v[104:107], v[156:159], v[212:215], v[104:107]
	v_mfma_f32_16x16x32_bf16 v[92:95], v[148:151], v[220:223], v[92:95]
	v_mfma_f32_16x16x32_bf16 v[88:91], v[156:159], v[220:223], v[88:91]
	v_mfma_f32_16x16x32_bf16 v[76:79], v[148:151], v[228:231], v[76:79]
	v_mfma_f32_16x16x32_bf16 v[72:75], v[156:159], v[228:231], v[72:75]
	s_setprio 0
	s_setprio 1
	v_mfma_f32_16x16x32_bf16 v[116:119], v[162:165], v[178:181], v[116:119]
	v_mfma_f32_16x16x32_bf16 v[112:115], v[170:173], v[178:181], v[112:115]
	v_mfma_f32_16x16x32_bf16 v[100:103], v[162:165], v[208:211], v[100:103]
	v_mfma_f32_16x16x32_bf16 v[96:99], v[170:173], v[208:211], v[96:99]
	v_mfma_f32_16x16x32_bf16 v[84:87], v[162:165], v[216:219], v[84:87]
	v_mfma_f32_16x16x32_bf16 v[80:83], v[170:173], v[216:219], v[80:83]
	v_mfma_f32_16x16x32_bf16 v[68:71], v[162:165], v[224:227], v[68:71]
	v_mfma_f32_16x16x32_bf16 v[64:67], v[170:173], v[224:227], v[64:67]
	v_mfma_f32_16x16x32_bf16 v[116:119], v[166:169], v[204:207], v[116:119]
	v_mfma_f32_16x16x32_bf16 v[112:115], v[174:177], v[204:207], v[112:115]
	v_mfma_f32_16x16x32_bf16 v[100:103], v[166:169], v[212:215], v[100:103]
	v_mfma_f32_16x16x32_bf16 v[96:99], v[174:177], v[212:215], v[96:99]
	s_setprio 2
	s_barrier
; #define PG8_STAGE(bufoff, gbase, voff) do { _Pragma("unroll") for (int _i = 0; _i < 2; ++_i) \
;         __builtin_amdgcn_global_load_lds((const unsigned*)((const char*)(gbase) + (voff)[_i]), (PG8_LAS unsigned*)(lds + (bufoff) + ldsw + _i * 8192), 16, 0, 0); } while (0)
; #define PG8_LDA(dst, b, h) do { _Pragma("unroll") for (int m = 0; m < 4; ++m) _Pragma("unroll") for (int k = 0; k < 2; ++k) dst[m][k] = *(const PG8_LAS bf16x8*)(lds + PG8_SA(b, h) + aoff + m * 2048 + k * 1024); } while (0)
; #define PG8_MMA(ai, bj, At, Bt) do { __builtin_amdgcn_s_setprio(1); _Pragma("unroll") for (int m = 0; m < 4; ++m) _Pragma("unroll") for (int n = 0; n < 2; ++n) _Pragma("unroll") for (int k = 0; k < 2; ++k) \
;         acc[ai][bj][m][n] = __builtin_amdgcn_mfma_f32_16x16x32_bf16(Bt[n][k], At[m][k], acc[ai][bj][m][n], 0, 0, 0); __builtin_amdgcn_s_setprio(0); } while (0)
; #define PG8_WAIT_V(n) asm volatile("s_waitcnt vmcnt(" #n ")" ::: "memory")
; #define PG8_WAIT_L(n) asm volatile("s_waitcnt lgkmcnt(" #n ")" ::: "memory")
; #define PG8_BAR __builtin_amdgcn_s_barrier()
; #define PG8_SCHED __builtin_amdgcn_sched_barrier(0)
; template <class Epi, class Sched, bool ALIGN_EPI = false, bool SP2 = false>
; __device__ __forceinline__ void gemm_phase(PG8_LAS unsigned char* lds, const Gemm g, const Sched& S, const Epi& E, int wv) {
;     ...
;             PG8_LDA(At, 1, 1); PG8_STAGE(PG8_SB(1, 0), b3, voffB); PG8_STAGE(PG8_SB(1, 1), b3 + hstep, voffB); PG8_STAGE(PG8_SA(1, 0), a3, voffA);
;             PG8_WAIT_V(8); PG8_WAIT_L(0); PG8_BAR; PG8_MMA(1, 0, At, B0); PG8_MMA(1, 1, At, B1); PG8_BAR; PG8_SCHED;
;     ...
;         if constexpr (ALIGN_EPI) { if (wr == 0) PG8_BAR; }
	v_mfma_f32_16x16x32_bf16 v[84:87], v[166:169], v[220:223], v[84:87]
	v_mfma_f32_16x16x32_bf16 v[80:83], v[174:177], v[220:223], v[80:83]
	v_mfma_f32_16x16x32_bf16 v[68:71], v[166:169], v[228:231], v[68:71]
	v_mfma_f32_16x16x32_bf16 v[64:67], v[174:177], v[228:231], v[64:67]
	s_setprio 0
	s_add_i32 s21, s21, s50
	v_lshl_add_u64 v[138:139], v[138:139], 0, s[74:75]
	s_mov_b32 m0, s21
	ds_read_b128 v[178:181], v143 offset:49152
	ds_read_b128 v[204:207], v143 offset:50176
	ds_read_b128 v[208:211], v143 offset:51200
	ds_read_b128 v[212:215], v143 offset:52224
	ds_read_b128 v[216:219], v143 offset:53248
	ds_read_b128 v[220:223], v143 offset:54272
	ds_read_b128 v[224:227], v143 offset:55296
	ds_read_b128 v[228:231], v143 offset:56320
	global_load_lds_dwordx4 v[138:139], off
	s_add_i32 m0, s21, 0x2000
	s_add_u32 s44, s44, 0x40080
	v_lshl_add_u64 v[138:139], v[232:233], 0, s[74:75]
	s_addc_u32 s45, s45, 0
	s_add_i32 s21, s26, s50
	global_load_lds_dwordx4 v[138:139], off
	v_lshl_add_u64 v[138:139], s[44:45], 0, v[160:161]
	s_mov_b32 m0, s21
	s_nop 0
	global_load_lds_dwordx4 v[138:139], off
	v_lshl_add_u64 v[138:139], s[44:45], 0, v[128:129]
	s_add_i32 m0, s21, 0x2000
	s_nop 0
	global_load_lds_dwordx4 v[138:139], off
	v_lshl_add_u64 v[138:139], v[234:235], 0, s[74:75]
	s_mov_b32 m0, s60
	s_nop 0
	global_load_lds_dwordx4 v[138:139], off
	v_lshl_add_u64 v[138:139], v[236:237], 0, s[74:75]
	s_mov_b32 m0, s61
	s_nop 0
	global_load_lds_dwordx4 v[138:139], off
	s_waitcnt vmcnt(8)
	s_waitcnt lgkmcnt(0)
	s_barrier
	s_setprio 1
	s_waitcnt lgkmcnt(0)
	v_mfma_f32_16x16x32_bf16 v[60:63], v[144:147], v[178:181], v[60:63]
	v_mfma_f32_16x16x32_bf16 v[56:59], v[152:155], v[178:181], v[56:59]
	v_mfma_f32_16x16x32_bf16 v[44:47], v[144:147], v[208:211], v[44:47]
	v_mfma_f32_16x16x32_bf16 v[40:43], v[152:155], v[208:211], v[40:43]
	v_mfma_f32_16x16x32_bf16 v[28:31], v[144:147], v[216:219], v[28:31]
	v_mfma_f32_16x16x32_bf16 v[24:27], v[152:155], v[216:219], v[24:27]
	v_mfma_f32_16x16x32_bf16 v[12:15], v[144:147], v[224:227], v[12:15]
	v_mfma_f32_16x16x32_bf16 v[8:11], v[152:155], v[224:227], v[8:11]
	v_mfma_f32_16x16x32_bf16 v[60:63], v[148:151], v[204:207], v[60:63]
	v_mfma_f32_16x16x32_bf16 v[56:59], v[156:159], v[204:207], v[56:59]
	v_mfma_f32_16x16x32_bf16 v[44:47], v[148:151], v[212:215], v[44:47]
	v_mfma_f32_16x16x32_bf16 v[40:43], v[156:159], v[212:215], v[40:43]
	v_mfma_f32_16x16x32_bf16 v[28:31], v[148:151], v[220:223], v[28:31]
	v_mfma_f32_16x16x32_bf16 v[24:27], v[156:159], v[220:223], v[24:27]
	v_mfma_f32_16x16x32_bf16 v[12:15], v[148:151], v[228:231], v[12:15]
	v_mfma_f32_16x16x32_bf16 v[8:11], v[156:159], v[228:231], v[8:11]
	s_setprio 0
	s_setprio 1
	v_mfma_f32_16x16x32_bf16 v[52:55], v[162:165], v[178:181], v[52:55]
	v_mfma_f32_16x16x32_bf16 v[48:51], v[170:173], v[178:181], v[48:51]
	v_mfma_f32_16x16x32_bf16 v[36:39], v[162:165], v[208:211], v[36:39]
	v_mfma_f32_16x16x32_bf16 v[32:35], v[170:173], v[208:211], v[32:35]
	v_mfma_f32_16x16x32_bf16 v[20:23], v[162:165], v[216:219], v[20:23]
	v_mfma_f32_16x16x32_bf16 v[16:19], v[170:173], v[216:219], v[16:19]
	v_mfma_f32_16x16x32_bf16 v[4:7], v[162:165], v[224:227], v[4:7]
	v_mfma_f32_16x16x32_bf16 v[0:3], v[170:173], v[224:227], v[0:3]
	v_mfma_f32_16x16x32_bf16 v[52:55], v[166:169], v[204:207], v[52:55]
	v_mfma_f32_16x16x32_bf16 v[48:51], v[174:177], v[204:207], v[48:51]
	v_mfma_f32_16x16x32_bf16 v[36:39], v[166:169], v[212:215], v[36:39]
	v_mfma_f32_16x16x32_bf16 v[32:35], v[174:177], v[212:215], v[32:35]
	s_setprio 2
	s_barrier
	v_mfma_f32_16x16x32_bf16 v[20:23], v[166:169], v[220:223], v[20:23]
	v_mfma_f32_16x16x32_bf16 v[16:19], v[174:177], v[220:223], v[16:19]
	v_mfma_f32_16x16x32_bf16 v[4:7], v[166:169], v[228:231], v[4:7]
	v_mfma_f32_16x16x32_bf16 v[0:3], v[174:177], v[228:231], v[0:3]
	s_setprio 0
	s_add_i32 s67, s67, 2
	s_add_u32 s42, s42, 0x100
	s_addc_u32 s43, s43, 0
	s_add_u32 s65, s65, 0x100
	s_addc_u32 s66, s66, 0
	s_cmp_gt_u32 s67, 13
	s_cbranch_scc0 .LBB0_773
	s_and_b64 vcc, exec, s[10:11]
	s_cbranch_vccz .LBB0_776
	s_barrier

; #define PG8_STAGE(bufoff, gbase, voff) do { _Pragma("unroll") for (int _i = 0; _i < 2; ++_i) \
;         __builtin_amdgcn_global_load_lds((const unsigned*)((const char*)(gbase) + (voff)[_i]), (PG8_LAS unsigned*)(lds + (bufoff) + ldsw + _i * 8192), 16, 0, 0); } while (0)
; #define PG8_LDA(dst, b, h) do { _Pragma("unroll") for (int m = 0; m < 4; ++m) _Pragma("unroll") for (int k = 0; k < 2; ++k) dst[m][k] = *(const PG8_LAS bf16x8*)(lds + PG8_SA(b, h) + aoff + m * 2048 + k * 1024); } while (0)
; #define PG8_LDB(dst, b, h) do { _Pragma("unroll") for (int n = 0; n < 2; ++n) _Pragma("unroll") for (int k = 0; k < 2; ++k) dst[n][k] = *(const PG8_LAS bf16x8*)(lds + PG8_SB(b, h) + boff + n * 2048 + k * 1024); } while (0)
; #define PG8_MMA(ai, bj, At, Bt) do { __builtin_amdgcn_s_setprio(1); _Pragma("unroll") for (int m = 0; m < 4; ++m) _Pragma("unroll") for (int n = 0; n < 2; ++n) _Pragma("unroll") for (int k = 0; k < 2; ++k) \
;         acc[ai][bj][m][n] = __builtin_amdgcn_mfma_f32_16x16x32_bf16(Bt[n][k], At[m][k], acc[ai][bj][m][n], 0, 0, 0); __builtin_amdgcn_s_setprio(0); } while (0)
; #define PG8_WAIT_V(n) asm volatile("s_waitcnt vmcnt(" #n ")" ::: "memory")
; template <class Epi, class Sched, bool ALIGN_EPI = false, bool SP2 = false>
; __device__ __forceinline__ void gemm_phase(PG8_LAS unsigned char* lds, const Gemm g, const Sched& S, const Epi& E, int wv) {
;     ...
;         const char* nA = has_next ? (const char*)g.A + (size_t)nxt.pm * tstep : cA; const char* nB = has_next ? (const char*)g.Bt + (size_t)nxt.pn * tstep : cB;
;         for (int t = 0; t < nt; t += 2) {
;             const bool last = (t == nt - 2);
;             const char* a1 = cA + (size_t)(t + 1) * kstep;
;             const char* a2 = last ? nA : cA + (size_t)(t + 2) * kstep; const char* b2 = last ? nB : cB + (size_t)(t + 2) * kstep;
;             const char* a3 = a2 + kstep; const char* b3 = b2 + kstep;
;             if (last && has_next) S.a_ready(nxt);
;             if constexpr (SP2) {
;             PG8_LDB(B0, 0, 0); PG8_LDB(B1, 0, 1); PG8_SCHED; PG8_LDA(At, 0, 0); PG8_STAGE(PG8_SA(1, 1), a1 + hstep, voffA);
;             PG8_WAIT_V(8); PG8_WAIT_L(0); PG8_BAR; PG8_MMA(0, 0, At, B0); PG8_MMA(0, 1, At, B1); PG8_BAR; PG8_SCHED;
;             PG8_LDA(At, 0, 1); PG8_STAGE(PG8_SB(0, 0), b2, voffB); PG8_STAGE(PG8_SB(0, 1), b2 + hstep, voffB); PG8_STAGE(PG8_SA(0, 0), a2, voffA);
.LBB0_845:
	s_add_u32 s44, s6, 0x100
	s_addc_u32 s45, s7, 0
	s_add_i32 s21, 0, 0x10000
	s_cmp_eq_u32 s67, 40
	s_cselect_b32 s51, s41, s45
	s_cselect_b32 s50, s40, s44
	s_cselect_b32 s49, s43, s25
	s_cselect_b32 s48, s42, s24
	s_add_i32 s26, 0, 0x14000
	v_add_u32_e32 v140, s21, v170
	v_add_u32_e32 v168, s26, v170
	ds_read_b128 v[128:131], v140
	ds_read_b128 v[132:135], v140 offset:1024
	ds_read_b128 v[136:139], v140 offset:2048
	ds_read_b128 v[140:143], v140 offset:3072
	ds_read_b128 v[144:147], v168
	ds_read_b128 v[148:151], v168 offset:1024
	ds_read_b128 v[164:167], v168 offset:2048
	ds_read_b128 v[172:175], v168 offset:3072
	v_lshl_add_u64 v[168:169], s[6:7], 0, v[158:159]
	s_add_i32 m0, s31, 0xc000
	ds_read_b128 v[176:179], v171
	ds_read_b128 v[204:207], v171 offset:1024
	ds_read_b128 v[208:211], v171 offset:2048
	ds_read_b128 v[212:215], v171 offset:3072
	ds_read_b128 v[216:219], v171 offset:4096
	ds_read_b128 v[220:223], v171 offset:5120
	ds_read_b128 v[224:227], v171 offset:6144
	ds_read_b128 v[228:231], v171 offset:7168
	global_load_lds_dwordx4 v[168:169], off
	v_lshl_add_u64 v[168:169], s[6:7], 0, v[162:163]
	s_add_i32 m0, s31, 0xe000
	s_nop 0
	global_load_lds_dwordx4 v[168:169], off
	s_waitcnt vmcnt(8)
	s_waitcnt lgkmcnt(0)
	s_barrier
	s_setprio 1
	s_waitcnt lgkmcnt(0)
	v_mfma_f32_16x16x32_bf16 v[124:127], v[128:131], v[176:179], v[124:127]
	v_mfma_f32_16x16x32_bf16 v[120:123], v[136:139], v[176:179], v[120:123]
	v_mfma_f32_16x16x32_bf16 v[108:111], v[128:131], v[208:211], v[108:111]
	v_mfma_f32_16x16x32_bf16 v[104:107], v[136:139], v[208:211], v[104:107]
	v_mfma_f32_16x16x32_bf16 v[92:95], v[128:131], v[216:219], v[92:95]
	v_mfma_f32_16x16x32_bf16 v[88:91], v[136:139], v[216:219], v[88:91]
	v_mfma_f32_16x16x32_bf16 v[76:79], v[128:131], v[224:227], v[76:79]
	v_mfma_f32_16x16x32_bf16 v[72:75], v[136:139], v[224:227], v[72:75]
	v_mfma_f32_16x16x32_bf16 v[124:127], v[132:135], v[204:207], v[124:127]
	v_mfma_f32_16x16x32_bf16 v[120:123], v[140:143], v[204:207], v[120:123]
	v_mfma_f32_16x16x32_bf16 v[108:111], v[132:135], v[212:215], v[108:111]
	v_mfma_f32_16x16x32_bf16 v[104:107], v[140:143], v[212:215], v[104:107]
	v_mfma_f32_16x16x32_bf16 v[92:95], v[132:135], v[220:223], v[92:95]
	v_mfma_f32_16x16x32_bf16 v[88:91], v[140:143], v[220:223], v[88:91]
	v_mfma_f32_16x16x32_bf16 v[76:79], v[132:135], v[228:231], v[76:79]
	v_mfma_f32_16x16x32_bf16 v[72:75], v[140:143], v[228:231], v[72:75]
	s_setprio 0
	s_setprio 1
	v_mfma_f32_16x16x32_bf16 v[116:119], v[144:147], v[176:179], v[116:119]
	v_mfma_f32_16x16x32_bf16 v[112:115], v[164:167], v[176:179], v[112:115]
	v_mfma_f32_16x16x32_bf16 v[100:103], v[144:147], v[208:211], v[100:103]
	v_mfma_f32_16x16x32_bf16 v[96:99], v[164:167], v[208:211], v[96:99]
	v_mfma_f32_16x16x32_bf16 v[84:87], v[144:147], v[216:219], v[84:87]
	v_mfma_f32_16x16x32_bf16 v[80:83], v[164:167], v[216:219], v[80:83]
	v_mfma_f32_16x16x32_bf16 v[68:71], v[144:147], v[224:227], v[68:71]
	v_mfma_f32_16x16x32_bf16 v[64:67], v[164:167], v[224:227], v[64:67]
	v_mfma_f32_16x16x32_bf16 v[116:119], v[148:151], v[204:207], v[116:119]
	v_mfma_f32_16x16x32_bf16 v[112:115], v[172:175], v[204:207], v[112:115]
	v_mfma_f32_16x16x32_bf16 v[100:103], v[148:151], v[212:215], v[100:103]
	v_mfma_f32_16x16x32_bf16 v[96:99], v[172:175], v[212:215], v[96:99]
	s_setprio 2
	s_barrier
	v_mfma_f32_16x16x32_bf16 v[84:87], v[148:151], v[220:223], v[84:87]
	v_mfma_f32_16x16x32_bf16 v[80:83], v[172:175], v[220:223], v[80:83]
	v_mfma_f32_16x16x32_bf16 v[68:71], v[148:151], v[228:231], v[68:71]
	v_mfma_f32_16x16x32_bf16 v[64:67], v[172:175], v[228:231], v[64:67]
	s_setprio 0
	s_add_i32 s6, s21, s30
	v_lshl_add_u64 v[168:169], s[48:49], 0, v[160:161]
	s_mov_b32 m0, s6
	ds_read_b128 v[176:179], v171 offset:16384
	ds_read_b128 v[204:207], v171 offset:17408
	ds_read_b128 v[208:211], v171 offset:18432
	ds_read_b128 v[212:215], v171 offset:19456
	ds_read_b128 v[216:219], v171 offset:20480
	ds_read_b128 v[220:223], v171 offset:21504
	ds_read_b128 v[224:227], v171 offset:22528
	ds_read_b128 v[228:231], v171 offset:23552
	global_load_lds_dwordx4 v[168:169], off
	s_add_i32 m0, s6, 0x2000
	s_add_u32 s6, s48, 0xb0000
	v_lshl_add_u64 v[180:181], s[48:49], 0, v[152:153]
	s_addc_u32 s7, s49, 0
	s_add_i32 s21, s26, s30
	global_load_lds_dwordx4 v[180:181], off
	v_lshl_add_u64 v[232:233], s[6:7], 0, v[160:161]
	s_mov_b32 m0, s21
	v_lshl_add_u64 v[234:235], s[50:51], 0, v[154:155]
	global_load_lds_dwordx4 v[232:233], off
	v_lshl_add_u64 v[232:233], s[6:7], 0, v[152:153]
	s_add_i32 m0, s21, 0x2000
	s_nop 0
	global_load_lds_dwordx4 v[232:233], off
	v_lshl_add_u64 v[232:233], s[50:51], 0, v[156:157]
	s_mov_b32 m0, s31
	s_nop 0
	global_load_lds_dwordx4 v[232:233], off
	s_mov_b32 m0, s52
	s_nop 0
	global_load_lds_dwordx4 v[234:235], off
	s_waitcnt vmcnt(8)
	s_waitcnt lgkmcnt(0)
	s_barrier
; #define PG8_STAGE(bufoff, gbase, voff) do { _Pragma("unroll") for (int _i = 0; _i < 2; ++_i) \
;         __builtin_amdgcn_global_load_lds((const unsigned*)((const char*)(gbase) + (voff)[_i]), (PG8_LAS unsigned*)(lds + (bufoff) + ldsw + _i * 8192), 16, 0, 0); } while (0)
; #define PG8_LDA(dst, b, h) do { _Pragma("unroll") for (int m = 0; m < 4; ++m) _Pragma("unroll") for (int k = 0; k < 2; ++k) dst[m][k] = *(const PG8_LAS bf16x8*)(lds + PG8_SA(b, h) + aoff + m * 2048 + k * 1024); } while (0)
; #define PG8_LDB(dst, b, h) do { _Pragma("unroll") for (int n = 0; n < 2; ++n) _Pragma("unroll") for (int k = 0; k < 2; ++k) dst[n][k] = *(const PG8_LAS bf16x8*)(lds + PG8_SB(b, h) + boff + n * 2048 + k * 1024); } while (0)
; #define PG8_MMA(ai, bj, At, Bt) do { __builtin_amdgcn_s_setprio(1); _Pragma("unroll") for (int m = 0; m < 4; ++m) _Pragma("unroll") for (int n = 0; n < 2; ++n) _Pragma("unroll") for (int k = 0; k < 2; ++k) \
;         acc[ai][bj][m][n] = __builtin_amdgcn_mfma_f32_16x16x32_bf16(Bt[n][k], At[m][k], acc[ai][bj][m][n], 0, 0, 0); __builtin_amdgcn_s_setprio(0); } while (0)
; #define PG8_WAIT_V(n) asm volatile("s_waitcnt vmcnt(" #n ")" ::: "memory")
; #define PG8_WAIT_L(n) asm volatile("s_waitcnt lgkmcnt(" #n ")" ::: "memory")
; #define PG8_BAR __builtin_amdgcn_s_barrier()
; #define PG8_SCHED __builtin_amdgcn_sched_barrier(0)
; template <class Epi, class Sched, bool ALIGN_EPI = false, bool SP2 = false>
; __device__ __forceinline__ void gemm_phase(PG8_LAS unsigned char* lds, const Gemm g, const Sched& S, const Epi& E, int wv) {
;     ...
;             PG8_WAIT_V(8); PG8_WAIT_L(0); PG8_BAR; PG8_MMA(1, 0, At, B0); PG8_MMA(1, 1, At, B1); PG8_BAR; PG8_SCHED;
;             PG8_LDB(B0, 1, 0); PG8_LDB(B1, 1, 1); PG8_SCHED; PG8_LDA(At, 1, 0); PG8_STAGE(PG8_SA(0, 1), a2 + hstep, voffA);
;             PG8_WAIT_V(8); PG8_WAIT_L(0); PG8_BAR; PG8_MMA(0, 0, At, B0); PG8_MMA(0, 1, At, B1); PG8_BAR; PG8_SCHED;
	s_setprio 1
	s_waitcnt lgkmcnt(0)
	v_mfma_f32_16x16x32_bf16 v[60:63], v[128:131], v[176:179], v[60:63]
	v_mfma_f32_16x16x32_bf16 v[56:59], v[136:139], v[176:179], v[56:59]
	v_mfma_f32_16x16x32_bf16 v[44:47], v[128:131], v[208:211], v[44:47]
	v_mfma_f32_16x16x32_bf16 v[40:43], v[136:139], v[208:211], v[40:43]
	v_mfma_f32_16x16x32_bf16 v[28:31], v[128:131], v[216:219], v[28:31]
	v_mfma_f32_16x16x32_bf16 v[24:27], v[136:139], v[216:219], v[24:27]
	v_mfma_f32_16x16x32_bf16 v[12:15], v[128:131], v[224:227], v[12:15]
	v_mfma_f32_16x16x32_bf16 v[8:11], v[136:139], v[224:227], v[8:11]
	v_mfma_f32_16x16x32_bf16 v[60:63], v[132:135], v[204:207], v[60:63]
	v_mfma_f32_16x16x32_bf16 v[56:59], v[140:143], v[204:207], v[56:59]
	v_mfma_f32_16x16x32_bf16 v[44:47], v[132:135], v[212:215], v[44:47]
	v_mfma_f32_16x16x32_bf16 v[40:43], v[140:143], v[212:215], v[40:43]
	v_mfma_f32_16x16x32_bf16 v[28:31], v[132:135], v[220:223], v[28:31]
	v_mfma_f32_16x16x32_bf16 v[24:27], v[140:143], v[220:223], v[24:27]
	v_mfma_f32_16x16x32_bf16 v[12:15], v[132:135], v[228:231], v[12:15]
	v_mfma_f32_16x16x32_bf16 v[8:11], v[140:143], v[228:231], v[8:11]
	s_setprio 0
	s_setprio 1
	v_mfma_f32_16x16x32_bf16 v[52:55], v[144:147], v[176:179], v[52:55]
	v_mfma_f32_16x16x32_bf16 v[48:51], v[164:167], v[176:179], v[48:51]
	v_mfma_f32_16x16x32_bf16 v[36:39], v[144:147], v[208:211], v[36:39]
	v_mfma_f32_16x16x32_bf16 v[32:35], v[164:167], v[208:211], v[32:35]
	v_mfma_f32_16x16x32_bf16 v[20:23], v[144:147], v[216:219], v[20:23]
	v_mfma_f32_16x16x32_bf16 v[16:19], v[164:167], v[216:219], v[16:19]
	v_mfma_f32_16x16x32_bf16 v[4:7], v[144:147], v[224:227], v[4:7]
	v_mfma_f32_16x16x32_bf16 v[0:3], v[164:167], v[224:227], v[0:3]
	v_mfma_f32_16x16x32_bf16 v[52:55], v[148:151], v[204:207], v[52:55]
	v_mfma_f32_16x16x32_bf16 v[48:51], v[172:175], v[204:207], v[48:51]
	v_mfma_f32_16x16x32_bf16 v[36:39], v[148:151], v[212:215], v[36:39]
	v_mfma_f32_16x16x32_bf16 v[32:35], v[172:175], v[212:215], v[32:35]
	s_setprio 2
	s_barrier
	v_mfma_f32_16x16x32_bf16 v[20:23], v[148:151], v[220:223], v[20:23]
	v_mfma_f32_16x16x32_bf16 v[16:19], v[172:175], v[220:223], v[16:19]
	v_mfma_f32_16x16x32_bf16 v[4:7], v[148:151], v[228:231], v[4:7]
	v_mfma_f32_16x16x32_bf16 v[0:3], v[172:175], v[228:231], v[0:3]
	s_setprio 0
	s_add_i32 s21, 0, 0x18000
	s_add_i32 s26, 0, 0x1c000
	v_add_u32_e32 v140, s21, v170
	v_add_u32_e32 v172, s26, v170
	ds_read_b128 v[128:131], v140
	ds_read_b128 v[132:135], v140 offset:1024
	ds_read_b128 v[136:139], v140 offset:2048
	ds_read_b128 v[140:143], v140 offset:3072
	ds_read_b128 v[144:147], v172
	ds_read_b128 v[148:151], v172 offset:1024
	ds_read_b128 v[164:167], v172 offset:2048
	ds_read_b128 v[172:175], v172 offset:3072
	s_add_u32 s6, s50, 0xb0000
	s_addc_u32 s7, s51, 0
	s_mov_b32 m0, s53
	v_lshl_add_u64 v[236:237], s[6:7], 0, v[156:157]
	ds_read_b128 v[176:179], v171 offset:32768
	ds_read_b128 v[204:207], v171 offset:33792
	ds_read_b128 v[208:211], v171 offset:34816
	ds_read_b128 v[212:215], v171 offset:35840
	ds_read_b128 v[216:219], v171 offset:36864
	ds_read_b128 v[220:223], v171 offset:37888
	ds_read_b128 v[224:227], v171 offset:38912
	ds_read_b128 v[228:231], v171 offset:39936
	global_load_lds_dwordx4 v[236:237], off
	v_lshl_add_u64 v[236:237], s[6:7], 0, v[154:155]
	s_mov_b32 m0, s54
	s_nop 0
	global_load_lds_dwordx4 v[236:237], off
	s_waitcnt vmcnt(8)
	s_waitcnt lgkmcnt(0)
	s_barrier
	s_setprio 1
	s_waitcnt lgkmcnt(0)
	v_mfma_f32_16x16x32_bf16 v[124:127], v[128:131], v[176:179], v[124:127]
	v_mfma_f32_16x16x32_bf16 v[120:123], v[136:139], v[176:179], v[120:123]
	v_mfma_f32_16x16x32_bf16 v[108:111], v[128:131], v[208:211], v[108:111]
	v_mfma_f32_16x16x32_bf16 v[104:107], v[136:139], v[208:211], v[104:107]
	v_mfma_f32_16x16x32_bf16 v[92:95], v[128:131], v[216:219], v[92:95]
	v_mfma_f32_16x16x32_bf16 v[88:91], v[136:139], v[216:219], v[88:91]
	v_mfma_f32_16x16x32_bf16 v[76:79], v[128:131], v[224:227], v[76:79]
	v_mfma_f32_16x16x32_bf16 v[72:75], v[136:139], v[224:227], v[72:75]
	v_mfma_f32_16x16x32_bf16 v[124:127], v[132:135], v[204:207], v[124:127]
	v_mfma_f32_16x16x32_bf16 v[120:123], v[140:143], v[204:207], v[120:123]
	v_mfma_f32_16x16x32_bf16 v[108:111], v[132:135], v[212:215], v[108:111]
	v_mfma_f32_16x16x32_bf16 v[104:107], v[140:143], v[212:215], v[104:107]
	v_mfma_f32_16x16x32_bf16 v[92:95], v[132:135], v[220:223], v[92:95]
	v_mfma_f32_16x16x32_bf16 v[88:91], v[140:143], v[220:223], v[88:91]
	v_mfma_f32_16x16x32_bf16 v[76:79], v[132:135], v[228:231], v[76:79]
	v_mfma_f32_16x16x32_bf16 v[72:75], v[140:143], v[228:231], v[72:75]
	s_setprio 0
	s_setprio 1
	v_mfma_f32_16x16x32_bf16 v[116:119], v[144:147], v[176:179], v[116:119]
	v_mfma_f32_16x16x32_bf16 v[112:115], v[164:167], v[176:179], v[112:115]
	v_mfma_f32_16x16x32_bf16 v[100:103], v[144:147], v[208:211], v[100:103]
	v_mfma_f32_16x16x32_bf16 v[96:99], v[164:167], v[208:211], v[96:99]
	v_mfma_f32_16x16x32_bf16 v[84:87], v[144:147], v[216:219], v[84:87]
	v_mfma_f32_16x16x32_bf16 v[80:83], v[164:167], v[216:219], v[80:83]
	v_mfma_f32_16x16x32_bf16 v[68:71], v[144:147], v[224:227], v[68:71]
	v_mfma_f32_16x16x32_bf16 v[64:67], v[164:167], v[224:227], v[64:67]
	v_mfma_f32_16x16x32_bf16 v[116:119], v[148:151], v[204:207], v[116:119]
	v_mfma_f32_16x16x32_bf16 v[112:115], v[172:175], v[204:207], v[112:115]
	v_mfma_f32_16x16x32_bf16 v[100:103], v[148:151], v[212:215], v[100:103]
	v_mfma_f32_16x16x32_bf16 v[96:99], v[172:175], v[212:215], v[96:99]
	s_setprio 2
	s_barrier
; #define PG8_STAGE(bufoff, gbase, voff) do { _Pragma("unroll") for (int _i = 0; _i < 2; ++_i) \
;         __builtin_amdgcn_global_load_lds((const unsigned*)((const char*)(gbase) + (voff)[_i]), (PG8_LAS unsigned*)(lds + (bufoff) + ldsw + _i * 8192), 16, 0, 0); } while (0)
; #define PG8_LDA(dst, b, h) do { _Pragma("unroll") for (int m = 0; m < 4; ++m) _Pragma("unroll") for (int k = 0; k < 2; ++k) dst[m][k] = *(const PG8_LAS bf16x8*)(lds + PG8_SA(b, h) + aoff + m * 2048 + k * 1024); } while (0)
; #define PG8_MMA(ai, bj, At, Bt) do { __builtin_amdgcn_s_setprio(1); _Pragma("unroll") for (int m = 0; m < 4; ++m) _Pragma("unroll") for (int n = 0; n < 2; ++n) _Pragma("unroll") for (int k = 0; k < 2; ++k) \
;         acc[ai][bj][m][n] = __builtin_amdgcn_mfma_f32_16x16x32_bf16(Bt[n][k], At[m][k], acc[ai][bj][m][n], 0, 0, 0); __builtin_amdgcn_s_setprio(0); } while (0)
; #define PG8_WAIT_V(n) asm volatile("s_waitcnt vmcnt(" #n ")" ::: "memory")
; #define PG8_WAIT_L(n) asm volatile("s_waitcnt lgkmcnt(" #n ")" ::: "memory")
; #define PG8_BAR __builtin_amdgcn_s_barrier()
; #define PG8_SCHED __builtin_amdgcn_sched_barrier(0)
; template <class Epi, class Sched, bool ALIGN_EPI = false, bool SP2 = false>
; __device__ __forceinline__ void gemm_phase(PG8_LAS unsigned char* lds, const Gemm g, const Sched& S, const Epi& E, int wv) {
;     ...
;             PG8_LDA(At, 1, 1); PG8_STAGE(PG8_SB(1, 0), b3, voffB); PG8_STAGE(PG8_SB(1, 1), b3 + hstep, voffB); PG8_STAGE(PG8_SA(1, 0), a3, voffA);
;             PG8_WAIT_V(8); PG8_WAIT_L(0); PG8_BAR; PG8_MMA(1, 0, At, B0); PG8_MMA(1, 1, At, B1); PG8_BAR; PG8_SCHED;
;     ...
;         if constexpr (ALIGN_EPI) { if (wr == 0) PG8_BAR; }
	v_mfma_f32_16x16x32_bf16 v[84:87], v[148:151], v[220:223], v[84:87]
	v_mfma_f32_16x16x32_bf16 v[80:83], v[172:175], v[220:223], v[80:83]
	v_mfma_f32_16x16x32_bf16 v[68:71], v[148:151], v[228:231], v[68:71]
	v_mfma_f32_16x16x32_bf16 v[64:67], v[172:175], v[228:231], v[64:67]
	s_setprio 0
	s_add_i32 s6, s21, s30
	v_lshl_add_u64 v[168:169], v[168:169], 0, s[74:75]
	s_mov_b32 m0, s6
	ds_read_b128 v[176:179], v171 offset:49152
	ds_read_b128 v[204:207], v171 offset:50176
	ds_read_b128 v[208:211], v171 offset:51200
	ds_read_b128 v[212:215], v171 offset:52224
	ds_read_b128 v[216:219], v171 offset:53248
	ds_read_b128 v[220:223], v171 offset:54272
	ds_read_b128 v[224:227], v171 offset:55296
	ds_read_b128 v[228:231], v171 offset:56320
	global_load_lds_dwordx4 v[168:169], off
	s_add_i32 m0, s6, 0x2000
	s_add_u32 s6, s48, 0xb0080
	v_lshl_add_u64 v[168:169], v[180:181], 0, s[74:75]
	s_addc_u32 s7, s49, 0
	s_add_i32 s21, s26, s30
	global_load_lds_dwordx4 v[168:169], off
	v_lshl_add_u64 v[168:169], s[6:7], 0, v[160:161]
	s_mov_b32 m0, s21
	s_nop 0
	global_load_lds_dwordx4 v[168:169], off
	v_lshl_add_u64 v[168:169], s[6:7], 0, v[152:153]
	s_add_i32 m0, s21, 0x2000
	s_nop 0
	global_load_lds_dwordx4 v[168:169], off
	v_lshl_add_u64 v[168:169], v[232:233], 0, s[74:75]
	s_mov_b32 m0, s61
	s_nop 0
	global_load_lds_dwordx4 v[168:169], off
	v_lshl_add_u64 v[168:169], v[234:235], 0, s[74:75]
	s_mov_b32 m0, s62
	s_nop 0
	global_load_lds_dwordx4 v[168:169], off
	s_waitcnt vmcnt(8)
	s_waitcnt lgkmcnt(0)
	s_barrier
	s_setprio 1
	s_waitcnt lgkmcnt(0)
	v_mfma_f32_16x16x32_bf16 v[60:63], v[128:131], v[176:179], v[60:63]
	v_mfma_f32_16x16x32_bf16 v[56:59], v[136:139], v[176:179], v[56:59]
	v_mfma_f32_16x16x32_bf16 v[44:47], v[128:131], v[208:211], v[44:47]
	v_mfma_f32_16x16x32_bf16 v[40:43], v[136:139], v[208:211], v[40:43]
	v_mfma_f32_16x16x32_bf16 v[28:31], v[128:131], v[216:219], v[28:31]
	v_mfma_f32_16x16x32_bf16 v[24:27], v[136:139], v[216:219], v[24:27]
	v_mfma_f32_16x16x32_bf16 v[12:15], v[128:131], v[224:227], v[12:15]
	v_mfma_f32_16x16x32_bf16 v[8:11], v[136:139], v[224:227], v[8:11]
	v_mfma_f32_16x16x32_bf16 v[60:63], v[132:135], v[204:207], v[60:63]
	v_mfma_f32_16x16x32_bf16 v[56:59], v[140:143], v[204:207], v[56:59]
	v_mfma_f32_16x16x32_bf16 v[44:47], v[132:135], v[212:215], v[44:47]
	v_mfma_f32_16x16x32_bf16 v[40:43], v[140:143], v[212:215], v[40:43]
	v_mfma_f32_16x16x32_bf16 v[28:31], v[132:135], v[220:223], v[28:31]
	v_mfma_f32_16x16x32_bf16 v[24:27], v[140:143], v[220:223], v[24:27]
	v_mfma_f32_16x16x32_bf16 v[12:15], v[132:135], v[228:231], v[12:15]
	v_mfma_f32_16x16x32_bf16 v[8:11], v[140:143], v[228:231], v[8:11]
	s_setprio 0
	s_setprio 1
	v_mfma_f32_16x16x32_bf16 v[52:55], v[144:147], v[176:179], v[52:55]
	v_mfma_f32_16x16x32_bf16 v[48:51], v[164:167], v[176:179], v[48:51]
	v_mfma_f32_16x16x32_bf16 v[36:39], v[144:147], v[208:211], v[36:39]
	v_mfma_f32_16x16x32_bf16 v[32:35], v[164:167], v[208:211], v[32:35]
	v_mfma_f32_16x16x32_bf16 v[20:23], v[144:147], v[216:219], v[20:23]
	v_mfma_f32_16x16x32_bf16 v[16:19], v[164:167], v[216:219], v[16:19]
	v_mfma_f32_16x16x32_bf16 v[4:7], v[144:147], v[224:227], v[4:7]
	v_mfma_f32_16x16x32_bf16 v[0:3], v[164:167], v[224:227], v[0:3]
	v_mfma_f32_16x16x32_bf16 v[52:55], v[148:151], v[204:207], v[52:55]
	v_mfma_f32_16x16x32_bf16 v[48:51], v[172:175], v[204:207], v[48:51]
	v_mfma_f32_16x16x32_bf16 v[36:39], v[148:151], v[212:215], v[36:39]
	v_mfma_f32_16x16x32_bf16 v[32:35], v[172:175], v[212:215], v[32:35]
	s_setprio 2
	s_barrier
	v_mfma_f32_16x16x32_bf16 v[20:23], v[148:151], v[220:223], v[20:23]
	v_mfma_f32_16x16x32_bf16 v[16:19], v[172:175], v[220:223], v[16:19]
	v_mfma_f32_16x16x32_bf16 v[4:7], v[148:151], v[228:231], v[4:7]
	v_mfma_f32_16x16x32_bf16 v[0:3], v[172:175], v[228:231], v[0:3]
	s_setprio 0
	s_add_i32 s67, s67, 2
	s_add_u32 s24, s24, 0x100
	s_addc_u32 s25, s25, 0
	s_cmp_gt_u32 s67, 41
	s_mov_b64 s[6:7], s[44:45]
	s_cbranch_scc0 .LBB0_845
	s_and_b64 vcc, exec, s[34:35]
	s_cbranch_vccz .LBB0_848
	s_barrier

; #define PG8_STAGE(bufoff, gbase, voff) do { _Pragma("unroll") for (int _i = 0; _i < 2; ++_i) \
;         __builtin_amdgcn_global_load_lds((const unsigned*)((const char*)(gbase) + (voff)[_i]), (PG8_LAS unsigned*)(lds + (bufoff) + ldsw + _i * 8192), 16, 0, 0); } while (0)
; #define PG8_LDA(dst, b, h) do { _Pragma("unroll") for (int m = 0; m < 4; ++m) _Pragma("unroll") for (int k = 0; k < 2; ++k) dst[m][k] = *(const PG8_LAS bf16x8*)(lds + PG8_SA(b, h) + aoff + m * 2048 + k * 1024); } while (0)
; #define PG8_LDB(dst, b, h) do { _Pragma("unroll") for (int n = 0; n < 2; ++n) _Pragma("unroll") for (int k = 0; k < 2; ++k) dst[n][k] = *(const PG8_LAS bf16x8*)(lds + PG8_SB(b, h) + boff + n * 2048 + k * 1024); } while (0)
; #define PG8_MMA(ai, bj, At, Bt) do { __builtin_amdgcn_s_setprio(1); _Pragma("unroll") for (int m = 0; m < 4; ++m) _Pragma("unroll") for (int n = 0; n < 2; ++n) _Pragma("unroll") for (int k = 0; k < 2; ++k) \
;         acc[ai][bj][m][n] = __builtin_amdgcn_mfma_f32_16x16x32_bf16(Bt[n][k], At[m][k], acc[ai][bj][m][n], 0, 0, 0); __builtin_amdgcn_s_setprio(0); } while (0)
; #define PG8_WAIT_V(n) asm volatile("s_waitcnt vmcnt(" #n ")" ::: "memory")
; template <class Epi, class Sched, bool ALIGN_EPI = false, bool SP2 = false>
; __device__ __forceinline__ void gemm_phase(PG8_LAS unsigned char* lds, const Gemm g, const Sched& S, const Epi& E, int wv) {
;     ...
;         const char* nA = has_next ? (const char*)g.A + (size_t)nxt.pm * tstep : cA; const char* nB = has_next ? (const char*)g.Bt + (size_t)nxt.pn * tstep : cB;
;         for (int t = 0; t < nt; t += 2) {
;             const bool last = (t == nt - 2);
;             const char* a1 = cA + (size_t)(t + 1) * kstep;
;             const char* a2 = last ? nA : cA + (size_t)(t + 2) * kstep; const char* b2 = last ? nB : cB + (size_t)(t + 2) * kstep;
;             const char* a3 = a2 + kstep; const char* b3 = b2 + kstep;
;             if (last && has_next) S.a_ready(nxt);
;             if constexpr (SP2) {
;             PG8_LDB(B0, 0, 0); PG8_LDB(B1, 0, 1); PG8_SCHED; PG8_LDA(At, 0, 0); PG8_STAGE(PG8_SA(1, 1), a1 + hstep, voffA);
;             PG8_WAIT_V(8); PG8_WAIT_L(0); PG8_BAR; PG8_MMA(0, 0, At, B0); PG8_MMA(0, 1, At, B1); PG8_BAR; PG8_SCHED;
;             PG8_LDA(At, 0, 1); PG8_STAGE(PG8_SB(0, 0), b2, voffB); PG8_STAGE(PG8_SB(0, 1), b2 + hstep, voffB); PG8_STAGE(PG8_SA(0, 0), a2, voffA);
.LBB0_1188:
	s_add_u32 s21, s44, 0xfffc0080
	s_addc_u32 s26, s45, -1
	s_add_i32 s28, 0, 0x10000
	s_cmp_eq_u32 s67, 12
	s_cselect_b32 s51, s13, s26
	s_cselect_b32 s50, s63, s21
	v_add_u32_e32 v138, s28, v139
	s_cselect_b32 s49, s19, s66
	s_cselect_b32 s48, s64, s65
	s_add_i32 s21, 0, 0x14000
	ds_read_b128 v[142:145], v138
	ds_read_b128 v[146:149], v138 offset:1024
	ds_read_b128 v[150:153], v138 offset:2048
	ds_read_b128 v[154:157], v138 offset:3072
	v_add_u32_e32 v138, s21, v139
	ds_read_b128 v[162:165], v138
	ds_read_b128 v[166:169], v138 offset:1024
	ds_read_b128 v[170:173], v138 offset:2048
	ds_read_b128 v[174:177], v138 offset:3072
	v_lshl_add_u64 v[158:159], s[44:45], 0, v[134:135]
	s_add_i32 m0, s31, 0xc000
	ds_read_b128 v[178:181], v141
	ds_read_b128 v[204:207], v141 offset:1024
	ds_read_b128 v[208:211], v141 offset:2048
	ds_read_b128 v[212:215], v141 offset:3072
	ds_read_b128 v[216:219], v141 offset:4096
	ds_read_b128 v[220:223], v141 offset:5120
	ds_read_b128 v[224:227], v141 offset:6144
	ds_read_b128 v[228:231], v141 offset:7168
	global_load_lds_dwordx4 v[158:159], off
	v_lshl_add_u64 v[158:159], s[44:45], 0, v[136:137]
	s_add_i32 m0, s31, 0xe000
	s_nop 0
	global_load_lds_dwordx4 v[158:159], off
	s_waitcnt vmcnt(8)
	s_waitcnt lgkmcnt(0)
	s_barrier
	s_setprio 1
	s_waitcnt lgkmcnt(0)
	v_mfma_f32_16x16x32_bf16 v[124:127], v[142:145], v[178:181], v[124:127]
	v_mfma_f32_16x16x32_bf16 v[120:123], v[150:153], v[178:181], v[120:123]
	v_mfma_f32_16x16x32_bf16 v[116:119], v[142:145], v[208:211], v[116:119]
	v_mfma_f32_16x16x32_bf16 v[112:115], v[150:153], v[208:211], v[112:115]
	v_mfma_f32_16x16x32_bf16 v[100:103], v[142:145], v[216:219], v[100:103]
	v_mfma_f32_16x16x32_bf16 v[96:99], v[150:153], v[216:219], v[96:99]
	v_mfma_f32_16x16x32_bf16 v[84:87], v[142:145], v[224:227], v[84:87]
	v_mfma_f32_16x16x32_bf16 v[76:79], v[150:153], v[224:227], v[76:79]
	v_mfma_f32_16x16x32_bf16 v[124:127], v[146:149], v[204:207], v[124:127]
	v_mfma_f32_16x16x32_bf16 v[120:123], v[154:157], v[204:207], v[120:123]
	v_mfma_f32_16x16x32_bf16 v[116:119], v[146:149], v[212:215], v[116:119]
	v_mfma_f32_16x16x32_bf16 v[112:115], v[154:157], v[212:215], v[112:115]
	v_mfma_f32_16x16x32_bf16 v[100:103], v[146:149], v[220:223], v[100:103]
	v_mfma_f32_16x16x32_bf16 v[96:99], v[154:157], v[220:223], v[96:99]
	v_mfma_f32_16x16x32_bf16 v[84:87], v[146:149], v[228:231], v[84:87]
	v_mfma_f32_16x16x32_bf16 v[76:79], v[154:157], v[228:231], v[76:79]
	s_setprio 0
	s_setprio 1
	v_mfma_f32_16x16x32_bf16 v[108:111], v[162:165], v[178:181], v[108:111]
	v_mfma_f32_16x16x32_bf16 v[104:107], v[170:173], v[178:181], v[104:107]
	v_mfma_f32_16x16x32_bf16 v[92:95], v[162:165], v[208:211], v[92:95]
	v_mfma_f32_16x16x32_bf16 v[88:91], v[170:173], v[208:211], v[88:91]
	v_mfma_f32_16x16x32_bf16 v[80:83], v[162:165], v[216:219], v[80:83]
	v_mfma_f32_16x16x32_bf16 v[72:75], v[170:173], v[216:219], v[72:75]
	v_mfma_f32_16x16x32_bf16 v[68:71], v[162:165], v[224:227], v[68:71]
	v_mfma_f32_16x16x32_bf16 v[64:67], v[170:173], v[224:227], v[64:67]
	v_mfma_f32_16x16x32_bf16 v[108:111], v[166:169], v[204:207], v[108:111]
	v_mfma_f32_16x16x32_bf16 v[104:107], v[174:177], v[204:207], v[104:107]
	v_mfma_f32_16x16x32_bf16 v[92:95], v[166:169], v[212:215], v[92:95]
	v_mfma_f32_16x16x32_bf16 v[88:91], v[174:177], v[212:215], v[88:91]
	s_setprio 2
	s_barrier
	v_mfma_f32_16x16x32_bf16 v[80:83], v[166:169], v[220:223], v[80:83]
	v_mfma_f32_16x16x32_bf16 v[72:75], v[174:177], v[220:223], v[72:75]
	v_mfma_f32_16x16x32_bf16 v[68:71], v[166:169], v[228:231], v[68:71]
	v_mfma_f32_16x16x32_bf16 v[64:67], v[174:177], v[228:231], v[64:67]
	s_setprio 0
	s_add_i32 s26, s28, s30
	v_lshl_add_u64 v[158:159], s[48:49], 0, v[160:161]
	s_mov_b32 m0, s26
	ds_read_b128 v[178:181], v141 offset:16384
	ds_read_b128 v[204:207], v141 offset:17408
	ds_read_b128 v[208:211], v141 offset:18432
	ds_read_b128 v[212:215], v141 offset:19456
	ds_read_b128 v[216:219], v141 offset:20480
	ds_read_b128 v[220:223], v141 offset:21504
	ds_read_b128 v[224:227], v141 offset:22528
	ds_read_b128 v[228:231], v141 offset:23552
	global_load_lds_dwordx4 v[158:159], off
	s_add_i32 m0, s26, 0x2000
	s_add_u32 s76, s48, 0x40000
	v_lshl_add_u64 v[232:233], s[48:49], 0, v[128:129]
	s_addc_u32 s77, s49, 0
	s_add_i32 s21, s21, s30
	global_load_lds_dwordx4 v[232:233], off
	v_lshl_add_u64 v[234:235], s[76:77], 0, v[160:161]
	s_mov_b32 m0, s21
	v_lshl_add_u64 v[236:237], s[50:51], 0, v[130:131]
	global_load_lds_dwordx4 v[234:235], off
	v_lshl_add_u64 v[234:235], s[76:77], 0, v[128:129]
	s_add_i32 m0, s21, 0x2000
	s_nop 0
	global_load_lds_dwordx4 v[234:235], off
	v_lshl_add_u64 v[234:235], s[50:51], 0, v[132:133]
	s_mov_b32 m0, s31
	s_nop 0
	global_load_lds_dwordx4 v[234:235], off
	s_mov_b32 m0, s52
	s_nop 0
	global_load_lds_dwordx4 v[236:237], off
	s_waitcnt vmcnt(8)
	s_waitcnt lgkmcnt(0)
	s_barrier
; #define PG8_STAGE(bufoff, gbase, voff) do { _Pragma("unroll") for (int _i = 0; _i < 2; ++_i) \
;         __builtin_amdgcn_global_load_lds((const unsigned*)((const char*)(gbase) + (voff)[_i]), (PG8_LAS unsigned*)(lds + (bufoff) + ldsw + _i * 8192), 16, 0, 0); } while (0)
; #define PG8_LDA(dst, b, h) do { _Pragma("unroll") for (int m = 0; m < 4; ++m) _Pragma("unroll") for (int k = 0; k < 2; ++k) dst[m][k] = *(const PG8_LAS bf16x8*)(lds + PG8_SA(b, h) + aoff + m * 2048 + k * 1024); } while (0)
; #define PG8_LDB(dst, b, h) do { _Pragma("unroll") for (int n = 0; n < 2; ++n) _Pragma("unroll") for (int k = 0; k < 2; ++k) dst[n][k] = *(const PG8_LAS bf16x8*)(lds + PG8_SB(b, h) + boff + n * 2048 + k * 1024); } while (0)
; #define PG8_MMA(ai, bj, At, Bt) do { __builtin_amdgcn_s_setprio(1); _Pragma("unroll") for (int m = 0; m < 4; ++m) _Pragma("unroll") for (int n = 0; n < 2; ++n) _Pragma("unroll") for (int k = 0; k < 2; ++k) \
;         acc[ai][bj][m][n] = __builtin_amdgcn_mfma_f32_16x16x32_bf16(Bt[n][k], At[m][k], acc[ai][bj][m][n], 0, 0, 0); __builtin_amdgcn_s_setprio(0); } while (0)
; #define PG8_WAIT_V(n) asm volatile("s_waitcnt vmcnt(" #n ")" ::: "memory")
; #define PG8_WAIT_L(n) asm volatile("s_waitcnt lgkmcnt(" #n ")" ::: "memory")
; #define PG8_BAR __builtin_amdgcn_s_barrier()
; #define PG8_SCHED __builtin_amdgcn_sched_barrier(0)
; template <class Epi, class Sched, bool ALIGN_EPI = false, bool SP2 = false>
; __device__ __forceinline__ void gemm_phase(PG8_LAS unsigned char* lds, const Gemm g, const Sched& S, const Epi& E, int wv) {
;     ...
;             PG8_WAIT_V(8); PG8_WAIT_L(0); PG8_BAR; PG8_MMA(1, 0, At, B0); PG8_MMA(1, 1, At, B1); PG8_BAR; PG8_SCHED;
;             PG8_LDB(B0, 1, 0); PG8_LDB(B1, 1, 1); PG8_SCHED; PG8_LDA(At, 1, 0); PG8_STAGE(PG8_SA(0, 1), a2 + hstep, voffA);
;             PG8_WAIT_V(8); PG8_WAIT_L(0); PG8_BAR; PG8_MMA(0, 0, At, B0); PG8_MMA(0, 1, At, B1); PG8_BAR; PG8_SCHED;
	s_setprio 1
	s_waitcnt lgkmcnt(0)
	v_mfma_f32_16x16x32_bf16 v[60:63], v[142:145], v[178:181], v[60:63]
	v_mfma_f32_16x16x32_bf16 v[56:59], v[150:153], v[178:181], v[56:59]
	v_mfma_f32_16x16x32_bf16 v[52:55], v[142:145], v[208:211], v[52:55]
	v_mfma_f32_16x16x32_bf16 v[44:47], v[150:153], v[208:211], v[44:47]
	v_mfma_f32_16x16x32_bf16 v[36:39], v[142:145], v[216:219], v[36:39]
	v_mfma_f32_16x16x32_bf16 v[28:31], v[150:153], v[216:219], v[28:31]
	v_mfma_f32_16x16x32_bf16 v[20:23], v[142:145], v[224:227], v[20:23]
	v_mfma_f32_16x16x32_bf16 v[12:15], v[150:153], v[224:227], v[12:15]
	v_mfma_f32_16x16x32_bf16 v[60:63], v[146:149], v[204:207], v[60:63]
	v_mfma_f32_16x16x32_bf16 v[56:59], v[154:157], v[204:207], v[56:59]
	v_mfma_f32_16x16x32_bf16 v[52:55], v[146:149], v[212:215], v[52:55]
	v_mfma_f32_16x16x32_bf16 v[44:47], v[154:157], v[212:215], v[44:47]
	v_mfma_f32_16x16x32_bf16 v[36:39], v[146:149], v[220:223], v[36:39]
	v_mfma_f32_16x16x32_bf16 v[28:31], v[154:157], v[220:223], v[28:31]
	v_mfma_f32_16x16x32_bf16 v[20:23], v[146:149], v[228:231], v[20:23]
	v_mfma_f32_16x16x32_bf16 v[12:15], v[154:157], v[228:231], v[12:15]
	s_setprio 0
	s_setprio 1
	v_mfma_f32_16x16x32_bf16 v[48:51], v[162:165], v[178:181], v[48:51]
	v_mfma_f32_16x16x32_bf16 v[40:43], v[170:173], v[178:181], v[40:43]
	v_mfma_f32_16x16x32_bf16 v[32:35], v[162:165], v[208:211], v[32:35]
	v_mfma_f32_16x16x32_bf16 v[24:27], v[170:173], v[208:211], v[24:27]
	v_mfma_f32_16x16x32_bf16 v[16:19], v[162:165], v[216:219], v[16:19]
	v_mfma_f32_16x16x32_bf16 v[8:11], v[170:173], v[216:219], v[8:11]
	v_mfma_f32_16x16x32_bf16 v[4:7], v[162:165], v[224:227], v[4:7]
	v_mfma_f32_16x16x32_bf16 v[0:3], v[170:173], v[224:227], v[0:3]
	v_mfma_f32_16x16x32_bf16 v[48:51], v[166:169], v[204:207], v[48:51]
	v_mfma_f32_16x16x32_bf16 v[40:43], v[174:177], v[204:207], v[40:43]
	v_mfma_f32_16x16x32_bf16 v[32:35], v[166:169], v[212:215], v[32:35]
	v_mfma_f32_16x16x32_bf16 v[24:27], v[174:177], v[212:215], v[24:27]
	s_setprio 2
	s_barrier
	v_mfma_f32_16x16x32_bf16 v[16:19], v[166:169], v[220:223], v[16:19]
	v_mfma_f32_16x16x32_bf16 v[8:11], v[174:177], v[220:223], v[8:11]
	v_mfma_f32_16x16x32_bf16 v[4:7], v[166:169], v[228:231], v[4:7]
	v_mfma_f32_16x16x32_bf16 v[0:3], v[174:177], v[228:231], v[0:3]
	s_setprio 0
	s_add_i32 s21, 0, 0x18000
	v_add_u32_e32 v138, s21, v139
	s_add_i32 s26, 0, 0x1c000
	ds_read_b128 v[142:145], v138
	ds_read_b128 v[146:149], v138 offset:1024
	ds_read_b128 v[150:153], v138 offset:2048
	ds_read_b128 v[154:157], v138 offset:3072
	v_add_u32_e32 v138, s26, v139
	ds_read_b128 v[162:165], v138
	ds_read_b128 v[166:169], v138 offset:1024
	ds_read_b128 v[170:173], v138 offset:2048
	ds_read_b128 v[174:177], v138 offset:3072
	s_add_u32 s50, s50, 0x40000
	s_addc_u32 s51, s51, 0
	s_mov_b32 m0, s53
	v_lshl_add_u64 v[238:239], s[50:51], 0, v[132:133]
	ds_read_b128 v[178:181], v141 offset:32768
	ds_read_b128 v[204:207], v141 offset:33792
	ds_read_b128 v[208:211], v141 offset:34816
	ds_read_b128 v[212:215], v141 offset:35840
	ds_read_b128 v[216:219], v141 offset:36864
	ds_read_b128 v[220:223], v141 offset:37888
	ds_read_b128 v[224:227], v141 offset:38912
	ds_read_b128 v[228:231], v141 offset:39936
	global_load_lds_dwordx4 v[238:239], off
	v_lshl_add_u64 v[238:239], s[50:51], 0, v[130:131]
	s_mov_b32 m0, s54
	s_nop 0
	global_load_lds_dwordx4 v[238:239], off
	s_waitcnt vmcnt(8)
	s_waitcnt lgkmcnt(0)
	s_barrier
	s_setprio 1
	s_waitcnt lgkmcnt(0)
	v_mfma_f32_16x16x32_bf16 v[124:127], v[142:145], v[178:181], v[124:127]
	v_mfma_f32_16x16x32_bf16 v[120:123], v[150:153], v[178:181], v[120:123]
	v_mfma_f32_16x16x32_bf16 v[116:119], v[142:145], v[208:211], v[116:119]
	v_mfma_f32_16x16x32_bf16 v[112:115], v[150:153], v[208:211], v[112:115]
	v_mfma_f32_16x16x32_bf16 v[100:103], v[142:145], v[216:219], v[100:103]
	v_mfma_f32_16x16x32_bf16 v[96:99], v[150:153], v[216:219], v[96:99]
	v_mfma_f32_16x16x32_bf16 v[84:87], v[142:145], v[224:227], v[84:87]
	v_mfma_f32_16x16x32_bf16 v[76:79], v[150:153], v[224:227], v[76:79]
	v_mfma_f32_16x16x32_bf16 v[124:127], v[146:149], v[204:207], v[124:127]
	v_mfma_f32_16x16x32_bf16 v[120:123], v[154:157], v[204:207], v[120:123]
	v_mfma_f32_16x16x32_bf16 v[116:119], v[146:149], v[212:215], v[116:119]
	v_mfma_f32_16x16x32_bf16 v[112:115], v[154:157], v[212:215], v[112:115]
	v_mfma_f32_16x16x32_bf16 v[100:103], v[146:149], v[220:223], v[100:103]
	v_mfma_f32_16x16x32_bf16 v[96:99], v[154:157], v[220:223], v[96:99]
	v_mfma_f32_16x16x32_bf16 v[84:87], v[146:149], v[228:231], v[84:87]
	v_mfma_f32_16x16x32_bf16 v[76:79], v[154:157], v[228:231], v[76:79]
	s_setprio 0
	s_setprio 1
	v_mfma_f32_16x16x32_bf16 v[108:111], v[162:165], v[178:181], v[108:111]
	v_mfma_f32_16x16x32_bf16 v[104:107], v[170:173], v[178:181], v[104:107]
	v_mfma_f32_16x16x32_bf16 v[92:95], v[162:165], v[208:211], v[92:95]
	v_mfma_f32_16x16x32_bf16 v[88:91], v[170:173], v[208:211], v[88:91]
	v_mfma_f32_16x16x32_bf16 v[80:83], v[162:165], v[216:219], v[80:83]
	v_mfma_f32_16x16x32_bf16 v[72:75], v[170:173], v[216:219], v[72:75]
	v_mfma_f32_16x16x32_bf16 v[68:71], v[162:165], v[224:227], v[68:71]
	v_mfma_f32_16x16x32_bf16 v[64:67], v[170:173], v[224:227], v[64:67]
	v_mfma_f32_16x16x32_bf16 v[108:111], v[166:169], v[204:207], v[108:111]
	v_mfma_f32_16x16x32_bf16 v[104:107], v[174:177], v[204:207], v[104:107]
	v_mfma_f32_16x16x32_bf16 v[92:95], v[166:169], v[212:215], v[92:95]
	v_mfma_f32_16x16x32_bf16 v[88:91], v[174:177], v[212:215], v[88:91]
	s_setprio 2
	s_barrier
; #define PG8_STAGE(bufoff, gbase, voff) do { _Pragma("unroll") for (int _i = 0; _i < 2; ++_i) \
;         __builtin_amdgcn_global_load_lds((const unsigned*)((const char*)(gbase) + (voff)[_i]), (PG8_LAS unsigned*)(lds + (bufoff) + ldsw + _i * 8192), 16, 0, 0); } while (0)
; #define PG8_LDA(dst, b, h) do { _Pragma("unroll") for (int m = 0; m < 4; ++m) _Pragma("unroll") for (int k = 0; k < 2; ++k) dst[m][k] = *(const PG8_LAS bf16x8*)(lds + PG8_SA(b, h) + aoff + m * 2048 + k * 1024); } while (0)
; #define PG8_MMA(ai, bj, At, Bt) do { __builtin_amdgcn_s_setprio(1); _Pragma("unroll") for (int m = 0; m < 4; ++m) _Pragma("unroll") for (int n = 0; n < 2; ++n) _Pragma("unroll") for (int k = 0; k < 2; ++k) \
;         acc[ai][bj][m][n] = __builtin_amdgcn_mfma_f32_16x16x32_bf16(Bt[n][k], At[m][k], acc[ai][bj][m][n], 0, 0, 0); __builtin_amdgcn_s_setprio(0); } while (0)
; #define PG8_WAIT_V(n) asm volatile("s_waitcnt vmcnt(" #n ")" ::: "memory")
; #define PG8_WAIT_L(n) asm volatile("s_waitcnt lgkmcnt(" #n ")" ::: "memory")
; #define PG8_BAR __builtin_amdgcn_s_barrier()
; #define PG8_SCHED __builtin_amdgcn_sched_barrier(0)
; template <class Epi, class Sched, bool ALIGN_EPI = false, bool SP2 = false>
; __device__ __forceinline__ void gemm_phase(PG8_LAS unsigned char* lds, const Gemm g, const Sched& S, const Epi& E, int wv) {
;     ...
;             PG8_LDA(At, 1, 1); PG8_STAGE(PG8_SB(1, 0), b3, voffB); PG8_STAGE(PG8_SB(1, 1), b3 + hstep, voffB); PG8_STAGE(PG8_SA(1, 0), a3, voffA);
;             PG8_WAIT_V(8); PG8_WAIT_L(0); PG8_BAR; PG8_MMA(1, 0, At, B0); PG8_MMA(1, 1, At, B1); PG8_BAR; PG8_SCHED;
;     ...
;         if constexpr (ALIGN_EPI) { if (wr == 0) PG8_BAR; }
	v_mfma_f32_16x16x32_bf16 v[80:83], v[166:169], v[220:223], v[80:83]
	v_mfma_f32_16x16x32_bf16 v[72:75], v[174:177], v[220:223], v[72:75]
	v_mfma_f32_16x16x32_bf16 v[68:71], v[166:169], v[228:231], v[68:71]
	v_mfma_f32_16x16x32_bf16 v[64:67], v[174:177], v[228:231], v[64:67]
	s_setprio 0
	s_add_i32 s21, s21, s30
	v_lshl_add_u64 v[158:159], v[158:159], 0, s[74:75]
	s_mov_b32 m0, s21
	ds_read_b128 v[178:181], v141 offset:49152
	ds_read_b128 v[204:207], v141 offset:50176
	ds_read_b128 v[208:211], v141 offset:51200
	ds_read_b128 v[212:215], v141 offset:52224
	ds_read_b128 v[216:219], v141 offset:53248
	ds_read_b128 v[220:223], v141 offset:54272
	ds_read_b128 v[224:227], v141 offset:55296
	ds_read_b128 v[228:231], v141 offset:56320
	global_load_lds_dwordx4 v[158:159], off
	s_add_i32 m0, s21, 0x2000
	s_add_u32 s48, s48, 0x40080
	v_lshl_add_u64 v[158:159], v[232:233], 0, s[74:75]
	s_addc_u32 s49, s49, 0
	s_add_i32 s21, s26, s30
	global_load_lds_dwordx4 v[158:159], off
	v_lshl_add_u64 v[158:159], s[48:49], 0, v[160:161]
	s_mov_b32 m0, s21
	s_nop 0
	global_load_lds_dwordx4 v[158:159], off
	v_lshl_add_u64 v[158:159], s[48:49], 0, v[128:129]
	s_add_i32 m0, s21, 0x2000
	s_nop 0
	global_load_lds_dwordx4 v[158:159], off
	v_lshl_add_u64 v[158:159], v[234:235], 0, s[74:75]
	s_mov_b32 m0, s60
	s_nop 0
	global_load_lds_dwordx4 v[158:159], off
	v_lshl_add_u64 v[158:159], v[236:237], 0, s[74:75]
	s_mov_b32 m0, s61
	s_nop 0
	global_load_lds_dwordx4 v[158:159], off
	s_waitcnt vmcnt(8)
	s_waitcnt lgkmcnt(0)
	s_barrier
	s_setprio 1
	s_waitcnt lgkmcnt(0)
	v_mfma_f32_16x16x32_bf16 v[60:63], v[142:145], v[178:181], v[60:63]
	v_mfma_f32_16x16x32_bf16 v[56:59], v[150:153], v[178:181], v[56:59]
	v_mfma_f32_16x16x32_bf16 v[52:55], v[142:145], v[208:211], v[52:55]
	v_mfma_f32_16x16x32_bf16 v[44:47], v[150:153], v[208:211], v[44:47]
	v_mfma_f32_16x16x32_bf16 v[36:39], v[142:145], v[216:219], v[36:39]
	v_mfma_f32_16x16x32_bf16 v[28:31], v[150:153], v[216:219], v[28:31]
	v_mfma_f32_16x16x32_bf16 v[20:23], v[142:145], v[224:227], v[20:23]
	v_mfma_f32_16x16x32_bf16 v[12:15], v[150:153], v[224:227], v[12:15]
	v_mfma_f32_16x16x32_bf16 v[60:63], v[146:149], v[204:207], v[60:63]
	v_mfma_f32_16x16x32_bf16 v[56:59], v[154:157], v[204:207], v[56:59]
	v_mfma_f32_16x16x32_bf16 v[52:55], v[146:149], v[212:215], v[52:55]
	v_mfma_f32_16x16x32_bf16 v[44:47], v[154:157], v[212:215], v[44:47]
	v_mfma_f32_16x16x32_bf16 v[36:39], v[146:149], v[220:223], v[36:39]
	v_mfma_f32_16x16x32_bf16 v[28:31], v[154:157], v[220:223], v[28:31]
	v_mfma_f32_16x16x32_bf16 v[20:23], v[146:149], v[228:231], v[20:23]
	v_mfma_f32_16x16x32_bf16 v[12:15], v[154:157], v[228:231], v[12:15]
	s_setprio 0
	s_setprio 1
	v_mfma_f32_16x16x32_bf16 v[48:51], v[162:165], v[178:181], v[48:51]
	v_mfma_f32_16x16x32_bf16 v[40:43], v[170:173], v[178:181], v[40:43]
	v_mfma_f32_16x16x32_bf16 v[32:35], v[162:165], v[208:211], v[32:35]
	v_mfma_f32_16x16x32_bf16 v[24:27], v[170:173], v[208:211], v[24:27]
	v_mfma_f32_16x16x32_bf16 v[16:19], v[162:165], v[216:219], v[16:19]
	v_mfma_f32_16x16x32_bf16 v[8:11], v[170:173], v[216:219], v[8:11]
	v_mfma_f32_16x16x32_bf16 v[4:7], v[162:165], v[224:227], v[4:7]
	v_mfma_f32_16x16x32_bf16 v[0:3], v[170:173], v[224:227], v[0:3]
	v_mfma_f32_16x16x32_bf16 v[48:51], v[166:169], v[204:207], v[48:51]
	v_mfma_f32_16x16x32_bf16 v[40:43], v[174:177], v[204:207], v[40:43]
	v_mfma_f32_16x16x32_bf16 v[32:35], v[166:169], v[212:215], v[32:35]
	v_mfma_f32_16x16x32_bf16 v[24:27], v[174:177], v[212:215], v[24:27]
	s_setprio 2
	s_barrier
	v_mfma_f32_16x16x32_bf16 v[16:19], v[166:169], v[220:223], v[16:19]
	v_mfma_f32_16x16x32_bf16 v[8:11], v[174:177], v[220:223], v[8:11]
	v_mfma_f32_16x16x32_bf16 v[4:7], v[166:169], v[228:231], v[4:7]
	v_mfma_f32_16x16x32_bf16 v[0:3], v[174:177], v[228:231], v[0:3]
	s_setprio 0
	s_add_i32 s67, s67, 2
	s_add_u32 s44, s44, 0x100
	s_addc_u32 s45, s45, 0
	s_add_u32 s65, s65, 0x100
	s_addc_u32 s66, s66, 0
	s_cmp_gt_u32 s67, 13
	s_cbranch_scc0 .LBB0_1188
	s_and_b64 vcc, exec, s[10:11]
	s_cbranch_vccz .LBB0_1191
	s_barrier

; #define PG8_STAGE(bufoff, gbase, voff) do { _Pragma("unroll") for (int _i = 0; _i < 2; ++_i) \
;         __builtin_amdgcn_global_load_lds((const unsigned*)((const char*)(gbase) + (voff)[_i]), (PG8_LAS unsigned*)(lds + (bufoff) + ldsw + _i * 8192), 16, 0, 0); } while (0)
; #define PG8_LDA(dst, b, h) do { _Pragma("unroll") for (int m = 0; m < 4; ++m) _Pragma("unroll") for (int k = 0; k < 2; ++k) dst[m][k] = *(const PG8_LAS bf16x8*)(lds + PG8_SA(b, h) + aoff + m * 2048 + k * 1024); } while (0)
; #define PG8_LDB(dst, b, h) do { _Pragma("unroll") for (int n = 0; n < 2; ++n) _Pragma("unroll") for (int k = 0; k < 2; ++k) dst[n][k] = *(const PG8_LAS bf16x8*)(lds + PG8_SB(b, h) + boff + n * 2048 + k * 1024); } while (0)
; #define PG8_MMA(ai, bj, At, Bt) do { __builtin_amdgcn_s_setprio(1); _Pragma("unroll") for (int m = 0; m < 4; ++m) _Pragma("unroll") for (int n = 0; n < 2; ++n) _Pragma("unroll") for (int k = 0; k < 2; ++k) \
;         acc[ai][bj][m][n] = __builtin_amdgcn_mfma_f32_16x16x32_bf16(Bt[n][k], At[m][k], acc[ai][bj][m][n], 0, 0, 0); __builtin_amdgcn_s_setprio(0); } while (0)
; #define PG8_WAIT_V(n) asm volatile("s_waitcnt vmcnt(" #n ")" ::: "memory")
; template <class Epi, class Sched, bool ALIGN_EPI = false, bool SP2 = false>
; __device__ __forceinline__ void gemm_phase(PG8_LAS unsigned char* lds, const Gemm g, const Sched& S, const Epi& E, int wv) {
;     ...
;         const char* nA = has_next ? (const char*)g.A + (size_t)nxt.pm * tstep : cA; const char* nB = has_next ? (const char*)g.Bt + (size_t)nxt.pn * tstep : cB;
;         for (int t = 0; t < nt; t += 2) {
;             const bool last = (t == nt - 2);
;             const char* a1 = cA + (size_t)(t + 1) * kstep;
;             const char* a2 = last ? nA : cA + (size_t)(t + 2) * kstep; const char* b2 = last ? nB : cB + (size_t)(t + 2) * kstep;
;             const char* a3 = a2 + kstep; const char* b3 = b2 + kstep;
;             if (last && has_next) S.a_ready(nxt);
;             if constexpr (SP2) {
;             PG8_LDB(B0, 0, 0); PG8_LDB(B1, 0, 1); PG8_SCHED; PG8_LDA(At, 0, 0); PG8_STAGE(PG8_SA(1, 1), a1 + hstep, voffA);
;             PG8_WAIT_V(8); PG8_WAIT_L(0); PG8_BAR; PG8_MMA(0, 0, At, B0); PG8_MMA(0, 1, At, B1); PG8_BAR; PG8_SCHED;
;             PG8_LDA(At, 0, 1); PG8_STAGE(PG8_SB(0, 0), b2, voffB); PG8_STAGE(PG8_SB(0, 1), b2 + hstep, voffB); PG8_STAGE(PG8_SA(0, 0), a2, voffA);
.LBB0_1956:
	s_add_u32 s21, s4, 0xfffc0080
	s_addc_u32 s26, s5, -1
	s_add_i32 s28, 0, 0x10000
	s_cmp_eq_u32 s67, 12
	s_cselect_b32 s51, s19, s26
	s_cselect_b32 s50, s63, s21
	s_cselect_b32 s49, s35, s66
	s_cselect_b32 s48, s64, s65
	s_add_i32 s21, 0, 0x14000
	v_add_u32_e32 v140, s28, v168
	v_add_u32_e32 v170, s21, v168
	ds_read_b128 v[128:131], v140
	ds_read_b128 v[132:135], v140 offset:1024
	ds_read_b128 v[136:139], v140 offset:2048
	ds_read_b128 v[140:143], v140 offset:3072
	ds_read_b128 v[144:147], v170
	ds_read_b128 v[148:151], v170 offset:1024
	ds_read_b128 v[164:167], v170 offset:2048
	ds_read_b128 v[170:173], v170 offset:3072
	v_lshl_add_u64 v[228:229], s[4:5], 0, v[158:159]
	s_add_i32 m0, s31, 0xc000
	ds_read_b128 v[174:177], v169
	ds_read_b128 v[178:181], v169 offset:1024
	ds_read_b128 v[204:207], v169 offset:2048
	ds_read_b128 v[208:211], v169 offset:3072
	ds_read_b128 v[212:215], v169 offset:4096
	ds_read_b128 v[216:219], v169 offset:5120
	ds_read_b128 v[220:223], v169 offset:6144
	ds_read_b128 v[224:227], v169 offset:7168
	global_load_lds_dwordx4 v[228:229], off
	v_lshl_add_u64 v[228:229], s[4:5], 0, v[162:163]
	s_add_i32 m0, s31, 0xe000
	s_nop 0
	global_load_lds_dwordx4 v[228:229], off
	s_waitcnt vmcnt(8)
	s_waitcnt lgkmcnt(0)
	s_barrier
	s_setprio 1
	s_waitcnt lgkmcnt(0)
	v_mfma_f32_16x16x32_bf16 v[124:127], v[128:131], v[174:177], v[124:127]
	v_mfma_f32_16x16x32_bf16 v[120:123], v[136:139], v[174:177], v[120:123]
	v_mfma_f32_16x16x32_bf16 v[108:111], v[128:131], v[204:207], v[108:111]
	v_mfma_f32_16x16x32_bf16 v[104:107], v[136:139], v[204:207], v[104:107]
	v_mfma_f32_16x16x32_bf16 v[92:95], v[128:131], v[212:215], v[92:95]
	v_mfma_f32_16x16x32_bf16 v[88:91], v[136:139], v[212:215], v[88:91]
	v_mfma_f32_16x16x32_bf16 v[76:79], v[128:131], v[220:223], v[76:79]
	v_mfma_f32_16x16x32_bf16 v[72:75], v[136:139], v[220:223], v[72:75]
	v_mfma_f32_16x16x32_bf16 v[124:127], v[132:135], v[178:181], v[124:127]
	v_mfma_f32_16x16x32_bf16 v[120:123], v[140:143], v[178:181], v[120:123]
	v_mfma_f32_16x16x32_bf16 v[108:111], v[132:135], v[208:211], v[108:111]
	v_mfma_f32_16x16x32_bf16 v[104:107], v[140:143], v[208:211], v[104:107]
	v_mfma_f32_16x16x32_bf16 v[92:95], v[132:135], v[216:219], v[92:95]
	v_mfma_f32_16x16x32_bf16 v[88:91], v[140:143], v[216:219], v[88:91]
	v_mfma_f32_16x16x32_bf16 v[76:79], v[132:135], v[224:227], v[76:79]
	v_mfma_f32_16x16x32_bf16 v[72:75], v[140:143], v[224:227], v[72:75]
	s_setprio 0
	s_setprio 1
	v_mfma_f32_16x16x32_bf16 v[116:119], v[144:147], v[174:177], v[116:119]
	v_mfma_f32_16x16x32_bf16 v[112:115], v[164:167], v[174:177], v[112:115]
	v_mfma_f32_16x16x32_bf16 v[100:103], v[144:147], v[204:207], v[100:103]
	v_mfma_f32_16x16x32_bf16 v[96:99], v[164:167], v[204:207], v[96:99]
	v_mfma_f32_16x16x32_bf16 v[84:87], v[144:147], v[212:215], v[84:87]
	v_mfma_f32_16x16x32_bf16 v[80:83], v[164:167], v[212:215], v[80:83]
	v_mfma_f32_16x16x32_bf16 v[68:71], v[144:147], v[220:223], v[68:71]
	v_mfma_f32_16x16x32_bf16 v[64:67], v[164:167], v[220:223], v[64:67]
	v_mfma_f32_16x16x32_bf16 v[116:119], v[148:151], v[178:181], v[116:119]
	v_mfma_f32_16x16x32_bf16 v[112:115], v[170:173], v[178:181], v[112:115]
	v_mfma_f32_16x16x32_bf16 v[100:103], v[148:151], v[208:211], v[100:103]
	v_mfma_f32_16x16x32_bf16 v[96:99], v[170:173], v[208:211], v[96:99]
	s_setprio 2
	s_barrier
	v_mfma_f32_16x16x32_bf16 v[84:87], v[148:151], v[216:219], v[84:87]
	v_mfma_f32_16x16x32_bf16 v[80:83], v[170:173], v[216:219], v[80:83]
	v_mfma_f32_16x16x32_bf16 v[68:71], v[148:151], v[224:227], v[68:71]
	v_mfma_f32_16x16x32_bf16 v[64:67], v[170:173], v[224:227], v[64:67]
	s_setprio 0
	s_add_i32 s26, s28, s30
	v_lshl_add_u64 v[228:229], s[48:49], 0, v[160:161]
	s_mov_b32 m0, s26
	ds_read_b128 v[174:177], v169 offset:16384
	ds_read_b128 v[178:181], v169 offset:17408
	ds_read_b128 v[204:207], v169 offset:18432
	ds_read_b128 v[208:211], v169 offset:19456
	ds_read_b128 v[212:215], v169 offset:20480
	ds_read_b128 v[216:219], v169 offset:21504
	ds_read_b128 v[220:223], v169 offset:22528
	ds_read_b128 v[224:227], v169 offset:23552
	global_load_lds_dwordx4 v[228:229], off
	s_add_i32 m0, s26, 0x2000
	s_add_u32 s76, s48, 0x40000
	v_lshl_add_u64 v[230:231], s[48:49], 0, v[152:153]
	s_addc_u32 s77, s49, 0
	s_add_i32 s21, s21, s30
	global_load_lds_dwordx4 v[230:231], off
	v_lshl_add_u64 v[232:233], s[76:77], 0, v[160:161]
	s_mov_b32 m0, s21
	v_lshl_add_u64 v[234:235], s[50:51], 0, v[154:155]
	global_load_lds_dwordx4 v[232:233], off
	v_lshl_add_u64 v[232:233], s[76:77], 0, v[152:153]
	s_add_i32 m0, s21, 0x2000
	s_nop 0
	global_load_lds_dwordx4 v[232:233], off
	v_lshl_add_u64 v[232:233], s[50:51], 0, v[156:157]
	s_mov_b32 m0, s31
	s_nop 0
	global_load_lds_dwordx4 v[232:233], off
	s_mov_b32 m0, s52
	s_nop 0
	global_load_lds_dwordx4 v[234:235], off
	s_waitcnt vmcnt(8)
	s_waitcnt lgkmcnt(0)
	s_barrier
; #define PG8_STAGE(bufoff, gbase, voff) do { _Pragma("unroll") for (int _i = 0; _i < 2; ++_i) \
;         __builtin_amdgcn_global_load_lds((const unsigned*)((const char*)(gbase) + (voff)[_i]), (PG8_LAS unsigned*)(lds + (bufoff) + ldsw + _i * 8192), 16, 0, 0); } while (0)
; #define PG8_LDA(dst, b, h) do { _Pragma("unroll") for (int m = 0; m < 4; ++m) _Pragma("unroll") for (int k = 0; k < 2; ++k) dst[m][k] = *(const PG8_LAS bf16x8*)(lds + PG8_SA(b, h) + aoff + m * 2048 + k * 1024); } while (0)
; #define PG8_LDB(dst, b, h) do { _Pragma("unroll") for (int n = 0; n < 2; ++n) _Pragma("unroll") for (int k = 0; k < 2; ++k) dst[n][k] = *(const PG8_LAS bf16x8*)(lds + PG8_SB(b, h) + boff + n * 2048 + k * 1024); } while (0)
; #define PG8_MMA(ai, bj, At, Bt) do { __builtin_amdgcn_s_setprio(1); _Pragma("unroll") for (int m = 0; m < 4; ++m) _Pragma("unroll") for (int n = 0; n < 2; ++n) _Pragma("unroll") for (int k = 0; k < 2; ++k) \
;         acc[ai][bj][m][n] = __builtin_amdgcn_mfma_f32_16x16x32_bf16(Bt[n][k], At[m][k], acc[ai][bj][m][n], 0, 0, 0); __builtin_amdgcn_s_setprio(0); } while (0)
; #define PG8_WAIT_V(n) asm volatile("s_waitcnt vmcnt(" #n ")" ::: "memory")
; #define PG8_WAIT_L(n) asm volatile("s_waitcnt lgkmcnt(" #n ")" ::: "memory")
; #define PG8_BAR __builtin_amdgcn_s_barrier()
; #define PG8_SCHED __builtin_amdgcn_sched_barrier(0)
; template <class Epi, class Sched, bool ALIGN_EPI = false, bool SP2 = false>
; __device__ __forceinline__ void gemm_phase(PG8_LAS unsigned char* lds, const Gemm g, const Sched& S, const Epi& E, int wv) {
;     ...
;             PG8_WAIT_V(8); PG8_WAIT_L(0); PG8_BAR; PG8_MMA(1, 0, At, B0); PG8_MMA(1, 1, At, B1); PG8_BAR; PG8_SCHED;
;             PG8_LDB(B0, 1, 0); PG8_LDB(B1, 1, 1); PG8_SCHED; PG8_LDA(At, 1, 0); PG8_STAGE(PG8_SA(0, 1), a2 + hstep, voffA);
;             PG8_WAIT_V(8); PG8_WAIT_L(0); PG8_BAR; PG8_MMA(0, 0, At, B0); PG8_MMA(0, 1, At, B1); PG8_BAR; PG8_SCHED;
	s_setprio 1
	s_waitcnt lgkmcnt(0)
	v_mfma_f32_16x16x32_bf16 v[60:63], v[128:131], v[174:177], v[60:63]
	v_mfma_f32_16x16x32_bf16 v[56:59], v[136:139], v[174:177], v[56:59]
	v_mfma_f32_16x16x32_bf16 v[44:47], v[128:131], v[204:207], v[44:47]
	v_mfma_f32_16x16x32_bf16 v[40:43], v[136:139], v[204:207], v[40:43]
	v_mfma_f32_16x16x32_bf16 v[28:31], v[128:131], v[212:215], v[28:31]
	v_mfma_f32_16x16x32_bf16 v[24:27], v[136:139], v[212:215], v[24:27]
	v_mfma_f32_16x16x32_bf16 v[12:15], v[128:131], v[220:223], v[12:15]
	v_mfma_f32_16x16x32_bf16 v[8:11], v[136:139], v[220:223], v[8:11]
	v_mfma_f32_16x16x32_bf16 v[60:63], v[132:135], v[178:181], v[60:63]
	v_mfma_f32_16x16x32_bf16 v[56:59], v[140:143], v[178:181], v[56:59]
	v_mfma_f32_16x16x32_bf16 v[44:47], v[132:135], v[208:211], v[44:47]
	v_mfma_f32_16x16x32_bf16 v[40:43], v[140:143], v[208:211], v[40:43]
	v_mfma_f32_16x16x32_bf16 v[28:31], v[132:135], v[216:219], v[28:31]
	v_mfma_f32_16x16x32_bf16 v[24:27], v[140:143], v[216:219], v[24:27]
	v_mfma_f32_16x16x32_bf16 v[12:15], v[132:135], v[224:227], v[12:15]
	v_mfma_f32_16x16x32_bf16 v[8:11], v[140:143], v[224:227], v[8:11]
	s_setprio 0
	s_setprio 1
	v_mfma_f32_16x16x32_bf16 v[52:55], v[144:147], v[174:177], v[52:55]
	v_mfma_f32_16x16x32_bf16 v[48:51], v[164:167], v[174:177], v[48:51]
	v_mfma_f32_16x16x32_bf16 v[36:39], v[144:147], v[204:207], v[36:39]
	v_mfma_f32_16x16x32_bf16 v[32:35], v[164:167], v[204:207], v[32:35]
	v_mfma_f32_16x16x32_bf16 v[20:23], v[144:147], v[212:215], v[20:23]
	v_mfma_f32_16x16x32_bf16 v[16:19], v[164:167], v[212:215], v[16:19]
	v_mfma_f32_16x16x32_bf16 v[4:7], v[144:147], v[220:223], v[4:7]
	v_mfma_f32_16x16x32_bf16 v[0:3], v[164:167], v[220:223], v[0:3]
	v_mfma_f32_16x16x32_bf16 v[52:55], v[148:151], v[178:181], v[52:55]
	v_mfma_f32_16x16x32_bf16 v[48:51], v[170:173], v[178:181], v[48:51]
	v_mfma_f32_16x16x32_bf16 v[36:39], v[148:151], v[208:211], v[36:39]
	v_mfma_f32_16x16x32_bf16 v[32:35], v[170:173], v[208:211], v[32:35]
	s_setprio 2
	s_barrier
	v_mfma_f32_16x16x32_bf16 v[20:23], v[148:151], v[216:219], v[20:23]
	v_mfma_f32_16x16x32_bf16 v[16:19], v[170:173], v[216:219], v[16:19]
	v_mfma_f32_16x16x32_bf16 v[4:7], v[148:151], v[224:227], v[4:7]
	v_mfma_f32_16x16x32_bf16 v[0:3], v[170:173], v[224:227], v[0:3]
	s_setprio 0
	s_add_i32 s21, 0, 0x18000
	s_add_i32 s26, 0, 0x1c000
	v_add_u32_e32 v140, s21, v168
	v_add_u32_e32 v170, s26, v168
	ds_read_b128 v[128:131], v140
	ds_read_b128 v[132:135], v140 offset:1024
	ds_read_b128 v[136:139], v140 offset:2048
	ds_read_b128 v[140:143], v140 offset:3072
	ds_read_b128 v[144:147], v170
	ds_read_b128 v[148:151], v170 offset:1024
	ds_read_b128 v[164:167], v170 offset:2048
	ds_read_b128 v[170:173], v170 offset:3072
	s_add_u32 s50, s50, 0x40000
	s_addc_u32 s51, s51, 0
	s_mov_b32 m0, s53
	v_lshl_add_u64 v[236:237], s[50:51], 0, v[156:157]
	ds_read_b128 v[174:177], v169 offset:32768
	ds_read_b128 v[178:181], v169 offset:33792
	ds_read_b128 v[204:207], v169 offset:34816
	ds_read_b128 v[208:211], v169 offset:35840
	ds_read_b128 v[212:215], v169 offset:36864
	ds_read_b128 v[216:219], v169 offset:37888
	ds_read_b128 v[220:223], v169 offset:38912
	ds_read_b128 v[224:227], v169 offset:39936
	global_load_lds_dwordx4 v[236:237], off
	v_lshl_add_u64 v[236:237], s[50:51], 0, v[154:155]
	s_mov_b32 m0, s54
	s_nop 0
	global_load_lds_dwordx4 v[236:237], off
	s_waitcnt vmcnt(8)
	s_waitcnt lgkmcnt(0)
	s_barrier
	s_setprio 1
	s_waitcnt lgkmcnt(0)
	v_mfma_f32_16x16x32_bf16 v[124:127], v[128:131], v[174:177], v[124:127]
	v_mfma_f32_16x16x32_bf16 v[120:123], v[136:139], v[174:177], v[120:123]
	v_mfma_f32_16x16x32_bf16 v[108:111], v[128:131], v[204:207], v[108:111]
	v_mfma_f32_16x16x32_bf16 v[104:107], v[136:139], v[204:207], v[104:107]
	v_mfma_f32_16x16x32_bf16 v[92:95], v[128:131], v[212:215], v[92:95]
	v_mfma_f32_16x16x32_bf16 v[88:91], v[136:139], v[212:215], v[88:91]
	v_mfma_f32_16x16x32_bf16 v[76:79], v[128:131], v[220:223], v[76:79]
	v_mfma_f32_16x16x32_bf16 v[72:75], v[136:139], v[220:223], v[72:75]
	v_mfma_f32_16x16x32_bf16 v[124:127], v[132:135], v[178:181], v[124:127]
	v_mfma_f32_16x16x32_bf16 v[120:123], v[140:143], v[178:181], v[120:123]
	v_mfma_f32_16x16x32_bf16 v[108:111], v[132:135], v[208:211], v[108:111]
	v_mfma_f32_16x16x32_bf16 v[104:107], v[140:143], v[208:211], v[104:107]
	v_mfma_f32_16x16x32_bf16 v[92:95], v[132:135], v[216:219], v[92:95]
	v_mfma_f32_16x16x32_bf16 v[88:91], v[140:143], v[216:219], v[88:91]
	v_mfma_f32_16x16x32_bf16 v[76:79], v[132:135], v[224:227], v[76:79]
	v_mfma_f32_16x16x32_bf16 v[72:75], v[140:143], v[224:227], v[72:75]
	s_setprio 0
	s_setprio 1
	v_mfma_f32_16x16x32_bf16 v[116:119], v[144:147], v[174:177], v[116:119]
	v_mfma_f32_16x16x32_bf16 v[112:115], v[164:167], v[174:177], v[112:115]
	v_mfma_f32_16x16x32_bf16 v[100:103], v[144:147], v[204:207], v[100:103]
	v_mfma_f32_16x16x32_bf16 v[96:99], v[164:167], v[204:207], v[96:99]
	v_mfma_f32_16x16x32_bf16 v[84:87], v[144:147], v[212:215], v[84:87]
	v_mfma_f32_16x16x32_bf16 v[80:83], v[164:167], v[212:215], v[80:83]
	v_mfma_f32_16x16x32_bf16 v[68:71], v[144:147], v[220:223], v[68:71]
	v_mfma_f32_16x16x32_bf16 v[64:67], v[164:167], v[220:223], v[64:67]
	v_mfma_f32_16x16x32_bf16 v[116:119], v[148:151], v[178:181], v[116:119]
	v_mfma_f32_16x16x32_bf16 v[112:115], v[170:173], v[178:181], v[112:115]
	v_mfma_f32_16x16x32_bf16 v[100:103], v[148:151], v[208:211], v[100:103]
	v_mfma_f32_16x16x32_bf16 v[96:99], v[170:173], v[208:211], v[96:99]
	s_setprio 2
	s_barrier
; #define PG8_STAGE(bufoff, gbase, voff) do { _Pragma("unroll") for (int _i = 0; _i < 2; ++_i) \
;         __builtin_amdgcn_global_load_lds((const unsigned*)((const char*)(gbase) + (voff)[_i]), (PG8_LAS unsigned*)(lds + (bufoff) + ldsw + _i * 8192), 16, 0, 0); } while (0)
; #define PG8_LDA(dst, b, h) do { _Pragma("unroll") for (int m = 0; m < 4; ++m) _Pragma("unroll") for (int k = 0; k < 2; ++k) dst[m][k] = *(const PG8_LAS bf16x8*)(lds + PG8_SA(b, h) + aoff + m * 2048 + k * 1024); } while (0)
; #define PG8_MMA(ai, bj, At, Bt) do { __builtin_amdgcn_s_setprio(1); _Pragma("unroll") for (int m = 0; m < 4; ++m) _Pragma("unroll") for (int n = 0; n < 2; ++n) _Pragma("unroll") for (int k = 0; k < 2; ++k) \
;         acc[ai][bj][m][n] = __builtin_amdgcn_mfma_f32_16x16x32_bf16(Bt[n][k], At[m][k], acc[ai][bj][m][n], 0, 0, 0); __builtin_amdgcn_s_setprio(0); } while (0)
; #define PG8_WAIT_V(n) asm volatile("s_waitcnt vmcnt(" #n ")" ::: "memory")
; #define PG8_WAIT_L(n) asm volatile("s_waitcnt lgkmcnt(" #n ")" ::: "memory")
; #define PG8_BAR __builtin_amdgcn_s_barrier()
; #define PG8_SCHED __builtin_amdgcn_sched_barrier(0)
; template <class Epi, class Sched, bool ALIGN_EPI = false, bool SP2 = false>
; __device__ __forceinline__ void gemm_phase(PG8_LAS unsigned char* lds, const Gemm g, const Sched& S, const Epi& E, int wv) {
;     ...
;             PG8_LDA(At, 1, 1); PG8_STAGE(PG8_SB(1, 0), b3, voffB); PG8_STAGE(PG8_SB(1, 1), b3 + hstep, voffB); PG8_STAGE(PG8_SA(1, 0), a3, voffA);
;             PG8_WAIT_V(8); PG8_WAIT_L(0); PG8_BAR; PG8_MMA(1, 0, At, B0); PG8_MMA(1, 1, At, B1); PG8_BAR; PG8_SCHED;
;     ...
;         if constexpr (ALIGN_EPI) { if (wr == 0) PG8_BAR; }
	v_mfma_f32_16x16x32_bf16 v[84:87], v[148:151], v[216:219], v[84:87]
	v_mfma_f32_16x16x32_bf16 v[80:83], v[170:173], v[216:219], v[80:83]
	v_mfma_f32_16x16x32_bf16 v[68:71], v[148:151], v[224:227], v[68:71]
	v_mfma_f32_16x16x32_bf16 v[64:67], v[170:173], v[224:227], v[64:67]
	s_setprio 0
	s_add_i32 s21, s21, s30
	v_lshl_add_u64 v[228:229], v[228:229], 0, s[74:75]
	s_mov_b32 m0, s21
	ds_read_b128 v[174:177], v169 offset:49152
	ds_read_b128 v[178:181], v169 offset:50176
	ds_read_b128 v[204:207], v169 offset:51200
	ds_read_b128 v[208:211], v169 offset:52224
	ds_read_b128 v[212:215], v169 offset:53248
	ds_read_b128 v[216:219], v169 offset:54272
	ds_read_b128 v[220:223], v169 offset:55296
	ds_read_b128 v[224:227], v169 offset:56320
	global_load_lds_dwordx4 v[228:229], off
	s_add_i32 m0, s21, 0x2000
	s_add_u32 s48, s48, 0x40080
	v_lshl_add_u64 v[228:229], v[230:231], 0, s[74:75]
	s_addc_u32 s49, s49, 0
	s_add_i32 s21, s26, s30
	global_load_lds_dwordx4 v[228:229], off
	v_lshl_add_u64 v[228:229], s[48:49], 0, v[160:161]
	s_mov_b32 m0, s21
	s_nop 0
	global_load_lds_dwordx4 v[228:229], off
	v_lshl_add_u64 v[228:229], s[48:49], 0, v[152:153]
	s_add_i32 m0, s21, 0x2000
	s_nop 0
	global_load_lds_dwordx4 v[228:229], off
	v_lshl_add_u64 v[228:229], v[232:233], 0, s[74:75]
	s_mov_b32 m0, s60
	s_nop 0
	global_load_lds_dwordx4 v[228:229], off
	v_lshl_add_u64 v[228:229], v[234:235], 0, s[74:75]
	s_mov_b32 m0, s61
	s_nop 0
	global_load_lds_dwordx4 v[228:229], off
	s_waitcnt vmcnt(8)
	s_waitcnt lgkmcnt(0)
	s_barrier
	s_setprio 1
	s_waitcnt lgkmcnt(0)
	v_mfma_f32_16x16x32_bf16 v[60:63], v[128:131], v[174:177], v[60:63]
	v_mfma_f32_16x16x32_bf16 v[56:59], v[136:139], v[174:177], v[56:59]
	v_mfma_f32_16x16x32_bf16 v[44:47], v[128:131], v[204:207], v[44:47]
	v_mfma_f32_16x16x32_bf16 v[40:43], v[136:139], v[204:207], v[40:43]
	v_mfma_f32_16x16x32_bf16 v[28:31], v[128:131], v[212:215], v[28:31]
	v_mfma_f32_16x16x32_bf16 v[24:27], v[136:139], v[212:215], v[24:27]
	v_mfma_f32_16x16x32_bf16 v[12:15], v[128:131], v[220:223], v[12:15]
	v_mfma_f32_16x16x32_bf16 v[8:11], v[136:139], v[220:223], v[8:11]
	v_mfma_f32_16x16x32_bf16 v[60:63], v[132:135], v[178:181], v[60:63]
	v_mfma_f32_16x16x32_bf16 v[56:59], v[140:143], v[178:181], v[56:59]
	v_mfma_f32_16x16x32_bf16 v[44:47], v[132:135], v[208:211], v[44:47]
	v_mfma_f32_16x16x32_bf16 v[40:43], v[140:143], v[208:211], v[40:43]
	v_mfma_f32_16x16x32_bf16 v[28:31], v[132:135], v[216:219], v[28:31]
	v_mfma_f32_16x16x32_bf16 v[24:27], v[140:143], v[216:219], v[24:27]
	v_mfma_f32_16x16x32_bf16 v[12:15], v[132:135], v[224:227], v[12:15]
	v_mfma_f32_16x16x32_bf16 v[8:11], v[140:143], v[224:227], v[8:11]
	s_setprio 0
	s_setprio 1
	v_mfma_f32_16x16x32_bf16 v[52:55], v[144:147], v[174:177], v[52:55]
	v_mfma_f32_16x16x32_bf16 v[48:51], v[164:167], v[174:177], v[48:51]
	v_mfma_f32_16x16x32_bf16 v[36:39], v[144:147], v[204:207], v[36:39]
	v_mfma_f32_16x16x32_bf16 v[32:35], v[164:167], v[204:207], v[32:35]
	v_mfma_f32_16x16x32_bf16 v[20:23], v[144:147], v[212:215], v[20:23]
	v_mfma_f32_16x16x32_bf16 v[16:19], v[164:167], v[212:215], v[16:19]
	v_mfma_f32_16x16x32_bf16 v[4:7], v[144:147], v[220:223], v[4:7]
	v_mfma_f32_16x16x32_bf16 v[0:3], v[164:167], v[220:223], v[0:3]
	v_mfma_f32_16x16x32_bf16 v[52:55], v[148:151], v[178:181], v[52:55]
	v_mfma_f32_16x16x32_bf16 v[48:51], v[170:173], v[178:181], v[48:51]
	v_mfma_f32_16x16x32_bf16 v[36:39], v[148:151], v[208:211], v[36:39]
	v_mfma_f32_16x16x32_bf16 v[32:35], v[170:173], v[208:211], v[32:35]
	s_setprio 2
	s_barrier
	v_mfma_f32_16x16x32_bf16 v[20:23], v[148:151], v[216:219], v[20:23]
	v_mfma_f32_16x16x32_bf16 v[16:19], v[170:173], v[216:219], v[16:19]
	v_mfma_f32_16x16x32_bf16 v[4:7], v[148:151], v[224:227], v[4:7]
	v_mfma_f32_16x16x32_bf16 v[0:3], v[170:173], v[224:227], v[0:3]
	s_setprio 0
	s_add_i32 s67, s67, 2
	s_add_u32 s4, s4, 0x100
	s_addc_u32 s5, s5, 0
	s_add_u32 s65, s65, 0x100
	s_addc_u32 s66, s66, 0
	s_cmp_gt_u32 s67, 13
	s_cbranch_scc0 .LBB0_1956
	s_and_b64 vcc, exec, s[12:13]
	s_cbranch_vccz .LBB0_1959
	s_barrier

; #define PG8_STAGE(bufoff, gbase, voff) do { _Pragma("unroll") for (int _i = 0; _i < 2; ++_i) \
;         __builtin_amdgcn_global_load_lds((const unsigned*)((const char*)(gbase) + (voff)[_i]), (PG8_LAS unsigned*)(lds + (bufoff) + ldsw + _i * 8192), 16, 0, 0); } while (0)
; #define PG8_LDA(dst, b, h) do { _Pragma("unroll") for (int m = 0; m < 4; ++m) _Pragma("unroll") for (int k = 0; k < 2; ++k) dst[m][k] = *(const PG8_LAS bf16x8*)(lds + PG8_SA(b, h) + aoff + m * 2048 + k * 1024); } while (0)
; #define PG8_LDB(dst, b, h) do { _Pragma("unroll") for (int n = 0; n < 2; ++n) _Pragma("unroll") for (int k = 0; k < 2; ++k) dst[n][k] = *(const PG8_LAS bf16x8*)(lds + PG8_SB(b, h) + boff + n * 2048 + k * 1024); } while (0)
; #define PG8_MMA(ai, bj, At, Bt) do { __builtin_amdgcn_s_setprio(1); _Pragma("unroll") for (int m = 0; m < 4; ++m) _Pragma("unroll") for (int n = 0; n < 2; ++n) _Pragma("unroll") for (int k = 0; k < 2; ++k) \
;         acc[ai][bj][m][n] = __builtin_amdgcn_mfma_f32_16x16x32_bf16(Bt[n][k], At[m][k], acc[ai][bj][m][n], 0, 0, 0); __builtin_amdgcn_s_setprio(0); } while (0)
; #define PG8_WAIT_V(n) asm volatile("s_waitcnt vmcnt(" #n ")" ::: "memory")
; template <class Epi, class Sched, bool ALIGN_EPI = false, bool SP2 = false>
; __device__ __forceinline__ void gemm_phase(PG8_LAS unsigned char* lds, const Gemm g, const Sched& S, const Epi& E, int wv) {
;     ...
;         const char* nA = has_next ? (const char*)g.A + (size_t)nxt.pm * tstep : cA; const char* nB = has_next ? (const char*)g.Bt + (size_t)nxt.pn * tstep : cB;
;         for (int t = 0; t < nt; t += 2) {
;             const bool last = (t == nt - 2);
;             const char* a1 = cA + (size_t)(t + 1) * kstep;
;             const char* a2 = last ? nA : cA + (size_t)(t + 2) * kstep; const char* b2 = last ? nB : cB + (size_t)(t + 2) * kstep;
;             const char* a3 = a2 + kstep; const char* b3 = b2 + kstep;
;             if (last && has_next) S.a_ready(nxt);
;             if constexpr (SP2) {
;             PG8_LDB(B0, 0, 0); PG8_LDB(B1, 0, 1); PG8_SCHED; PG8_LDA(At, 0, 0); PG8_STAGE(PG8_SA(1, 1), a1 + hstep, voffA);
;             PG8_WAIT_V(8); PG8_WAIT_L(0); PG8_BAR; PG8_MMA(0, 0, At, B0); PG8_MMA(0, 1, At, B1); PG8_BAR; PG8_SCHED;
;             PG8_LDA(At, 0, 1); PG8_STAGE(PG8_SB(0, 0), b2, voffB); PG8_STAGE(PG8_SB(0, 1), b2 + hstep, voffB); PG8_STAGE(PG8_SA(0, 0), a2, voffA);
.LBB0_2108:
	s_add_u32 s21, s44, 0xfffc0080
	s_addc_u32 s26, s45, -1
	s_add_i32 s28, 0, 0x10000
	s_cmp_eq_u32 s67, 12
	s_cselect_b32 s51, s13, s26
	s_cselect_b32 s50, s63, s21
	v_add_u32_e32 v138, s28, v141
	s_cselect_b32 s49, s19, s66
	s_cselect_b32 s48, s64, s65
	s_add_i32 s21, 0, 0x14000
	ds_read_b128 v[144:147], v138
	ds_read_b128 v[148:151], v138 offset:1024
	ds_read_b128 v[152:155], v138 offset:2048
	ds_read_b128 v[156:159], v138 offset:3072
	v_add_u32_e32 v138, s21, v141
	ds_read_b128 v[162:165], v138
	ds_read_b128 v[166:169], v138 offset:1024
	ds_read_b128 v[170:173], v138 offset:2048
	ds_read_b128 v[174:177], v138 offset:3072
	v_lshl_add_u64 v[138:139], s[44:45], 0, v[134:135]
	s_add_i32 m0, s31, 0xc000
	ds_read_b128 v[178:181], v143
	ds_read_b128 v[204:207], v143 offset:1024
	ds_read_b128 v[208:211], v143 offset:2048
	ds_read_b128 v[212:215], v143 offset:3072
	ds_read_b128 v[216:219], v143 offset:4096
	ds_read_b128 v[220:223], v143 offset:5120
	ds_read_b128 v[224:227], v143 offset:6144
	ds_read_b128 v[228:231], v143 offset:7168
	global_load_lds_dwordx4 v[138:139], off
	v_lshl_add_u64 v[138:139], s[44:45], 0, v[136:137]
	s_add_i32 m0, s31, 0xe000
	s_nop 0
	global_load_lds_dwordx4 v[138:139], off
	s_waitcnt vmcnt(8)
	s_waitcnt lgkmcnt(0)
	s_barrier
	s_setprio 1
	s_waitcnt lgkmcnt(0)
	v_mfma_f32_16x16x32_bf16 v[124:127], v[144:147], v[178:181], v[124:127]
	v_mfma_f32_16x16x32_bf16 v[120:123], v[152:155], v[178:181], v[120:123]
	v_mfma_f32_16x16x32_bf16 v[108:111], v[144:147], v[208:211], v[108:111]
	v_mfma_f32_16x16x32_bf16 v[104:107], v[152:155], v[208:211], v[104:107]
	v_mfma_f32_16x16x32_bf16 v[92:95], v[144:147], v[216:219], v[92:95]
	v_mfma_f32_16x16x32_bf16 v[88:91], v[152:155], v[216:219], v[88:91]
	v_mfma_f32_16x16x32_bf16 v[76:79], v[144:147], v[224:227], v[76:79]
	v_mfma_f32_16x16x32_bf16 v[72:75], v[152:155], v[224:227], v[72:75]
	v_mfma_f32_16x16x32_bf16 v[124:127], v[148:151], v[204:207], v[124:127]
	v_mfma_f32_16x16x32_bf16 v[120:123], v[156:159], v[204:207], v[120:123]
	v_mfma_f32_16x16x32_bf16 v[108:111], v[148:151], v[212:215], v[108:111]
	v_mfma_f32_16x16x32_bf16 v[104:107], v[156:159], v[212:215], v[104:107]
	v_mfma_f32_16x16x32_bf16 v[92:95], v[148:151], v[220:223], v[92:95]
	v_mfma_f32_16x16x32_bf16 v[88:91], v[156:159], v[220:223], v[88:91]
	v_mfma_f32_16x16x32_bf16 v[76:79], v[148:151], v[228:231], v[76:79]
	v_mfma_f32_16x16x32_bf16 v[72:75], v[156:159], v[228:231], v[72:75]
	s_setprio 0
	s_setprio 1
	v_mfma_f32_16x16x32_bf16 v[116:119], v[162:165], v[178:181], v[116:119]
	v_mfma_f32_16x16x32_bf16 v[112:115], v[170:173], v[178:181], v[112:115]
	v_mfma_f32_16x16x32_bf16 v[100:103], v[162:165], v[208:211], v[100:103]
	v_mfma_f32_16x16x32_bf16 v[96:99], v[170:173], v[208:211], v[96:99]
	v_mfma_f32_16x16x32_bf16 v[84:87], v[162:165], v[216:219], v[84:87]
	v_mfma_f32_16x16x32_bf16 v[80:83], v[170:173], v[216:219], v[80:83]
	v_mfma_f32_16x16x32_bf16 v[68:71], v[162:165], v[224:227], v[68:71]
	v_mfma_f32_16x16x32_bf16 v[64:67], v[170:173], v[224:227], v[64:67]
	v_mfma_f32_16x16x32_bf16 v[116:119], v[166:169], v[204:207], v[116:119]
	v_mfma_f32_16x16x32_bf16 v[112:115], v[174:177], v[204:207], v[112:115]
	v_mfma_f32_16x16x32_bf16 v[100:103], v[166:169], v[212:215], v[100:103]
	v_mfma_f32_16x16x32_bf16 v[96:99], v[174:177], v[212:215], v[96:99]
	s_setprio 2
	s_barrier
	v_mfma_f32_16x16x32_bf16 v[84:87], v[166:169], v[220:223], v[84:87]
	v_mfma_f32_16x16x32_bf16 v[80:83], v[174:177], v[220:223], v[80:83]
	v_mfma_f32_16x16x32_bf16 v[68:71], v[166:169], v[228:231], v[68:71]
	v_mfma_f32_16x16x32_bf16 v[64:67], v[174:177], v[228:231], v[64:67]
	s_setprio 0
	s_add_i32 s26, s28, s30
	v_lshl_add_u64 v[138:139], s[48:49], 0, v[160:161]
	s_mov_b32 m0, s26
	ds_read_b128 v[178:181], v143 offset:16384
	ds_read_b128 v[204:207], v143 offset:17408
	ds_read_b128 v[208:211], v143 offset:18432
	ds_read_b128 v[212:215], v143 offset:19456
	ds_read_b128 v[216:219], v143 offset:20480
	ds_read_b128 v[220:223], v143 offset:21504
	ds_read_b128 v[224:227], v143 offset:22528
	ds_read_b128 v[228:231], v143 offset:23552
	global_load_lds_dwordx4 v[138:139], off
	s_add_i32 m0, s26, 0x2000
	s_add_u32 s76, s48, 0x40000
	v_lshl_add_u64 v[232:233], s[48:49], 0, v[128:129]
	s_addc_u32 s77, s49, 0
	s_add_i32 s21, s21, s30
	global_load_lds_dwordx4 v[232:233], off
	v_lshl_add_u64 v[234:235], s[76:77], 0, v[160:161]
	s_mov_b32 m0, s21
	v_lshl_add_u64 v[236:237], s[50:51], 0, v[130:131]
	global_load_lds_dwordx4 v[234:235], off
	v_lshl_add_u64 v[234:235], s[76:77], 0, v[128:129]
	s_add_i32 m0, s21, 0x2000
	s_nop 0
	global_load_lds_dwordx4 v[234:235], off
	v_lshl_add_u64 v[234:235], s[50:51], 0, v[132:133]
	s_mov_b32 m0, s31
	s_nop 0
	global_load_lds_dwordx4 v[234:235], off
	s_mov_b32 m0, s52
	s_nop 0
	global_load_lds_dwordx4 v[236:237], off
	s_waitcnt vmcnt(8)
	s_waitcnt lgkmcnt(0)
	s_barrier
; #define PG8_STAGE(bufoff, gbase, voff) do { _Pragma("unroll") for (int _i = 0; _i < 2; ++_i) \
;         __builtin_amdgcn_global_load_lds((const unsigned*)((const char*)(gbase) + (voff)[_i]), (PG8_LAS unsigned*)(lds + (bufoff) + ldsw + _i * 8192), 16, 0, 0); } while (0)
; #define PG8_LDA(dst, b, h) do { _Pragma("unroll") for (int m = 0; m < 4; ++m) _Pragma("unroll") for (int k = 0; k < 2; ++k) dst[m][k] = *(const PG8_LAS bf16x8*)(lds + PG8_SA(b, h) + aoff + m * 2048 + k * 1024); } while (0)
; #define PG8_LDB(dst, b, h) do { _Pragma("unroll") for (int n = 0; n < 2; ++n) _Pragma("unroll") for (int k = 0; k < 2; ++k) dst[n][k] = *(const PG8_LAS bf16x8*)(lds + PG8_SB(b, h) + boff + n * 2048 + k * 1024); } while (0)
; #define PG8_MMA(ai, bj, At, Bt) do { __builtin_amdgcn_s_setprio(1); _Pragma("unroll") for (int m = 0; m < 4; ++m) _Pragma("unroll") for (int n = 0; n < 2; ++n) _Pragma("unroll") for (int k = 0; k < 2; ++k) \
;         acc[ai][bj][m][n] = __builtin_amdgcn_mfma_f32_16x16x32_bf16(Bt[n][k], At[m][k], acc[ai][bj][m][n], 0, 0, 0); __builtin_amdgcn_s_setprio(0); } while (0)
; #define PG8_WAIT_V(n) asm volatile("s_waitcnt vmcnt(" #n ")" ::: "memory")
; #define PG8_WAIT_L(n) asm volatile("s_waitcnt lgkmcnt(" #n ")" ::: "memory")
; #define PG8_BAR __builtin_amdgcn_s_barrier()
; #define PG8_SCHED __builtin_amdgcn_sched_barrier(0)
; template <class Epi, class Sched, bool ALIGN_EPI = false, bool SP2 = false>
; __device__ __forceinline__ void gemm_phase(PG8_LAS unsigned char* lds, const Gemm g, const Sched& S, const Epi& E, int wv) {
;     ...
;             PG8_WAIT_V(8); PG8_WAIT_L(0); PG8_BAR; PG8_MMA(1, 0, At, B0); PG8_MMA(1, 1, At, B1); PG8_BAR; PG8_SCHED;
;             PG8_LDB(B0, 1, 0); PG8_LDB(B1, 1, 1); PG8_SCHED; PG8_LDA(At, 1, 0); PG8_STAGE(PG8_SA(0, 1), a2 + hstep, voffA);
;             PG8_WAIT_V(8); PG8_WAIT_L(0); PG8_BAR; PG8_MMA(0, 0, At, B0); PG8_MMA(0, 1, At, B1); PG8_BAR; PG8_SCHED;
	s_setprio 1
	s_waitcnt lgkmcnt(0)
	v_mfma_f32_16x16x32_bf16 v[60:63], v[144:147], v[178:181], v[60:63]
	v_mfma_f32_16x16x32_bf16 v[56:59], v[152:155], v[178:181], v[56:59]
	v_mfma_f32_16x16x32_bf16 v[44:47], v[144:147], v[208:211], v[44:47]
	v_mfma_f32_16x16x32_bf16 v[40:43], v[152:155], v[208:211], v[40:43]
	v_mfma_f32_16x16x32_bf16 v[28:31], v[144:147], v[216:219], v[28:31]
	v_mfma_f32_16x16x32_bf16 v[24:27], v[152:155], v[216:219], v[24:27]
	v_mfma_f32_16x16x32_bf16 v[12:15], v[144:147], v[224:227], v[12:15]
	v_mfma_f32_16x16x32_bf16 v[8:11], v[152:155], v[224:227], v[8:11]
	v_mfma_f32_16x16x32_bf16 v[60:63], v[148:151], v[204:207], v[60:63]
	v_mfma_f32_16x16x32_bf16 v[56:59], v[156:159], v[204:207], v[56:59]
	v_mfma_f32_16x16x32_bf16 v[44:47], v[148:151], v[212:215], v[44:47]
	v_mfma_f32_16x16x32_bf16 v[40:43], v[156:159], v[212:215], v[40:43]
	v_mfma_f32_16x16x32_bf16 v[28:31], v[148:151], v[220:223], v[28:31]
	v_mfma_f32_16x16x32_bf16 v[24:27], v[156:159], v[220:223], v[24:27]
	v_mfma_f32_16x16x32_bf16 v[12:15], v[148:151], v[228:231], v[12:15]
	v_mfma_f32_16x16x32_bf16 v[8:11], v[156:159], v[228:231], v[8:11]
	s_setprio 0
	s_setprio 1
	v_mfma_f32_16x16x32_bf16 v[52:55], v[162:165], v[178:181], v[52:55]
	v_mfma_f32_16x16x32_bf16 v[48:51], v[170:173], v[178:181], v[48:51]
	v_mfma_f32_16x16x32_bf16 v[36:39], v[162:165], v[208:211], v[36:39]
	v_mfma_f32_16x16x32_bf16 v[32:35], v[170:173], v[208:211], v[32:35]
	v_mfma_f32_16x16x32_bf16 v[20:23], v[162:165], v[216:219], v[20:23]
	v_mfma_f32_16x16x32_bf16 v[16:19], v[170:173], v[216:219], v[16:19]
	v_mfma_f32_16x16x32_bf16 v[4:7], v[162:165], v[224:227], v[4:7]
	v_mfma_f32_16x16x32_bf16 v[0:3], v[170:173], v[224:227], v[0:3]
	v_mfma_f32_16x16x32_bf16 v[52:55], v[166:169], v[204:207], v[52:55]
	v_mfma_f32_16x16x32_bf16 v[48:51], v[174:177], v[204:207], v[48:51]
	v_mfma_f32_16x16x32_bf16 v[36:39], v[166:169], v[212:215], v[36:39]
	v_mfma_f32_16x16x32_bf16 v[32:35], v[174:177], v[212:215], v[32:35]
	s_setprio 2
	s_barrier
	v_mfma_f32_16x16x32_bf16 v[20:23], v[166:169], v[220:223], v[20:23]
	v_mfma_f32_16x16x32_bf16 v[16:19], v[174:177], v[220:223], v[16:19]
	v_mfma_f32_16x16x32_bf16 v[4:7], v[166:169], v[228:231], v[4:7]
	v_mfma_f32_16x16x32_bf16 v[0:3], v[174:177], v[228:231], v[0:3]
	s_setprio 0
	s_add_i32 s21, 0, 0x18000
	v_add_u32_e32 v140, s21, v141
	s_add_i32 s26, 0, 0x1c000
	ds_read_b128 v[144:147], v140
	ds_read_b128 v[148:151], v140 offset:1024
	ds_read_b128 v[152:155], v140 offset:2048
	ds_read_b128 v[156:159], v140 offset:3072
	v_add_u32_e32 v140, s26, v141
	ds_read_b128 v[162:165], v140
	ds_read_b128 v[166:169], v140 offset:1024
	ds_read_b128 v[170:173], v140 offset:2048
	ds_read_b128 v[174:177], v140 offset:3072
	s_add_u32 s50, s50, 0x40000
	s_addc_u32 s51, s51, 0
	s_mov_b32 m0, s53
	v_lshl_add_u64 v[238:239], s[50:51], 0, v[132:133]
	ds_read_b128 v[178:181], v143 offset:32768
	ds_read_b128 v[204:207], v143 offset:33792
	ds_read_b128 v[208:211], v143 offset:34816
	ds_read_b128 v[212:215], v143 offset:35840
	ds_read_b128 v[216:219], v143 offset:36864
	ds_read_b128 v[220:223], v143 offset:37888
	ds_read_b128 v[224:227], v143 offset:38912
	ds_read_b128 v[228:231], v143 offset:39936
	global_load_lds_dwordx4 v[238:239], off
	v_lshl_add_u64 v[238:239], s[50:51], 0, v[130:131]
	s_mov_b32 m0, s54
	s_nop 0
	global_load_lds_dwordx4 v[238:239], off
	s_waitcnt vmcnt(8)
	s_waitcnt lgkmcnt(0)
	s_barrier
	s_setprio 1
	s_waitcnt lgkmcnt(0)
	v_mfma_f32_16x16x32_bf16 v[124:127], v[144:147], v[178:181], v[124:127]
	v_mfma_f32_16x16x32_bf16 v[120:123], v[152:155], v[178:181], v[120:123]
	v_mfma_f32_16x16x32_bf16 v[108:111], v[144:147], v[208:211], v[108:111]
	v_mfma_f32_16x16x32_bf16 v[104:107], v[152:155], v[208:211], v[104:107]
	v_mfma_f32_16x16x32_bf16 v[92:95], v[144:147], v[216:219], v[92:95]
	v_mfma_f32_16x16x32_bf16 v[88:91], v[152:155], v[216:219], v[88:91]
	v_mfma_f32_16x16x32_bf16 v[76:79], v[144:147], v[224:227], v[76:79]
	v_mfma_f32_16x16x32_bf16 v[72:75], v[152:155], v[224:227], v[72:75]
	v_mfma_f32_16x16x32_bf16 v[124:127], v[148:151], v[204:207], v[124:127]
	v_mfma_f32_16x16x32_bf16 v[120:123], v[156:159], v[204:207], v[120:123]
	v_mfma_f32_16x16x32_bf16 v[108:111], v[148:151], v[212:215], v[108:111]
	v_mfma_f32_16x16x32_bf16 v[104:107], v[156:159], v[212:215], v[104:107]
	v_mfma_f32_16x16x32_bf16 v[92:95], v[148:151], v[220:223], v[92:95]
	v_mfma_f32_16x16x32_bf16 v[88:91], v[156:159], v[220:223], v[88:91]
	v_mfma_f32_16x16x32_bf16 v[76:79], v[148:151], v[228:231], v[76:79]
	v_mfma_f32_16x16x32_bf16 v[72:75], v[156:159], v[228:231], v[72:75]
	s_setprio 0
	s_setprio 1
	v_mfma_f32_16x16x32_bf16 v[116:119], v[162:165], v[178:181], v[116:119]
	v_mfma_f32_16x16x32_bf16 v[112:115], v[170:173], v[178:181], v[112:115]
	v_mfma_f32_16x16x32_bf16 v[100:103], v[162:165], v[208:211], v[100:103]
	v_mfma_f32_16x16x32_bf16 v[96:99], v[170:173], v[208:211], v[96:99]
	v_mfma_f32_16x16x32_bf16 v[84:87], v[162:165], v[216:219], v[84:87]
	v_mfma_f32_16x16x32_bf16 v[80:83], v[170:173], v[216:219], v[80:83]
	v_mfma_f32_16x16x32_bf16 v[68:71], v[162:165], v[224:227], v[68:71]
	v_mfma_f32_16x16x32_bf16 v[64:67], v[170:173], v[224:227], v[64:67]
	v_mfma_f32_16x16x32_bf16 v[116:119], v[166:169], v[204:207], v[116:119]
	v_mfma_f32_16x16x32_bf16 v[112:115], v[174:177], v[204:207], v[112:115]
	v_mfma_f32_16x16x32_bf16 v[100:103], v[166:169], v[212:215], v[100:103]
	v_mfma_f32_16x16x32_bf16 v[96:99], v[174:177], v[212:215], v[96:99]
	s_setprio 2
	s_barrier
; #define PG8_STAGE(bufoff, gbase, voff) do { _Pragma("unroll") for (int _i = 0; _i < 2; ++_i) \
;         __builtin_amdgcn_global_load_lds((const unsigned*)((const char*)(gbase) + (voff)[_i]), (PG8_LAS unsigned*)(lds + (bufoff) + ldsw + _i * 8192), 16, 0, 0); } while (0)
; #define PG8_LDA(dst, b, h) do { _Pragma("unroll") for (int m = 0; m < 4; ++m) _Pragma("unroll") for (int k = 0; k < 2; ++k) dst[m][k] = *(const PG8_LAS bf16x8*)(lds + PG8_SA(b, h) + aoff + m * 2048 + k * 1024); } while (0)
; #define PG8_MMA(ai, bj, At, Bt) do { __builtin_amdgcn_s_setprio(1); _Pragma("unroll") for (int m = 0; m < 4; ++m) _Pragma("unroll") for (int n = 0; n < 2; ++n) _Pragma("unroll") for (int k = 0; k < 2; ++k) \
;         acc[ai][bj][m][n] = __builtin_amdgcn_mfma_f32_16x16x32_bf16(Bt[n][k], At[m][k], acc[ai][bj][m][n], 0, 0, 0); __builtin_amdgcn_s_setprio(0); } while (0)
; #define PG8_WAIT_V(n) asm volatile("s_waitcnt vmcnt(" #n ")" ::: "memory")
; #define PG8_WAIT_L(n) asm volatile("s_waitcnt lgkmcnt(" #n ")" ::: "memory")
; #define PG8_BAR __builtin_amdgcn_s_barrier()
; #define PG8_SCHED __builtin_amdgcn_sched_barrier(0)
; template <class Epi, class Sched, bool ALIGN_EPI = false, bool SP2 = false>
; __device__ __forceinline__ void gemm_phase(PG8_LAS unsigned char* lds, const Gemm g, const Sched& S, const Epi& E, int wv) {
;     ...
;             PG8_LDA(At, 1, 1); PG8_STAGE(PG8_SB(1, 0), b3, voffB); PG8_STAGE(PG8_SB(1, 1), b3 + hstep, voffB); PG8_STAGE(PG8_SA(1, 0), a3, voffA);
;             PG8_WAIT_V(8); PG8_WAIT_L(0); PG8_BAR; PG8_MMA(1, 0, At, B0); PG8_MMA(1, 1, At, B1); PG8_BAR; PG8_SCHED;
;     ...
;         if constexpr (ALIGN_EPI) { if (wr == 0) PG8_BAR; }
	v_mfma_f32_16x16x32_bf16 v[84:87], v[166:169], v[220:223], v[84:87]
	v_mfma_f32_16x16x32_bf16 v[80:83], v[174:177], v[220:223], v[80:83]
	v_mfma_f32_16x16x32_bf16 v[68:71], v[166:169], v[228:231], v[68:71]
	v_mfma_f32_16x16x32_bf16 v[64:67], v[174:177], v[228:231], v[64:67]
	s_setprio 0
	s_add_i32 s21, s21, s30
	v_lshl_add_u64 v[138:139], v[138:139], 0, s[74:75]
	s_mov_b32 m0, s21
	ds_read_b128 v[178:181], v143 offset:49152
	ds_read_b128 v[204:207], v143 offset:50176
	ds_read_b128 v[208:211], v143 offset:51200
	ds_read_b128 v[212:215], v143 offset:52224
	ds_read_b128 v[216:219], v143 offset:53248
	ds_read_b128 v[220:223], v143 offset:54272
	ds_read_b128 v[224:227], v143 offset:55296
	ds_read_b128 v[228:231], v143 offset:56320
	global_load_lds_dwordx4 v[138:139], off
	s_add_i32 m0, s21, 0x2000
	s_add_u32 s48, s48, 0x40080
	v_lshl_add_u64 v[138:139], v[232:233], 0, s[74:75]
	s_addc_u32 s49, s49, 0
	s_add_i32 s21, s26, s30
	global_load_lds_dwordx4 v[138:139], off
	v_lshl_add_u64 v[138:139], s[48:49], 0, v[160:161]
	s_mov_b32 m0, s21
	s_nop 0
	global_load_lds_dwordx4 v[138:139], off
	v_lshl_add_u64 v[138:139], s[48:49], 0, v[128:129]
	s_add_i32 m0, s21, 0x2000
	s_nop 0
	global_load_lds_dwordx4 v[138:139], off
	v_lshl_add_u64 v[138:139], v[234:235], 0, s[74:75]
	s_mov_b32 m0, s60
	s_nop 0
	global_load_lds_dwordx4 v[138:139], off
	v_lshl_add_u64 v[138:139], v[236:237], 0, s[74:75]
	s_mov_b32 m0, s61
	s_nop 0
	global_load_lds_dwordx4 v[138:139], off
	s_waitcnt vmcnt(8)
	s_waitcnt lgkmcnt(0)
	s_barrier
	s_setprio 1
	s_waitcnt lgkmcnt(0)
	v_mfma_f32_16x16x32_bf16 v[60:63], v[144:147], v[178:181], v[60:63]
	v_mfma_f32_16x16x32_bf16 v[56:59], v[152:155], v[178:181], v[56:59]
	v_mfma_f32_16x16x32_bf16 v[44:47], v[144:147], v[208:211], v[44:47]
	v_mfma_f32_16x16x32_bf16 v[40:43], v[152:155], v[208:211], v[40:43]
	v_mfma_f32_16x16x32_bf16 v[28:31], v[144:147], v[216:219], v[28:31]
	v_mfma_f32_16x16x32_bf16 v[24:27], v[152:155], v[216:219], v[24:27]
	v_mfma_f32_16x16x32_bf16 v[12:15], v[144:147], v[224:227], v[12:15]
	v_mfma_f32_16x16x32_bf16 v[8:11], v[152:155], v[224:227], v[8:11]
	v_mfma_f32_16x16x32_bf16 v[60:63], v[148:151], v[204:207], v[60:63]
	v_mfma_f32_16x16x32_bf16 v[56:59], v[156:159], v[204:207], v[56:59]
	v_mfma_f32_16x16x32_bf16 v[44:47], v[148:151], v[212:215], v[44:47]
	v_mfma_f32_16x16x32_bf16 v[40:43], v[156:159], v[212:215], v[40:43]
	v_mfma_f32_16x16x32_bf16 v[28:31], v[148:151], v[220:223], v[28:31]
	v_mfma_f32_16x16x32_bf16 v[24:27], v[156:159], v[220:223], v[24:27]
	v_mfma_f32_16x16x32_bf16 v[12:15], v[148:151], v[228:231], v[12:15]
	v_mfma_f32_16x16x32_bf16 v[8:11], v[156:159], v[228:231], v[8:11]
	s_setprio 0
	s_setprio 1
	v_mfma_f32_16x16x32_bf16 v[52:55], v[162:165], v[178:181], v[52:55]
	v_mfma_f32_16x16x32_bf16 v[48:51], v[170:173], v[178:181], v[48:51]
	v_mfma_f32_16x16x32_bf16 v[36:39], v[162:165], v[208:211], v[36:39]
	v_mfma_f32_16x16x32_bf16 v[32:35], v[170:173], v[208:211], v[32:35]
	v_mfma_f32_16x16x32_bf16 v[20:23], v[162:165], v[216:219], v[20:23]
	v_mfma_f32_16x16x32_bf16 v[16:19], v[170:173], v[216:219], v[16:19]
	v_mfma_f32_16x16x32_bf16 v[4:7], v[162:165], v[224:227], v[4:7]
	v_mfma_f32_16x16x32_bf16 v[0:3], v[170:173], v[224:227], v[0:3]
	v_mfma_f32_16x16x32_bf16 v[52:55], v[166:169], v[204:207], v[52:55]
	v_mfma_f32_16x16x32_bf16 v[48:51], v[174:177], v[204:207], v[48:51]
	v_mfma_f32_16x16x32_bf16 v[36:39], v[166:169], v[212:215], v[36:39]
	v_mfma_f32_16x16x32_bf16 v[32:35], v[174:177], v[212:215], v[32:35]
	s_setprio 2
	s_barrier
	v_mfma_f32_16x16x32_bf16 v[20:23], v[166:169], v[220:223], v[20:23]
	v_mfma_f32_16x16x32_bf16 v[16:19], v[174:177], v[220:223], v[16:19]
	v_mfma_f32_16x16x32_bf16 v[4:7], v[166:169], v[228:231], v[4:7]
	v_mfma_f32_16x16x32_bf16 v[0:3], v[174:177], v[228:231], v[0:3]
	s_setprio 0
	s_add_i32 s67, s67, 2
	s_add_u32 s44, s44, 0x100
	s_addc_u32 s45, s45, 0
	s_add_u32 s65, s65, 0x100
	s_addc_u32 s66, s66, 0
	s_cmp_gt_u32 s67, 13
	s_cbranch_scc0 .LBB0_2108
	s_and_b64 vcc, exec, s[10:11]
	s_cbranch_vccz .LBB0_2111
	s_barrier

; #define PG8_STAGE(bufoff, gbase, voff) do { _Pragma("unroll") for (int _i = 0; _i < 2; ++_i) \
;         __builtin_amdgcn_global_load_lds((const unsigned*)((const char*)(gbase) + (voff)[_i]), (PG8_LAS unsigned*)(lds + (bufoff) + ldsw + _i * 8192), 16, 0, 0); } while (0)
; #define PG8_LDA(dst, b, h) do { _Pragma("unroll") for (int m = 0; m < 4; ++m) _Pragma("unroll") for (int k = 0; k < 2; ++k) dst[m][k] = *(const PG8_LAS bf16x8*)(lds + PG8_SA(b, h) + aoff + m * 2048 + k * 1024); } while (0)
; #define PG8_LDB(dst, b, h) do { _Pragma("unroll") for (int n = 0; n < 2; ++n) _Pragma("unroll") for (int k = 0; k < 2; ++k) dst[n][k] = *(const PG8_LAS bf16x8*)(lds + PG8_SB(b, h) + boff + n * 2048 + k * 1024); } while (0)
; #define PG8_MMA(ai, bj, At, Bt) do { __builtin_amdgcn_s_setprio(1); _Pragma("unroll") for (int m = 0; m < 4; ++m) _Pragma("unroll") for (int n = 0; n < 2; ++n) _Pragma("unroll") for (int k = 0; k < 2; ++k) \
;         acc[ai][bj][m][n] = __builtin_amdgcn_mfma_f32_16x16x32_bf16(Bt[n][k], At[m][k], acc[ai][bj][m][n], 0, 0, 0); __builtin_amdgcn_s_setprio(0); } while (0)
; #define PG8_WAIT_V(n) asm volatile("s_waitcnt vmcnt(" #n ")" ::: "memory")
; template <class Epi, class Sched, bool ALIGN_EPI = false, bool SP2 = false>
; __device__ __forceinline__ void gemm_phase(PG8_LAS unsigned char* lds, const Gemm g, const Sched& S, const Epi& E, int wv) {
;     ...
;         const char* nA = has_next ? (const char*)g.A + (size_t)nxt.pm * tstep : cA; const char* nB = has_next ? (const char*)g.Bt + (size_t)nxt.pn * tstep : cB;
;         for (int t = 0; t < nt; t += 2) {
;             const bool last = (t == nt - 2);
;             const char* a1 = cA + (size_t)(t + 1) * kstep;
;             const char* a2 = last ? nA : cA + (size_t)(t + 2) * kstep; const char* b2 = last ? nB : cB + (size_t)(t + 2) * kstep;
;             const char* a3 = a2 + kstep; const char* b3 = b2 + kstep;
;             if (last && has_next) S.a_ready(nxt);
;             if constexpr (SP2) {
;             PG8_LDB(B0, 0, 0); PG8_LDB(B1, 0, 1); PG8_SCHED; PG8_LDA(At, 0, 0); PG8_STAGE(PG8_SA(1, 1), a1 + hstep, voffA);
;             PG8_WAIT_V(8); PG8_WAIT_L(0); PG8_BAR; PG8_MMA(0, 0, At, B0); PG8_MMA(0, 1, At, B1); PG8_BAR; PG8_SCHED;
;             PG8_LDA(At, 0, 1); PG8_STAGE(PG8_SB(0, 0), b2, voffB); PG8_STAGE(PG8_SB(0, 1), b2 + hstep, voffB); PG8_STAGE(PG8_SA(0, 0), a2, voffA);
.LBB0_2180:
	s_add_u32 s42, s6, 0x100
	s_addc_u32 s43, s7, 0
	s_add_i32 s21, 0, 0x10000
	s_cmp_eq_u32 s65, 40
	s_cselect_b32 s49, s35, s43
	s_cselect_b32 s48, s34, s42
	s_cselect_b32 s45, s41, s25
	s_cselect_b32 s44, s40, s24
	s_add_i32 s26, 0, 0x14000
	v_add_u32_e32 v140, s21, v168
	v_add_u32_e32 v170, s26, v168
	ds_read_b128 v[128:131], v140
	ds_read_b128 v[132:135], v140 offset:1024
	ds_read_b128 v[136:139], v140 offset:2048
	ds_read_b128 v[140:143], v140 offset:3072
	ds_read_b128 v[144:147], v170
	ds_read_b128 v[148:151], v170 offset:1024
	ds_read_b128 v[164:167], v170 offset:2048
	ds_read_b128 v[170:173], v170 offset:3072
	v_lshl_add_u64 v[228:229], s[6:7], 0, v[158:159]
	s_add_i32 m0, s31, 0xc000
	ds_read_b128 v[174:177], v169
	ds_read_b128 v[178:181], v169 offset:1024
	ds_read_b128 v[204:207], v169 offset:2048
	ds_read_b128 v[208:211], v169 offset:3072
	ds_read_b128 v[212:215], v169 offset:4096
	ds_read_b128 v[216:219], v169 offset:5120
	ds_read_b128 v[220:223], v169 offset:6144
	ds_read_b128 v[224:227], v169 offset:7168
	global_load_lds_dwordx4 v[228:229], off
	v_lshl_add_u64 v[228:229], s[6:7], 0, v[162:163]
	s_add_i32 m0, s31, 0xe000
	s_nop 0
	global_load_lds_dwordx4 v[228:229], off
	s_waitcnt vmcnt(8)
	s_waitcnt lgkmcnt(0)
	s_barrier
	s_setprio 1
	s_waitcnt lgkmcnt(0)
	v_mfma_f32_16x16x32_bf16 v[124:127], v[128:131], v[174:177], v[124:127]
	v_mfma_f32_16x16x32_bf16 v[120:123], v[136:139], v[174:177], v[120:123]
	v_mfma_f32_16x16x32_bf16 v[108:111], v[128:131], v[204:207], v[108:111]
	v_mfma_f32_16x16x32_bf16 v[104:107], v[136:139], v[204:207], v[104:107]
	v_mfma_f32_16x16x32_bf16 v[92:95], v[128:131], v[212:215], v[92:95]
	v_mfma_f32_16x16x32_bf16 v[88:91], v[136:139], v[212:215], v[88:91]
	v_mfma_f32_16x16x32_bf16 v[76:79], v[128:131], v[220:223], v[76:79]
	v_mfma_f32_16x16x32_bf16 v[72:75], v[136:139], v[220:223], v[72:75]
	v_mfma_f32_16x16x32_bf16 v[124:127], v[132:135], v[178:181], v[124:127]
	v_mfma_f32_16x16x32_bf16 v[120:123], v[140:143], v[178:181], v[120:123]
	v_mfma_f32_16x16x32_bf16 v[108:111], v[132:135], v[208:211], v[108:111]
	v_mfma_f32_16x16x32_bf16 v[104:107], v[140:143], v[208:211], v[104:107]
	v_mfma_f32_16x16x32_bf16 v[92:95], v[132:135], v[216:219], v[92:95]
	v_mfma_f32_16x16x32_bf16 v[88:91], v[140:143], v[216:219], v[88:91]
	v_mfma_f32_16x16x32_bf16 v[76:79], v[132:135], v[224:227], v[76:79]
	v_mfma_f32_16x16x32_bf16 v[72:75], v[140:143], v[224:227], v[72:75]
	s_setprio 0
	s_setprio 1
	v_mfma_f32_16x16x32_bf16 v[116:119], v[144:147], v[174:177], v[116:119]
	v_mfma_f32_16x16x32_bf16 v[112:115], v[164:167], v[174:177], v[112:115]
	v_mfma_f32_16x16x32_bf16 v[100:103], v[144:147], v[204:207], v[100:103]
	v_mfma_f32_16x16x32_bf16 v[96:99], v[164:167], v[204:207], v[96:99]
	v_mfma_f32_16x16x32_bf16 v[84:87], v[144:147], v[212:215], v[84:87]
	v_mfma_f32_16x16x32_bf16 v[80:83], v[164:167], v[212:215], v[80:83]
	v_mfma_f32_16x16x32_bf16 v[68:71], v[144:147], v[220:223], v[68:71]
	v_mfma_f32_16x16x32_bf16 v[64:67], v[164:167], v[220:223], v[64:67]
	v_mfma_f32_16x16x32_bf16 v[116:119], v[148:151], v[178:181], v[116:119]
	v_mfma_f32_16x16x32_bf16 v[112:115], v[170:173], v[178:181], v[112:115]
	v_mfma_f32_16x16x32_bf16 v[100:103], v[148:151], v[208:211], v[100:103]
	v_mfma_f32_16x16x32_bf16 v[96:99], v[170:173], v[208:211], v[96:99]
	s_setprio 2
	s_barrier
	v_mfma_f32_16x16x32_bf16 v[84:87], v[148:151], v[216:219], v[84:87]
	v_mfma_f32_16x16x32_bf16 v[80:83], v[170:173], v[216:219], v[80:83]
	v_mfma_f32_16x16x32_bf16 v[68:71], v[148:151], v[224:227], v[68:71]
	v_mfma_f32_16x16x32_bf16 v[64:67], v[170:173], v[224:227], v[64:67]
	s_setprio 0
	s_add_i32 s6, s21, s30
	v_lshl_add_u64 v[228:229], s[44:45], 0, v[160:161]
	s_mov_b32 m0, s6
	ds_read_b128 v[174:177], v169 offset:16384
	ds_read_b128 v[178:181], v169 offset:17408
	ds_read_b128 v[204:207], v169 offset:18432
	ds_read_b128 v[208:211], v169 offset:19456
	ds_read_b128 v[212:215], v169 offset:20480
	ds_read_b128 v[216:219], v169 offset:21504
	ds_read_b128 v[220:223], v169 offset:22528
	ds_read_b128 v[224:227], v169 offset:23552
	global_load_lds_dwordx4 v[228:229], off
	s_add_i32 m0, s6, 0x2000
	s_add_u32 s6, s44, 0xb0000
	v_lshl_add_u64 v[230:231], s[44:45], 0, v[152:153]
	s_addc_u32 s7, s45, 0
	s_add_i32 s21, s26, s30
	global_load_lds_dwordx4 v[230:231], off
	v_lshl_add_u64 v[232:233], s[6:7], 0, v[160:161]
	s_mov_b32 m0, s21
	v_lshl_add_u64 v[234:235], s[48:49], 0, v[154:155]
	global_load_lds_dwordx4 v[232:233], off
	v_lshl_add_u64 v[232:233], s[6:7], 0, v[152:153]
	s_add_i32 m0, s21, 0x2000
	s_nop 0
	global_load_lds_dwordx4 v[232:233], off
	v_lshl_add_u64 v[232:233], s[48:49], 0, v[156:157]
	s_mov_b32 m0, s31
	s_nop 0
	global_load_lds_dwordx4 v[232:233], off
	s_mov_b32 m0, s50
	s_nop 0
	global_load_lds_dwordx4 v[234:235], off
	s_waitcnt vmcnt(8)
	s_waitcnt lgkmcnt(0)
	s_barrier
; #define PG8_STAGE(bufoff, gbase, voff) do { _Pragma("unroll") for (int _i = 0; _i < 2; ++_i) \
;         __builtin_amdgcn_global_load_lds((const unsigned*)((const char*)(gbase) + (voff)[_i]), (PG8_LAS unsigned*)(lds + (bufoff) + ldsw + _i * 8192), 16, 0, 0); } while (0)
; #define PG8_LDA(dst, b, h) do { _Pragma("unroll") for (int m = 0; m < 4; ++m) _Pragma("unroll") for (int k = 0; k < 2; ++k) dst[m][k] = *(const PG8_LAS bf16x8*)(lds + PG8_SA(b, h) + aoff + m * 2048 + k * 1024); } while (0)
; #define PG8_LDB(dst, b, h) do { _Pragma("unroll") for (int n = 0; n < 2; ++n) _Pragma("unroll") for (int k = 0; k < 2; ++k) dst[n][k] = *(const PG8_LAS bf16x8*)(lds + PG8_SB(b, h) + boff + n * 2048 + k * 1024); } while (0)
; #define PG8_MMA(ai, bj, At, Bt) do { __builtin_amdgcn_s_setprio(1); _Pragma("unroll") for (int m = 0; m < 4; ++m) _Pragma("unroll") for (int n = 0; n < 2; ++n) _Pragma("unroll") for (int k = 0; k < 2; ++k) \
;         acc[ai][bj][m][n] = __builtin_amdgcn_mfma_f32_16x16x32_bf16(Bt[n][k], At[m][k], acc[ai][bj][m][n], 0, 0, 0); __builtin_amdgcn_s_setprio(0); } while (0)
; #define PG8_WAIT_V(n) asm volatile("s_waitcnt vmcnt(" #n ")" ::: "memory")
; #define PG8_WAIT_L(n) asm volatile("s_waitcnt lgkmcnt(" #n ")" ::: "memory")
; #define PG8_BAR __builtin_amdgcn_s_barrier()
; #define PG8_SCHED __builtin_amdgcn_sched_barrier(0)
; template <class Epi, class Sched, bool ALIGN_EPI = false, bool SP2 = false>
; __device__ __forceinline__ void gemm_phase(PG8_LAS unsigned char* lds, const Gemm g, const Sched& S, const Epi& E, int wv) {
;     ...
;             PG8_WAIT_V(8); PG8_WAIT_L(0); PG8_BAR; PG8_MMA(1, 0, At, B0); PG8_MMA(1, 1, At, B1); PG8_BAR; PG8_SCHED;
;             PG8_LDB(B0, 1, 0); PG8_LDB(B1, 1, 1); PG8_SCHED; PG8_LDA(At, 1, 0); PG8_STAGE(PG8_SA(0, 1), a2 + hstep, voffA);
;             PG8_WAIT_V(8); PG8_WAIT_L(0); PG8_BAR; PG8_MMA(0, 0, At, B0); PG8_MMA(0, 1, At, B1); PG8_BAR; PG8_SCHED;
	s_setprio 1
	s_waitcnt lgkmcnt(0)
	v_mfma_f32_16x16x32_bf16 v[60:63], v[128:131], v[174:177], v[60:63]
	v_mfma_f32_16x16x32_bf16 v[56:59], v[136:139], v[174:177], v[56:59]
	v_mfma_f32_16x16x32_bf16 v[44:47], v[128:131], v[204:207], v[44:47]
	v_mfma_f32_16x16x32_bf16 v[40:43], v[136:139], v[204:207], v[40:43]
	v_mfma_f32_16x16x32_bf16 v[28:31], v[128:131], v[212:215], v[28:31]
	v_mfma_f32_16x16x32_bf16 v[24:27], v[136:139], v[212:215], v[24:27]
	v_mfma_f32_16x16x32_bf16 v[12:15], v[128:131], v[220:223], v[12:15]
	v_mfma_f32_16x16x32_bf16 v[8:11], v[136:139], v[220:223], v[8:11]
	v_mfma_f32_16x16x32_bf16 v[60:63], v[132:135], v[178:181], v[60:63]
	v_mfma_f32_16x16x32_bf16 v[56:59], v[140:143], v[178:181], v[56:59]
	v_mfma_f32_16x16x32_bf16 v[44:47], v[132:135], v[208:211], v[44:47]
	v_mfma_f32_16x16x32_bf16 v[40:43], v[140:143], v[208:211], v[40:43]
	v_mfma_f32_16x16x32_bf16 v[28:31], v[132:135], v[216:219], v[28:31]
	v_mfma_f32_16x16x32_bf16 v[24:27], v[140:143], v[216:219], v[24:27]
	v_mfma_f32_16x16x32_bf16 v[12:15], v[132:135], v[224:227], v[12:15]
	v_mfma_f32_16x16x32_bf16 v[8:11], v[140:143], v[224:227], v[8:11]
	s_setprio 0
	s_setprio 1
	v_mfma_f32_16x16x32_bf16 v[52:55], v[144:147], v[174:177], v[52:55]
	v_mfma_f32_16x16x32_bf16 v[48:51], v[164:167], v[174:177], v[48:51]
	v_mfma_f32_16x16x32_bf16 v[36:39], v[144:147], v[204:207], v[36:39]
	v_mfma_f32_16x16x32_bf16 v[32:35], v[164:167], v[204:207], v[32:35]
	v_mfma_f32_16x16x32_bf16 v[20:23], v[144:147], v[212:215], v[20:23]
	v_mfma_f32_16x16x32_bf16 v[16:19], v[164:167], v[212:215], v[16:19]
	v_mfma_f32_16x16x32_bf16 v[4:7], v[144:147], v[220:223], v[4:7]
	v_mfma_f32_16x16x32_bf16 v[0:3], v[164:167], v[220:223], v[0:3]
	v_mfma_f32_16x16x32_bf16 v[52:55], v[148:151], v[178:181], v[52:55]
	v_mfma_f32_16x16x32_bf16 v[48:51], v[170:173], v[178:181], v[48:51]
	v_mfma_f32_16x16x32_bf16 v[36:39], v[148:151], v[208:211], v[36:39]
	v_mfma_f32_16x16x32_bf16 v[32:35], v[170:173], v[208:211], v[32:35]
	s_setprio 2
	s_barrier
	v_mfma_f32_16x16x32_bf16 v[20:23], v[148:151], v[216:219], v[20:23]
	v_mfma_f32_16x16x32_bf16 v[16:19], v[170:173], v[216:219], v[16:19]
	v_mfma_f32_16x16x32_bf16 v[4:7], v[148:151], v[224:227], v[4:7]
	v_mfma_f32_16x16x32_bf16 v[0:3], v[170:173], v[224:227], v[0:3]
	s_setprio 0
	s_add_i32 s21, 0, 0x18000
	s_add_i32 s26, 0, 0x1c000
	v_add_u32_e32 v140, s21, v168
	v_add_u32_e32 v170, s26, v168
	ds_read_b128 v[128:131], v140
	ds_read_b128 v[132:135], v140 offset:1024
	ds_read_b128 v[136:139], v140 offset:2048
	ds_read_b128 v[140:143], v140 offset:3072
	ds_read_b128 v[144:147], v170
	ds_read_b128 v[148:151], v170 offset:1024
	ds_read_b128 v[164:167], v170 offset:2048
	ds_read_b128 v[170:173], v170 offset:3072
	s_add_u32 s6, s48, 0xb0000
	s_addc_u32 s7, s49, 0
	s_mov_b32 m0, s51
	v_lshl_add_u64 v[236:237], s[6:7], 0, v[156:157]
	ds_read_b128 v[174:177], v169 offset:32768
	ds_read_b128 v[178:181], v169 offset:33792
	ds_read_b128 v[204:207], v169 offset:34816
	ds_read_b128 v[208:211], v169 offset:35840
	ds_read_b128 v[212:215], v169 offset:36864
	ds_read_b128 v[216:219], v169 offset:37888
	ds_read_b128 v[220:223], v169 offset:38912
	ds_read_b128 v[224:227], v169 offset:39936
	global_load_lds_dwordx4 v[236:237], off
	v_lshl_add_u64 v[236:237], s[6:7], 0, v[154:155]
	s_mov_b32 m0, s52
	s_nop 0
	global_load_lds_dwordx4 v[236:237], off
	s_waitcnt vmcnt(8)
	s_waitcnt lgkmcnt(0)
	s_barrier
	s_setprio 1
	s_waitcnt lgkmcnt(0)
	v_mfma_f32_16x16x32_bf16 v[124:127], v[128:131], v[174:177], v[124:127]
	v_mfma_f32_16x16x32_bf16 v[120:123], v[136:139], v[174:177], v[120:123]
	v_mfma_f32_16x16x32_bf16 v[108:111], v[128:131], v[204:207], v[108:111]
	v_mfma_f32_16x16x32_bf16 v[104:107], v[136:139], v[204:207], v[104:107]
	v_mfma_f32_16x16x32_bf16 v[92:95], v[128:131], v[212:215], v[92:95]
	v_mfma_f32_16x16x32_bf16 v[88:91], v[136:139], v[212:215], v[88:91]
	v_mfma_f32_16x16x32_bf16 v[76:79], v[128:131], v[220:223], v[76:79]
	v_mfma_f32_16x16x32_bf16 v[72:75], v[136:139], v[220:223], v[72:75]
	v_mfma_f32_16x16x32_bf16 v[124:127], v[132:135], v[178:181], v[124:127]
	v_mfma_f32_16x16x32_bf16 v[120:123], v[140:143], v[178:181], v[120:123]
	v_mfma_f32_16x16x32_bf16 v[108:111], v[132:135], v[208:211], v[108:111]
	v_mfma_f32_16x16x32_bf16 v[104:107], v[140:143], v[208:211], v[104:107]
	v_mfma_f32_16x16x32_bf16 v[92:95], v[132:135], v[216:219], v[92:95]
	v_mfma_f32_16x16x32_bf16 v[88:91], v[140:143], v[216:219], v[88:91]
	v_mfma_f32_16x16x32_bf16 v[76:79], v[132:135], v[224:227], v[76:79]
	v_mfma_f32_16x16x32_bf16 v[72:75], v[140:143], v[224:227], v[72:75]
	s_setprio 0
	s_setprio 1
	v_mfma_f32_16x16x32_bf16 v[116:119], v[144:147], v[174:177], v[116:119]
	v_mfma_f32_16x16x32_bf16 v[112:115], v[164:167], v[174:177], v[112:115]
	v_mfma_f32_16x16x32_bf16 v[100:103], v[144:147], v[204:207], v[100:103]
	v_mfma_f32_16x16x32_bf16 v[96:99], v[164:167], v[204:207], v[96:99]
	v_mfma_f32_16x16x32_bf16 v[84:87], v[144:147], v[212:215], v[84:87]
	v_mfma_f32_16x16x32_bf16 v[80:83], v[164:167], v[212:215], v[80:83]
	v_mfma_f32_16x16x32_bf16 v[68:71], v[144:147], v[220:223], v[68:71]
	v_mfma_f32_16x16x32_bf16 v[64:67], v[164:167], v[220:223], v[64:67]
	v_mfma_f32_16x16x32_bf16 v[116:119], v[148:151], v[178:181], v[116:119]
	v_mfma_f32_16x16x32_bf16 v[112:115], v[170:173], v[178:181], v[112:115]
	v_mfma_f32_16x16x32_bf16 v[100:103], v[148:151], v[208:211], v[100:103]
	v_mfma_f32_16x16x32_bf16 v[96:99], v[170:173], v[208:211], v[96:99]
	s_setprio 2
	s_barrier
; #define PG8_STAGE(bufoff, gbase, voff) do { _Pragma("unroll") for (int _i = 0; _i < 2; ++_i) \
;         __builtin_amdgcn_global_load_lds((const unsigned*)((const char*)(gbase) + (voff)[_i]), (PG8_LAS unsigned*)(lds + (bufoff) + ldsw + _i * 8192), 16, 0, 0); } while (0)
; #define PG8_LDA(dst, b, h) do { _Pragma("unroll") for (int m = 0; m < 4; ++m) _Pragma("unroll") for (int k = 0; k < 2; ++k) dst[m][k] = *(const PG8_LAS bf16x8*)(lds + PG8_SA(b, h) + aoff + m * 2048 + k * 1024); } while (0)
; #define PG8_MMA(ai, bj, At, Bt) do { __builtin_amdgcn_s_setprio(1); _Pragma("unroll") for (int m = 0; m < 4; ++m) _Pragma("unroll") for (int n = 0; n < 2; ++n) _Pragma("unroll") for (int k = 0; k < 2; ++k) \
;         acc[ai][bj][m][n] = __builtin_amdgcn_mfma_f32_16x16x32_bf16(Bt[n][k], At[m][k], acc[ai][bj][m][n], 0, 0, 0); __builtin_amdgcn_s_setprio(0); } while (0)
; #define PG8_WAIT_V(n) asm volatile("s_waitcnt vmcnt(" #n ")" ::: "memory")
; #define PG8_WAIT_L(n) asm volatile("s_waitcnt lgkmcnt(" #n ")" ::: "memory")
; #define PG8_BAR __builtin_amdgcn_s_barrier()
; #define PG8_SCHED __builtin_amdgcn_sched_barrier(0)
; template <class Epi, class Sched, bool ALIGN_EPI = false, bool SP2 = false>
; __device__ __forceinline__ void gemm_phase(PG8_LAS unsigned char* lds, const Gemm g, const Sched& S, const Epi& E, int wv) {
;     ...
;             PG8_LDA(At, 1, 1); PG8_STAGE(PG8_SB(1, 0), b3, voffB); PG8_STAGE(PG8_SB(1, 1), b3 + hstep, voffB); PG8_STAGE(PG8_SA(1, 0), a3, voffA);
;             PG8_WAIT_V(8); PG8_WAIT_L(0); PG8_BAR; PG8_MMA(1, 0, At, B0); PG8_MMA(1, 1, At, B1); PG8_BAR; PG8_SCHED;
;     ...
;         if constexpr (ALIGN_EPI) { if (wr == 0) PG8_BAR; }
	v_mfma_f32_16x16x32_bf16 v[84:87], v[148:151], v[216:219], v[84:87]
	v_mfma_f32_16x16x32_bf16 v[80:83], v[170:173], v[216:219], v[80:83]
	v_mfma_f32_16x16x32_bf16 v[68:71], v[148:151], v[224:227], v[68:71]
	v_mfma_f32_16x16x32_bf16 v[64:67], v[170:173], v[224:227], v[64:67]
	s_setprio 0
	s_add_i32 s6, s21, s30
	v_lshl_add_u64 v[228:229], v[228:229], 0, s[74:75]
	s_mov_b32 m0, s6
	ds_read_b128 v[174:177], v169 offset:49152
	ds_read_b128 v[178:181], v169 offset:50176
	ds_read_b128 v[204:207], v169 offset:51200
	ds_read_b128 v[208:211], v169 offset:52224
	ds_read_b128 v[212:215], v169 offset:53248
	ds_read_b128 v[216:219], v169 offset:54272
	ds_read_b128 v[220:223], v169 offset:55296
	ds_read_b128 v[224:227], v169 offset:56320
	global_load_lds_dwordx4 v[228:229], off
	s_add_i32 m0, s6, 0x2000
	s_add_u32 s6, s44, 0xb0080
	v_lshl_add_u64 v[228:229], v[230:231], 0, s[74:75]
	s_addc_u32 s7, s45, 0
	s_add_i32 s21, s26, s30
	global_load_lds_dwordx4 v[228:229], off
	v_lshl_add_u64 v[228:229], s[6:7], 0, v[160:161]
	s_mov_b32 m0, s21
	s_nop 0
	global_load_lds_dwordx4 v[228:229], off
	v_lshl_add_u64 v[228:229], s[6:7], 0, v[152:153]
	s_add_i32 m0, s21, 0x2000
	s_nop 0
	global_load_lds_dwordx4 v[228:229], off
	v_lshl_add_u64 v[228:229], v[232:233], 0, s[74:75]
	s_mov_b32 m0, s56
	s_nop 0
	global_load_lds_dwordx4 v[228:229], off
	v_lshl_add_u64 v[228:229], v[234:235], 0, s[74:75]
	s_mov_b32 m0, s57
	s_nop 0
	global_load_lds_dwordx4 v[228:229], off
	s_waitcnt vmcnt(8)
	s_waitcnt lgkmcnt(0)
	s_barrier
	s_setprio 1
	s_waitcnt lgkmcnt(0)
	v_mfma_f32_16x16x32_bf16 v[60:63], v[128:131], v[174:177], v[60:63]
	v_mfma_f32_16x16x32_bf16 v[56:59], v[136:139], v[174:177], v[56:59]
	v_mfma_f32_16x16x32_bf16 v[44:47], v[128:131], v[204:207], v[44:47]
	v_mfma_f32_16x16x32_bf16 v[40:43], v[136:139], v[204:207], v[40:43]
	v_mfma_f32_16x16x32_bf16 v[28:31], v[128:131], v[212:215], v[28:31]
	v_mfma_f32_16x16x32_bf16 v[24:27], v[136:139], v[212:215], v[24:27]
	v_mfma_f32_16x16x32_bf16 v[12:15], v[128:131], v[220:223], v[12:15]
	v_mfma_f32_16x16x32_bf16 v[8:11], v[136:139], v[220:223], v[8:11]
	v_mfma_f32_16x16x32_bf16 v[60:63], v[132:135], v[178:181], v[60:63]
	v_mfma_f32_16x16x32_bf16 v[56:59], v[140:143], v[178:181], v[56:59]
	v_mfma_f32_16x16x32_bf16 v[44:47], v[132:135], v[208:211], v[44:47]
	v_mfma_f32_16x16x32_bf16 v[40:43], v[140:143], v[208:211], v[40:43]
	v_mfma_f32_16x16x32_bf16 v[28:31], v[132:135], v[216:219], v[28:31]
	v_mfma_f32_16x16x32_bf16 v[24:27], v[140:143], v[216:219], v[24:27]
	v_mfma_f32_16x16x32_bf16 v[12:15], v[132:135], v[224:227], v[12:15]
	v_mfma_f32_16x16x32_bf16 v[8:11], v[140:143], v[224:227], v[8:11]
	s_setprio 0
	s_setprio 1
	v_mfma_f32_16x16x32_bf16 v[52:55], v[144:147], v[174:177], v[52:55]
	v_mfma_f32_16x16x32_bf16 v[48:51], v[164:167], v[174:177], v[48:51]
	v_mfma_f32_16x16x32_bf16 v[36:39], v[144:147], v[204:207], v[36:39]
	v_mfma_f32_16x16x32_bf16 v[32:35], v[164:167], v[204:207], v[32:35]
	v_mfma_f32_16x16x32_bf16 v[20:23], v[144:147], v[212:215], v[20:23]
	v_mfma_f32_16x16x32_bf16 v[16:19], v[164:167], v[212:215], v[16:19]
	v_mfma_f32_16x16x32_bf16 v[4:7], v[144:147], v[220:223], v[4:7]
	v_mfma_f32_16x16x32_bf16 v[0:3], v[164:167], v[220:223], v[0:3]
	v_mfma_f32_16x16x32_bf16 v[52:55], v[148:151], v[178:181], v[52:55]
	v_mfma_f32_16x16x32_bf16 v[48:51], v[170:173], v[178:181], v[48:51]
	v_mfma_f32_16x16x32_bf16 v[36:39], v[148:151], v[208:211], v[36:39]
	v_mfma_f32_16x16x32_bf16 v[32:35], v[170:173], v[208:211], v[32:35]
	s_setprio 2
	s_barrier
	v_mfma_f32_16x16x32_bf16 v[20:23], v[148:151], v[216:219], v[20:23]
	v_mfma_f32_16x16x32_bf16 v[16:19], v[170:173], v[216:219], v[16:19]
	v_mfma_f32_16x16x32_bf16 v[4:7], v[148:151], v[224:227], v[4:7]
	v_mfma_f32_16x16x32_bf16 v[0:3], v[170:173], v[224:227], v[0:3]
	s_setprio 0
	s_add_i32 s65, s65, 2
	s_add_u32 s24, s24, 0x100
	s_addc_u32 s25, s25, 0
	s_cmp_gt_u32 s65, 41
	s_mov_b64 s[6:7], s[42:43]
	s_cbranch_scc0 .LBB0_2180
	s_and_b64 vcc, exec, s[18:19]
	s_cbranch_vccz .LBB0_2183
	s_barrier

; #define PG8_STAGE(bufoff, gbase, voff) do { _Pragma("unroll") for (int _i = 0; _i < 2; ++_i) \
;         __builtin_amdgcn_global_load_lds((const unsigned*)((const char*)(gbase) + (voff)[_i]), (PG8_LAS unsigned*)(lds + (bufoff) + ldsw + _i * 8192), 16, 0, 0); } while (0)
; #define PG8_LDA(dst, b, h) do { _Pragma("unroll") for (int m = 0; m < 4; ++m) _Pragma("unroll") for (int k = 0; k < 2; ++k) dst[m][k] = *(const PG8_LAS bf16x8*)(lds + PG8_SA(b, h) + aoff + m * 2048 + k * 1024); } while (0)
; #define PG8_LDB(dst, b, h) do { _Pragma("unroll") for (int n = 0; n < 2; ++n) _Pragma("unroll") for (int k = 0; k < 2; ++k) dst[n][k] = *(const PG8_LAS bf16x8*)(lds + PG8_SB(b, h) + boff + n * 2048 + k * 1024); } while (0)
; #define PG8_MMA(ai, bj, At, Bt) do { __builtin_amdgcn_s_setprio(1); _Pragma("unroll") for (int m = 0; m < 4; ++m) _Pragma("unroll") for (int n = 0; n < 2; ++n) _Pragma("unroll") for (int k = 0; k < 2; ++k) \
;         acc[ai][bj][m][n] = __builtin_amdgcn_mfma_f32_16x16x32_bf16(Bt[n][k], At[m][k], acc[ai][bj][m][n], 0, 0, 0); __builtin_amdgcn_s_setprio(0); } while (0)
; #define PG8_WAIT_V(n) asm volatile("s_waitcnt vmcnt(" #n ")" ::: "memory")
; template <class Epi, class Sched, bool ALIGN_EPI = false, bool SP2 = false>
; __device__ __forceinline__ void gemm_phase(PG8_LAS unsigned char* lds, const Gemm g, const Sched& S, const Epi& E, int wv) {
;     ...
;         const char* nA = has_next ? (const char*)g.A + (size_t)nxt.pm * tstep : cA; const char* nB = has_next ? (const char*)g.Bt + (size_t)nxt.pn * tstep : cB;
;         for (int t = 0; t < nt; t += 2) {
;             const bool last = (t == nt - 2);
;             const char* a1 = cA + (size_t)(t + 1) * kstep;
;             const char* a2 = last ? nA : cA + (size_t)(t + 2) * kstep; const char* b2 = last ? nB : cB + (size_t)(t + 2) * kstep;
;             const char* a3 = a2 + kstep; const char* b3 = b2 + kstep;
;             if (last && has_next) S.a_ready(nxt);
;             if constexpr (SP2) {
;             PG8_LDB(B0, 0, 0); PG8_LDB(B1, 0, 1); PG8_SCHED; PG8_LDA(At, 0, 0); PG8_STAGE(PG8_SA(1, 1), a1 + hstep, voffA);
;             PG8_WAIT_V(8); PG8_WAIT_L(0); PG8_BAR; PG8_MMA(0, 0, At, B0); PG8_MMA(0, 1, At, B1); PG8_BAR; PG8_SCHED;
;             PG8_LDA(At, 0, 1); PG8_STAGE(PG8_SB(0, 0), b2, voffB); PG8_STAGE(PG8_SB(0, 1), b2 + hstep, voffB); PG8_STAGE(PG8_SA(0, 0), a2, voffA);
.LBB0_2213:
	s_add_u32 s21, s44, s56
	s_addc_u32 s26, s45, 0
	s_add_u32 s28, s21, 0x100
	s_addc_u32 s36, s26, 0
	s_and_b64 s[60:61], s[52:53], exec
	s_cselect_b32 s61, s13, s36
	s_cselect_b32 s60, s83, s28
	s_add_u32 s28, s34, s56
	s_addc_u32 s36, s35, 0
	s_add_u32 s28, s28, 0x100
	s_addc_u32 s36, s36, 0
	s_add_i32 s58, 0, 0x10000
	s_and_b64 s[52:53], s[52:53], exec
	s_cselect_b32 s63, s19, s36
	s_cselect_b32 s62, s91, s28
	s_add_i32 s53, 0, 0x14000
	s_add_u32 vcc_lo, s21, 0x10080
	s_addc_u32 vcc_hi, s26, 0
	s_add_i32 s28, s58, s29
	s_add_i32 m0, s80, 0xc000
	s_add_i32 s30, s80, 0xe000
	s_add_i32 s55, s28, 0x2000
	s_add_u32 s64, s62, 0x10000
	v_add_u32_e32 v148, s58, v134
	v_add_u32_e32 v166, s53, v134
	s_addc_u32 s65, s63, 0
	s_add_i32 s36, s53, s29
	ds_read_b128 v[136:139], v148
	ds_read_b128 v[140:143], v148 offset:1024
	ds_read_b128 v[144:147], v148 offset:2048
	ds_read_b128 v[148:151], v148 offset:3072
	ds_read_b128 v[152:155], v166
	ds_read_b128 v[156:159], v166 offset:1024
	ds_read_b128 v[162:165], v166 offset:2048
	ds_read_b128 v[166:169], v166 offset:3072
	s_add_i32 s21, s36, 0x2000
	s_add_i32 s92, 0, 0x18000
	s_add_i32 s94, 0, 0x1c000
	s_add_u32 s56, s60, 0x10000
	s_addc_u32 s57, s61, 0
	s_add_i32 s93, s92, s29
	s_add_i32 s88, s93, 0x2000
	s_add_u32 s52, s62, 0x10080
	s_addc_u32 s53, s63, 0
	s_add_i32 s58, s94, s29
	s_add_i32 s26, s58, 0x2000
	v_lshl_add_u64 v[224:225], vcc, 0, v[132:133]
	ds_read_b128 v[170:173], v135
	ds_read_b128 v[174:177], v135 offset:1024
	ds_read_b128 v[178:181], v135 offset:2048
	ds_read_b128 v[204:207], v135 offset:3072
	ds_read_b128 v[208:211], v135 offset:4096
	ds_read_b128 v[212:215], v135 offset:5120
	ds_read_b128 v[216:219], v135 offset:6144
	ds_read_b128 v[220:223], v135 offset:7168
	global_load_lds_dwordx4 v[224:225], off
	v_lshl_add_u64 v[224:225], vcc, 0, v[130:131]
	s_mov_b32 m0, s30
	s_nop 0
	global_load_lds_dwordx4 v[224:225], off
	s_waitcnt vmcnt(8)
	s_waitcnt lgkmcnt(0)
	s_barrier
	s_setprio 1
	s_waitcnt lgkmcnt(0)
	v_mfma_f32_16x16x32_bf16 v[124:127], v[136:139], v[170:173], v[124:127]
	v_mfma_f32_16x16x32_bf16 v[120:123], v[144:147], v[170:173], v[120:123]
	v_mfma_f32_16x16x32_bf16 v[116:119], v[136:139], v[178:181], v[116:119]
	v_mfma_f32_16x16x32_bf16 v[112:115], v[144:147], v[178:181], v[112:115]
	v_mfma_f32_16x16x32_bf16 v[100:103], v[136:139], v[208:211], v[100:103]
	v_mfma_f32_16x16x32_bf16 v[96:99], v[144:147], v[208:211], v[96:99]
	v_mfma_f32_16x16x32_bf16 v[84:87], v[136:139], v[216:219], v[84:87]
	v_mfma_f32_16x16x32_bf16 v[80:83], v[144:147], v[216:219], v[80:83]
	v_mfma_f32_16x16x32_bf16 v[124:127], v[140:143], v[174:177], v[124:127]
	v_mfma_f32_16x16x32_bf16 v[120:123], v[148:151], v[174:177], v[120:123]
	v_mfma_f32_16x16x32_bf16 v[116:119], v[140:143], v[204:207], v[116:119]
	v_mfma_f32_16x16x32_bf16 v[112:115], v[148:151], v[204:207], v[112:115]
	v_mfma_f32_16x16x32_bf16 v[100:103], v[140:143], v[212:215], v[100:103]
	v_mfma_f32_16x16x32_bf16 v[96:99], v[148:151], v[212:215], v[96:99]
	v_mfma_f32_16x16x32_bf16 v[84:87], v[140:143], v[220:223], v[84:87]
	v_mfma_f32_16x16x32_bf16 v[80:83], v[148:151], v[220:223], v[80:83]
	s_setprio 0
	s_setprio 1
	v_mfma_f32_16x16x32_bf16 v[108:111], v[152:155], v[170:173], v[108:111]
	v_mfma_f32_16x16x32_bf16 v[104:107], v[162:165], v[170:173], v[104:107]
	v_mfma_f32_16x16x32_bf16 v[92:95], v[152:155], v[178:181], v[92:95]
	v_mfma_f32_16x16x32_bf16 v[88:91], v[162:165], v[178:181], v[88:91]
	v_mfma_f32_16x16x32_bf16 v[76:79], v[152:155], v[208:211], v[76:79]
	v_mfma_f32_16x16x32_bf16 v[72:75], v[162:165], v[208:211], v[72:75]
	v_mfma_f32_16x16x32_bf16 v[68:71], v[152:155], v[216:219], v[68:71]
	v_mfma_f32_16x16x32_bf16 v[64:67], v[162:165], v[216:219], v[64:67]
	v_mfma_f32_16x16x32_bf16 v[108:111], v[156:159], v[174:177], v[108:111]
	v_mfma_f32_16x16x32_bf16 v[104:107], v[166:169], v[174:177], v[104:107]
	v_mfma_f32_16x16x32_bf16 v[92:95], v[156:159], v[204:207], v[92:95]
	v_mfma_f32_16x16x32_bf16 v[88:91], v[166:169], v[204:207], v[88:91]
	s_setprio 2
	s_barrier
	v_mfma_f32_16x16x32_bf16 v[76:79], v[156:159], v[212:215], v[76:79]
	v_mfma_f32_16x16x32_bf16 v[72:75], v[166:169], v[212:215], v[72:75]
	v_mfma_f32_16x16x32_bf16 v[68:71], v[156:159], v[220:223], v[68:71]
	v_mfma_f32_16x16x32_bf16 v[64:67], v[166:169], v[220:223], v[64:67]
	s_setprio 0
	s_mov_b32 m0, s28
	v_lshl_add_u64 v[224:225], s[62:63], 0, v[160:161]
	ds_read_b128 v[170:173], v135 offset:16384
	ds_read_b128 v[174:177], v135 offset:17408
	ds_read_b128 v[178:181], v135 offset:18432
	ds_read_b128 v[204:207], v135 offset:19456
	ds_read_b128 v[208:211], v135 offset:20480
	ds_read_b128 v[212:215], v135 offset:21504
	ds_read_b128 v[216:219], v135 offset:22528
	ds_read_b128 v[220:223], v135 offset:23552
	global_load_lds_dwordx4 v[224:225], off
	v_lshl_add_u64 v[226:227], s[62:63], 0, v[128:129]
	s_mov_b32 m0, s55
	v_lshl_add_u64 v[228:229], s[64:65], 0, v[160:161]
	global_load_lds_dwordx4 v[226:227], off
	s_mov_b32 m0, s36
	v_lshl_add_u64 v[230:231], s[60:61], 0, v[130:131]
	global_load_lds_dwordx4 v[228:229], off
	v_lshl_add_u64 v[228:229], s[64:65], 0, v[128:129]
	s_mov_b32 m0, s21
	s_nop 0
	global_load_lds_dwordx4 v[228:229], off
	v_lshl_add_u64 v[228:229], s[60:61], 0, v[132:133]
	s_mov_b32 m0, s80
	s_nop 0
	global_load_lds_dwordx4 v[228:229], off
	s_mov_b32 m0, s31
	s_nop 0
	global_load_lds_dwordx4 v[230:231], off
	s_waitcnt vmcnt(8)
	s_waitcnt lgkmcnt(0)
	s_barrier
; #define PG8_STAGE(bufoff, gbase, voff) do { _Pragma("unroll") for (int _i = 0; _i < 2; ++_i) \
;         __builtin_amdgcn_global_load_lds((const unsigned*)((const char*)(gbase) + (voff)[_i]), (PG8_LAS unsigned*)(lds + (bufoff) + ldsw + _i * 8192), 16, 0, 0); } while (0)
; #define PG8_LDA(dst, b, h) do { _Pragma("unroll") for (int m = 0; m < 4; ++m) _Pragma("unroll") for (int k = 0; k < 2; ++k) dst[m][k] = *(const PG8_LAS bf16x8*)(lds + PG8_SA(b, h) + aoff + m * 2048 + k * 1024); } while (0)
; #define PG8_LDB(dst, b, h) do { _Pragma("unroll") for (int n = 0; n < 2; ++n) _Pragma("unroll") for (int k = 0; k < 2; ++k) dst[n][k] = *(const PG8_LAS bf16x8*)(lds + PG8_SB(b, h) + boff + n * 2048 + k * 1024); } while (0)
; #define PG8_MMA(ai, bj, At, Bt) do { __builtin_amdgcn_s_setprio(1); _Pragma("unroll") for (int m = 0; m < 4; ++m) _Pragma("unroll") for (int n = 0; n < 2; ++n) _Pragma("unroll") for (int k = 0; k < 2; ++k) \
;         acc[ai][bj][m][n] = __builtin_amdgcn_mfma_f32_16x16x32_bf16(Bt[n][k], At[m][k], acc[ai][bj][m][n], 0, 0, 0); __builtin_amdgcn_s_setprio(0); } while (0)
; #define PG8_WAIT_V(n) asm volatile("s_waitcnt vmcnt(" #n ")" ::: "memory")
; #define PG8_WAIT_L(n) asm volatile("s_waitcnt lgkmcnt(" #n ")" ::: "memory")
; #define PG8_BAR __builtin_amdgcn_s_barrier()
; #define PG8_SCHED __builtin_amdgcn_sched_barrier(0)
; template <class Epi, class Sched, bool ALIGN_EPI = false, bool SP2 = false>
; __device__ __forceinline__ void gemm_phase(PG8_LAS unsigned char* lds, const Gemm g, const Sched& S, const Epi& E, int wv) {
;     ...
;             PG8_WAIT_V(8); PG8_WAIT_L(0); PG8_BAR; PG8_MMA(1, 0, At, B0); PG8_MMA(1, 1, At, B1); PG8_BAR; PG8_SCHED;
;             PG8_LDB(B0, 1, 0); PG8_LDB(B1, 1, 1); PG8_SCHED; PG8_LDA(At, 1, 0); PG8_STAGE(PG8_SA(0, 1), a2 + hstep, voffA);
;             PG8_WAIT_V(8); PG8_WAIT_L(0); PG8_BAR; PG8_MMA(0, 0, At, B0); PG8_MMA(0, 1, At, B1); PG8_BAR; PG8_SCHED;
	s_setprio 1
	s_waitcnt lgkmcnt(0)
	v_mfma_f32_16x16x32_bf16 v[60:63], v[136:139], v[170:173], v[60:63]
	v_mfma_f32_16x16x32_bf16 v[56:59], v[144:147], v[170:173], v[56:59]
	v_mfma_f32_16x16x32_bf16 v[52:55], v[136:139], v[178:181], v[52:55]
	v_mfma_f32_16x16x32_bf16 v[48:51], v[144:147], v[178:181], v[48:51]
	v_mfma_f32_16x16x32_bf16 v[36:39], v[136:139], v[208:211], v[36:39]
	v_mfma_f32_16x16x32_bf16 v[32:35], v[144:147], v[208:211], v[32:35]
	v_mfma_f32_16x16x32_bf16 v[20:23], v[136:139], v[216:219], v[20:23]
	v_mfma_f32_16x16x32_bf16 v[16:19], v[144:147], v[216:219], v[16:19]
	v_mfma_f32_16x16x32_bf16 v[60:63], v[140:143], v[174:177], v[60:63]
	v_mfma_f32_16x16x32_bf16 v[56:59], v[148:151], v[174:177], v[56:59]
	v_mfma_f32_16x16x32_bf16 v[52:55], v[140:143], v[204:207], v[52:55]
	v_mfma_f32_16x16x32_bf16 v[48:51], v[148:151], v[204:207], v[48:51]
	v_mfma_f32_16x16x32_bf16 v[36:39], v[140:143], v[212:215], v[36:39]
	v_mfma_f32_16x16x32_bf16 v[32:35], v[148:151], v[212:215], v[32:35]
	v_mfma_f32_16x16x32_bf16 v[20:23], v[140:143], v[220:223], v[20:23]
	v_mfma_f32_16x16x32_bf16 v[16:19], v[148:151], v[220:223], v[16:19]
	s_setprio 0
	s_setprio 1
	v_mfma_f32_16x16x32_bf16 v[44:47], v[152:155], v[170:173], v[44:47]
	v_mfma_f32_16x16x32_bf16 v[40:43], v[162:165], v[170:173], v[40:43]
	v_mfma_f32_16x16x32_bf16 v[28:31], v[152:155], v[178:181], v[28:31]
	v_mfma_f32_16x16x32_bf16 v[24:27], v[162:165], v[178:181], v[24:27]
	v_mfma_f32_16x16x32_bf16 v[12:15], v[152:155], v[208:211], v[12:15]
	v_mfma_f32_16x16x32_bf16 v[8:11], v[162:165], v[208:211], v[8:11]
	v_mfma_f32_16x16x32_bf16 v[4:7], v[152:155], v[216:219], v[4:7]
	v_mfma_f32_16x16x32_bf16 v[0:3], v[162:165], v[216:219], v[0:3]
	v_mfma_f32_16x16x32_bf16 v[44:47], v[156:159], v[174:177], v[44:47]
	v_mfma_f32_16x16x32_bf16 v[40:43], v[166:169], v[174:177], v[40:43]
	v_mfma_f32_16x16x32_bf16 v[28:31], v[156:159], v[204:207], v[28:31]
	v_mfma_f32_16x16x32_bf16 v[24:27], v[166:169], v[204:207], v[24:27]
	s_setprio 2
	s_barrier
	v_mfma_f32_16x16x32_bf16 v[12:15], v[156:159], v[212:215], v[12:15]
	v_mfma_f32_16x16x32_bf16 v[8:11], v[166:169], v[212:215], v[8:11]
	v_mfma_f32_16x16x32_bf16 v[4:7], v[156:159], v[220:223], v[4:7]
	v_mfma_f32_16x16x32_bf16 v[0:3], v[166:169], v[220:223], v[0:3]
	s_setprio 0
	v_add_u32_e32 v148, s92, v134
	v_add_u32_e32 v166, s94, v134
	ds_read_b128 v[136:139], v148
	ds_read_b128 v[140:143], v148 offset:1024
	ds_read_b128 v[144:147], v148 offset:2048
	ds_read_b128 v[148:151], v148 offset:3072
	ds_read_b128 v[152:155], v166
	ds_read_b128 v[156:159], v166 offset:1024
	ds_read_b128 v[162:165], v166 offset:2048
	ds_read_b128 v[166:169], v166 offset:3072
	s_mov_b32 m0, s54
	v_lshl_add_u64 v[232:233], s[56:57], 0, v[132:133]
	ds_read_b128 v[170:173], v135 offset:32768
	ds_read_b128 v[174:177], v135 offset:33792
	ds_read_b128 v[178:181], v135 offset:34816
	ds_read_b128 v[204:207], v135 offset:35840
	ds_read_b128 v[208:211], v135 offset:36864
	ds_read_b128 v[212:215], v135 offset:37888
	ds_read_b128 v[216:219], v135 offset:38912
	ds_read_b128 v[220:223], v135 offset:39936
	global_load_lds_dwordx4 v[232:233], off
	v_lshl_add_u64 v[232:233], s[56:57], 0, v[130:131]
	s_mov_b32 m0, s66
	s_nop 0
	global_load_lds_dwordx4 v[232:233], off
	s_waitcnt vmcnt(8)
	s_waitcnt lgkmcnt(0)
	s_barrier
	s_setprio 1
	s_waitcnt lgkmcnt(0)
	v_mfma_f32_16x16x32_bf16 v[124:127], v[136:139], v[170:173], v[124:127]
	v_mfma_f32_16x16x32_bf16 v[120:123], v[144:147], v[170:173], v[120:123]
	v_mfma_f32_16x16x32_bf16 v[116:119], v[136:139], v[178:181], v[116:119]
	v_mfma_f32_16x16x32_bf16 v[112:115], v[144:147], v[178:181], v[112:115]
	v_mfma_f32_16x16x32_bf16 v[100:103], v[136:139], v[208:211], v[100:103]
	v_mfma_f32_16x16x32_bf16 v[96:99], v[144:147], v[208:211], v[96:99]
	v_mfma_f32_16x16x32_bf16 v[84:87], v[136:139], v[216:219], v[84:87]
	v_mfma_f32_16x16x32_bf16 v[80:83], v[144:147], v[216:219], v[80:83]
	v_mfma_f32_16x16x32_bf16 v[124:127], v[140:143], v[174:177], v[124:127]
	v_mfma_f32_16x16x32_bf16 v[120:123], v[148:151], v[174:177], v[120:123]
	v_mfma_f32_16x16x32_bf16 v[116:119], v[140:143], v[204:207], v[116:119]
	v_mfma_f32_16x16x32_bf16 v[112:115], v[148:151], v[204:207], v[112:115]
	v_mfma_f32_16x16x32_bf16 v[100:103], v[140:143], v[212:215], v[100:103]
	v_mfma_f32_16x16x32_bf16 v[96:99], v[148:151], v[212:215], v[96:99]
	v_mfma_f32_16x16x32_bf16 v[84:87], v[140:143], v[220:223], v[84:87]
	v_mfma_f32_16x16x32_bf16 v[80:83], v[148:151], v[220:223], v[80:83]
	s_setprio 0
	s_setprio 1
	v_mfma_f32_16x16x32_bf16 v[108:111], v[152:155], v[170:173], v[108:111]
	v_mfma_f32_16x16x32_bf16 v[104:107], v[162:165], v[170:173], v[104:107]
	v_mfma_f32_16x16x32_bf16 v[92:95], v[152:155], v[178:181], v[92:95]
	v_mfma_f32_16x16x32_bf16 v[88:91], v[162:165], v[178:181], v[88:91]
	v_mfma_f32_16x16x32_bf16 v[76:79], v[152:155], v[208:211], v[76:79]
	v_mfma_f32_16x16x32_bf16 v[72:75], v[162:165], v[208:211], v[72:75]
	v_mfma_f32_16x16x32_bf16 v[68:71], v[152:155], v[216:219], v[68:71]
	v_mfma_f32_16x16x32_bf16 v[64:67], v[162:165], v[216:219], v[64:67]
	v_mfma_f32_16x16x32_bf16 v[108:111], v[156:159], v[174:177], v[108:111]
	v_mfma_f32_16x16x32_bf16 v[104:107], v[166:169], v[174:177], v[104:107]
	v_mfma_f32_16x16x32_bf16 v[92:95], v[156:159], v[204:207], v[92:95]
	v_mfma_f32_16x16x32_bf16 v[88:91], v[166:169], v[204:207], v[88:91]
	s_setprio 2
	s_barrier
; #define PG8_STAGE(bufoff, gbase, voff) do { _Pragma("unroll") for (int _i = 0; _i < 2; ++_i) \
;         __builtin_amdgcn_global_load_lds((const unsigned*)((const char*)(gbase) + (voff)[_i]), (PG8_LAS unsigned*)(lds + (bufoff) + ldsw + _i * 8192), 16, 0, 0); } while (0)
; #define PG8_LDA(dst, b, h) do { _Pragma("unroll") for (int m = 0; m < 4; ++m) _Pragma("unroll") for (int k = 0; k < 2; ++k) dst[m][k] = *(const PG8_LAS bf16x8*)(lds + PG8_SA(b, h) + aoff + m * 2048 + k * 1024); } while (0)
; #define PG8_MMA(ai, bj, At, Bt) do { __builtin_amdgcn_s_setprio(1); _Pragma("unroll") for (int m = 0; m < 4; ++m) _Pragma("unroll") for (int n = 0; n < 2; ++n) _Pragma("unroll") for (int k = 0; k < 2; ++k) \
;         acc[ai][bj][m][n] = __builtin_amdgcn_mfma_f32_16x16x32_bf16(Bt[n][k], At[m][k], acc[ai][bj][m][n], 0, 0, 0); __builtin_amdgcn_s_setprio(0); } while (0)
; #define PG8_WAIT_V(n) asm volatile("s_waitcnt vmcnt(" #n ")" ::: "memory")
; #define PG8_WAIT_L(n) asm volatile("s_waitcnt lgkmcnt(" #n ")" ::: "memory")
; #define PG8_BAR __builtin_amdgcn_s_barrier()
; #define PG8_SCHED __builtin_amdgcn_sched_barrier(0)
; template <class Epi, class Sched, bool ALIGN_EPI = false, bool SP2 = false>
; __device__ __forceinline__ void gemm_phase(PG8_LAS unsigned char* lds, const Gemm g, const Sched& S, const Epi& E, int wv) {
;     ...
;             PG8_LDA(At, 1, 1); PG8_STAGE(PG8_SB(1, 0), b3, voffB); PG8_STAGE(PG8_SB(1, 1), b3 + hstep, voffB); PG8_STAGE(PG8_SA(1, 0), a3, voffA);
;             PG8_WAIT_V(8); PG8_WAIT_L(0); PG8_BAR; PG8_MMA(1, 0, At, B0); PG8_MMA(1, 1, At, B1); PG8_BAR; PG8_SCHED;
;     ...
;         if constexpr (ALIGN_EPI) { if (wr == 0) PG8_BAR; }
	v_mfma_f32_16x16x32_bf16 v[76:79], v[156:159], v[212:215], v[76:79]
	v_mfma_f32_16x16x32_bf16 v[72:75], v[166:169], v[212:215], v[72:75]
	v_mfma_f32_16x16x32_bf16 v[68:71], v[156:159], v[220:223], v[68:71]
	v_mfma_f32_16x16x32_bf16 v[64:67], v[166:169], v[220:223], v[64:67]
	s_setprio 0
	s_mov_b32 m0, s93
	v_lshl_add_u64 v[224:225], v[224:225], 0, s[74:75]
	ds_read_b128 v[170:173], v135 offset:49152
	ds_read_b128 v[174:177], v135 offset:50176
	ds_read_b128 v[178:181], v135 offset:51200
	ds_read_b128 v[204:207], v135 offset:52224
	ds_read_b128 v[208:211], v135 offset:53248
	ds_read_b128 v[212:215], v135 offset:54272
	ds_read_b128 v[216:219], v135 offset:55296
	ds_read_b128 v[220:223], v135 offset:56320
	global_load_lds_dwordx4 v[224:225], off
	v_lshl_add_u64 v[224:225], v[226:227], 0, s[74:75]
	s_mov_b32 m0, s88
	s_nop 0
	global_load_lds_dwordx4 v[224:225], off
	v_lshl_add_u64 v[224:225], s[52:53], 0, v[160:161]
	s_mov_b32 m0, s58
	s_nop 0
	global_load_lds_dwordx4 v[224:225], off
	v_lshl_add_u64 v[224:225], s[52:53], 0, v[128:129]
	s_mov_b32 m0, s26
	s_nop 0
	global_load_lds_dwordx4 v[224:225], off
	v_lshl_add_u64 v[224:225], v[228:229], 0, s[74:75]
	s_mov_b32 m0, s81
	s_nop 0
	global_load_lds_dwordx4 v[224:225], off
	v_lshl_add_u64 v[224:225], v[230:231], 0, s[74:75]
	s_mov_b32 m0, s89
	s_nop 0
	global_load_lds_dwordx4 v[224:225], off
	s_waitcnt vmcnt(8)
	s_waitcnt lgkmcnt(0)
	s_barrier
	s_setprio 1
	s_waitcnt lgkmcnt(0)
	v_mfma_f32_16x16x32_bf16 v[60:63], v[136:139], v[170:173], v[60:63]
	v_mfma_f32_16x16x32_bf16 v[56:59], v[144:147], v[170:173], v[56:59]
	v_mfma_f32_16x16x32_bf16 v[52:55], v[136:139], v[178:181], v[52:55]
	v_mfma_f32_16x16x32_bf16 v[48:51], v[144:147], v[178:181], v[48:51]
	v_mfma_f32_16x16x32_bf16 v[36:39], v[136:139], v[208:211], v[36:39]
	v_mfma_f32_16x16x32_bf16 v[32:35], v[144:147], v[208:211], v[32:35]
	v_mfma_f32_16x16x32_bf16 v[20:23], v[136:139], v[216:219], v[20:23]
	v_mfma_f32_16x16x32_bf16 v[16:19], v[144:147], v[216:219], v[16:19]
	v_mfma_f32_16x16x32_bf16 v[60:63], v[140:143], v[174:177], v[60:63]
	v_mfma_f32_16x16x32_bf16 v[56:59], v[148:151], v[174:177], v[56:59]
	v_mfma_f32_16x16x32_bf16 v[52:55], v[140:143], v[204:207], v[52:55]
	v_mfma_f32_16x16x32_bf16 v[48:51], v[148:151], v[204:207], v[48:51]
	v_mfma_f32_16x16x32_bf16 v[36:39], v[140:143], v[212:215], v[36:39]
	v_mfma_f32_16x16x32_bf16 v[32:35], v[148:151], v[212:215], v[32:35]
	v_mfma_f32_16x16x32_bf16 v[20:23], v[140:143], v[220:223], v[20:23]
	v_mfma_f32_16x16x32_bf16 v[16:19], v[148:151], v[220:223], v[16:19]
	s_setprio 0
	s_setprio 1
	v_mfma_f32_16x16x32_bf16 v[44:47], v[152:155], v[170:173], v[44:47]
	v_mfma_f32_16x16x32_bf16 v[40:43], v[162:165], v[170:173], v[40:43]
	v_mfma_f32_16x16x32_bf16 v[28:31], v[152:155], v[178:181], v[28:31]
	v_mfma_f32_16x16x32_bf16 v[24:27], v[162:165], v[178:181], v[24:27]
	v_mfma_f32_16x16x32_bf16 v[12:15], v[152:155], v[208:211], v[12:15]
	v_mfma_f32_16x16x32_bf16 v[8:11], v[162:165], v[208:211], v[8:11]
	v_mfma_f32_16x16x32_bf16 v[4:7], v[152:155], v[216:219], v[4:7]
	v_mfma_f32_16x16x32_bf16 v[0:3], v[162:165], v[216:219], v[0:3]
	v_mfma_f32_16x16x32_bf16 v[44:47], v[156:159], v[174:177], v[44:47]
	v_mfma_f32_16x16x32_bf16 v[40:43], v[166:169], v[174:177], v[40:43]
	v_mfma_f32_16x16x32_bf16 v[28:31], v[156:159], v[204:207], v[28:31]
	v_mfma_f32_16x16x32_bf16 v[24:27], v[166:169], v[204:207], v[24:27]
	s_setprio 2
	s_barrier
	v_mfma_f32_16x16x32_bf16 v[12:15], v[156:159], v[212:215], v[12:15]
	v_mfma_f32_16x16x32_bf16 v[8:11], v[166:169], v[212:215], v[8:11]
	v_mfma_f32_16x16x32_bf16 v[4:7], v[156:159], v[220:223], v[4:7]
	v_mfma_f32_16x16x32_bf16 v[0:3], v[166:169], v[220:223], v[0:3]
	s_setprio 0
	s_movk_i32 s56, 0x100
	s_andn2_b64 vcc, exec, s[50:51]
	s_mov_b64 s[52:53], -1
	s_mov_b64 s[50:51], 0
	s_cbranch_vccz .LBB0_2213
	s_and_b64 vcc, exec, s[8:9]
	s_cbranch_vccz .LBB0_2216
	s_barrier

; #define PG8_STAGE(bufoff, gbase, voff) do { _Pragma("unroll") for (int _i = 0; _i < 2; ++_i) \
;         __builtin_amdgcn_global_load_lds((const unsigned*)((const char*)(gbase) + (voff)[_i]), (PG8_LAS unsigned*)(lds + (bufoff) + ldsw + _i * 8192), 16, 0, 0); } while (0)
; #define PG8_LDA(dst, b, h) do { _Pragma("unroll") for (int m = 0; m < 4; ++m) _Pragma("unroll") for (int k = 0; k < 2; ++k) dst[m][k] = *(const PG8_LAS bf16x8*)(lds + PG8_SA(b, h) + aoff + m * 2048 + k * 1024); } while (0)
; #define PG8_LDB(dst, b, h) do { _Pragma("unroll") for (int n = 0; n < 2; ++n) _Pragma("unroll") for (int k = 0; k < 2; ++k) dst[n][k] = *(const PG8_LAS bf16x8*)(lds + PG8_SB(b, h) + boff + n * 2048 + k * 1024); } while (0)
; #define PG8_MMA(ai, bj, At, Bt) do { __builtin_amdgcn_s_setprio(1); _Pragma("unroll") for (int m = 0; m < 4; ++m) _Pragma("unroll") for (int n = 0; n < 2; ++n) _Pragma("unroll") for (int k = 0; k < 2; ++k) \
;         acc[ai][bj][m][n] = __builtin_amdgcn_mfma_f32_16x16x32_bf16(Bt[n][k], At[m][k], acc[ai][bj][m][n], 0, 0, 0); __builtin_amdgcn_s_setprio(0); } while (0)
; #define PG8_WAIT_V(n) asm volatile("s_waitcnt vmcnt(" #n ")" ::: "memory")
; template <class Epi, class Sched, bool ALIGN_EPI = false, bool SP2 = false>
; __device__ __forceinline__ void gemm_phase(PG8_LAS unsigned char* lds, const Gemm g, const Sched& S, const Epi& E, int wv) {
;     ...
;         const char* nA = has_next ? (const char*)g.A + (size_t)nxt.pm * tstep : cA; const char* nB = has_next ? (const char*)g.Bt + (size_t)nxt.pn * tstep : cB;
;         for (int t = 0; t < nt; t += 2) {
;             const bool last = (t == nt - 2);
;             const char* a1 = cA + (size_t)(t + 1) * kstep;
;             const char* a2 = last ? nA : cA + (size_t)(t + 2) * kstep; const char* b2 = last ? nB : cB + (size_t)(t + 2) * kstep;
;             const char* a3 = a2 + kstep; const char* b3 = b2 + kstep;
;             if (last && has_next) S.a_ready(nxt);
;             if constexpr (SP2) {
;             PG8_LDB(B0, 0, 0); PG8_LDB(B1, 0, 1); PG8_SCHED; PG8_LDA(At, 0, 0); PG8_STAGE(PG8_SA(1, 1), a1 + hstep, voffA);
;             PG8_WAIT_V(8); PG8_WAIT_L(0); PG8_BAR; PG8_MMA(0, 0, At, B0); PG8_MMA(0, 1, At, B1); PG8_BAR; PG8_SCHED;
;             PG8_LDA(At, 0, 1); PG8_STAGE(PG8_SB(0, 0), b2, voffB); PG8_STAGE(PG8_SB(0, 1), b2 + hstep, voffB); PG8_STAGE(PG8_SA(0, 0), a2, voffA);
.LBB0_2281:
	s_add_u32 s6, s4, 0xfffc0080
	s_addc_u32 s7, s5, -1
	s_add_i32 s21, 0, 0x10000
	s_cmp_eq_u32 vcc_hi, 12
	s_cselect_b32 s9, s53, s7
	s_cselect_b32 s8, s81, s6
	s_cselect_b32 s7, s57, vcc_lo
	s_cselect_b32 s6, s83, s91
	s_add_i32 s26, 0, 0x14000
	v_add_u32_e32 v140, s21, v203
	v_add_u32_e32 v156, s26, v203
	ds_read_b128 v[124:127], v140
	ds_read_b128 v[128:131], v140 offset:1024
	ds_read_b128 v[136:139], v140 offset:2048
	ds_read_b128 v[140:143], v140 offset:3072
	ds_read_b128 v[144:147], v156
	ds_read_b128 v[148:151], v156 offset:1024
	ds_read_b128 v[152:155], v156 offset:2048
	ds_read_b128 v[156:159], v156 offset:3072
	v_lshl_add_u64 v[180:181], s[4:5], 0, v[168:169]
	s_add_i32 m0, s66, 0xc000
	ds_read_b128 v[172:175], v204
	ds_read_b128 v[176:179], v204 offset:1024
	ds_read_b128 v[206:209], v204 offset:2048
	ds_read_b128 v[210:213], v204 offset:3072
	ds_read_b128 v[214:217], v204 offset:4096
	ds_read_b128 v[218:221], v204 offset:5120
	ds_read_b128 v[222:225], v204 offset:6144
	ds_read_b128 v[226:229], v204 offset:7168
	global_load_lds_dwordx4 v[180:181], off
	v_lshl_add_u64 v[180:181], s[4:5], 0, v[170:171]
	s_add_i32 m0, s66, 0xe000
	s_nop 0
	global_load_lds_dwordx4 v[180:181], off
	s_waitcnt vmcnt(8)
	s_waitcnt lgkmcnt(0)
	s_barrier
	s_setprio 1
	s_waitcnt lgkmcnt(0)
	v_mfma_f32_16x16x32_bf16 v[132:135], v[124:127], v[172:175], v[132:135]
	v_mfma_f32_16x16x32_bf16 v[120:123], v[136:139], v[172:175], v[120:123]
	v_mfma_f32_16x16x32_bf16 v[108:111], v[124:127], v[206:209], v[108:111]
	v_mfma_f32_16x16x32_bf16 v[104:107], v[136:139], v[206:209], v[104:107]
	v_mfma_f32_16x16x32_bf16 v[92:95], v[124:127], v[214:217], v[92:95]
	v_mfma_f32_16x16x32_bf16 v[88:91], v[136:139], v[214:217], v[88:91]
	v_mfma_f32_16x16x32_bf16 v[76:79], v[124:127], v[222:225], v[76:79]
	v_mfma_f32_16x16x32_bf16 v[72:75], v[136:139], v[222:225], v[72:75]
	v_mfma_f32_16x16x32_bf16 v[132:135], v[128:131], v[176:179], v[132:135]
	v_mfma_f32_16x16x32_bf16 v[120:123], v[140:143], v[176:179], v[120:123]
	v_mfma_f32_16x16x32_bf16 v[108:111], v[128:131], v[210:213], v[108:111]
	v_mfma_f32_16x16x32_bf16 v[104:107], v[140:143], v[210:213], v[104:107]
	v_mfma_f32_16x16x32_bf16 v[92:95], v[128:131], v[218:221], v[92:95]
	v_mfma_f32_16x16x32_bf16 v[88:91], v[140:143], v[218:221], v[88:91]
	v_mfma_f32_16x16x32_bf16 v[76:79], v[128:131], v[226:229], v[76:79]
	v_mfma_f32_16x16x32_bf16 v[72:75], v[140:143], v[226:229], v[72:75]
	s_setprio 0
	s_setprio 1
	v_mfma_f32_16x16x32_bf16 v[116:119], v[144:147], v[172:175], v[116:119]
	v_mfma_f32_16x16x32_bf16 v[112:115], v[152:155], v[172:175], v[112:115]
	v_mfma_f32_16x16x32_bf16 v[100:103], v[144:147], v[206:209], v[100:103]
	v_mfma_f32_16x16x32_bf16 v[96:99], v[152:155], v[206:209], v[96:99]
	v_mfma_f32_16x16x32_bf16 v[84:87], v[144:147], v[214:217], v[84:87]
	v_mfma_f32_16x16x32_bf16 v[80:83], v[152:155], v[214:217], v[80:83]
	v_mfma_f32_16x16x32_bf16 v[68:71], v[144:147], v[222:225], v[68:71]
	v_mfma_f32_16x16x32_bf16 v[64:67], v[152:155], v[222:225], v[64:67]
	v_mfma_f32_16x16x32_bf16 v[116:119], v[148:151], v[176:179], v[116:119]
	v_mfma_f32_16x16x32_bf16 v[112:115], v[156:159], v[176:179], v[112:115]
	v_mfma_f32_16x16x32_bf16 v[100:103], v[148:151], v[210:213], v[100:103]
	v_mfma_f32_16x16x32_bf16 v[96:99], v[156:159], v[210:213], v[96:99]
	s_setprio 2
	s_barrier
	v_mfma_f32_16x16x32_bf16 v[84:87], v[148:151], v[218:221], v[84:87]
	v_mfma_f32_16x16x32_bf16 v[80:83], v[156:159], v[218:221], v[80:83]
	v_mfma_f32_16x16x32_bf16 v[68:71], v[148:151], v[226:229], v[68:71]
	v_mfma_f32_16x16x32_bf16 v[64:67], v[156:159], v[226:229], v[64:67]
	s_setprio 0
	s_add_i32 s21, s21, s31
	v_lshl_add_u64 v[180:181], s[6:7], 0, v[160:161]
	s_mov_b32 m0, s21
	ds_read_b128 v[172:175], v204 offset:16384
	ds_read_b128 v[176:179], v204 offset:17408
	ds_read_b128 v[206:209], v204 offset:18432
	ds_read_b128 v[210:213], v204 offset:19456
	ds_read_b128 v[214:217], v204 offset:20480
	ds_read_b128 v[218:221], v204 offset:21504
	ds_read_b128 v[222:225], v204 offset:22528
	ds_read_b128 v[226:229], v204 offset:23552
	global_load_lds_dwordx4 v[180:181], off
	s_add_i32 m0, s21, 0x2000
	s_add_u32 s92, s6, 0x40000
	v_lshl_add_u64 v[230:231], s[6:7], 0, v[162:163]
	s_addc_u32 s93, s7, 0
	s_add_i32 s21, s26, s31
	global_load_lds_dwordx4 v[230:231], off
	v_lshl_add_u64 v[232:233], s[92:93], 0, v[160:161]
	s_mov_b32 m0, s21
	v_lshl_add_u64 v[234:235], s[8:9], 0, v[164:165]
	global_load_lds_dwordx4 v[232:233], off
	v_lshl_add_u64 v[232:233], s[92:93], 0, v[162:163]
	s_add_i32 m0, s21, 0x2000
	s_nop 0
	global_load_lds_dwordx4 v[232:233], off
	v_lshl_add_u64 v[232:233], s[8:9], 0, v[166:167]
	s_mov_b32 m0, s66
	s_nop 0
	global_load_lds_dwordx4 v[232:233], off
	s_mov_b32 m0, s67
	s_nop 0
	global_load_lds_dwordx4 v[234:235], off
	s_waitcnt vmcnt(8)
	s_waitcnt lgkmcnt(0)
	s_barrier
; #define PG8_STAGE(bufoff, gbase, voff) do { _Pragma("unroll") for (int _i = 0; _i < 2; ++_i) \
;         __builtin_amdgcn_global_load_lds((const unsigned*)((const char*)(gbase) + (voff)[_i]), (PG8_LAS unsigned*)(lds + (bufoff) + ldsw + _i * 8192), 16, 0, 0); } while (0)
; #define PG8_LDA(dst, b, h) do { _Pragma("unroll") for (int m = 0; m < 4; ++m) _Pragma("unroll") for (int k = 0; k < 2; ++k) dst[m][k] = *(const PG8_LAS bf16x8*)(lds + PG8_SA(b, h) + aoff + m * 2048 + k * 1024); } while (0)
; #define PG8_LDB(dst, b, h) do { _Pragma("unroll") for (int n = 0; n < 2; ++n) _Pragma("unroll") for (int k = 0; k < 2; ++k) dst[n][k] = *(const PG8_LAS bf16x8*)(lds + PG8_SB(b, h) + boff + n * 2048 + k * 1024); } while (0)
; #define PG8_MMA(ai, bj, At, Bt) do { __builtin_amdgcn_s_setprio(1); _Pragma("unroll") for (int m = 0; m < 4; ++m) _Pragma("unroll") for (int n = 0; n < 2; ++n) _Pragma("unroll") for (int k = 0; k < 2; ++k) \
;         acc[ai][bj][m][n] = __builtin_amdgcn_mfma_f32_16x16x32_bf16(Bt[n][k], At[m][k], acc[ai][bj][m][n], 0, 0, 0); __builtin_amdgcn_s_setprio(0); } while (0)
; #define PG8_WAIT_V(n) asm volatile("s_waitcnt vmcnt(" #n ")" ::: "memory")
; #define PG8_WAIT_L(n) asm volatile("s_waitcnt lgkmcnt(" #n ")" ::: "memory")
; #define PG8_BAR __builtin_amdgcn_s_barrier()
; #define PG8_SCHED __builtin_amdgcn_sched_barrier(0)
; template <class Epi, class Sched, bool ALIGN_EPI = false, bool SP2 = false>
; __device__ __forceinline__ void gemm_phase(PG8_LAS unsigned char* lds, const Gemm g, const Sched& S, const Epi& E, int wv) {
;     ...
;             PG8_WAIT_V(8); PG8_WAIT_L(0); PG8_BAR; PG8_MMA(1, 0, At, B0); PG8_MMA(1, 1, At, B1); PG8_BAR; PG8_SCHED;
;             PG8_LDB(B0, 1, 0); PG8_LDB(B1, 1, 1); PG8_SCHED; PG8_LDA(At, 1, 0); PG8_STAGE(PG8_SA(0, 1), a2 + hstep, voffA);
;             PG8_WAIT_V(8); PG8_WAIT_L(0); PG8_BAR; PG8_MMA(0, 0, At, B0); PG8_MMA(0, 1, At, B1); PG8_BAR; PG8_SCHED;
	s_setprio 1
	s_waitcnt lgkmcnt(0)
	v_mfma_f32_16x16x32_bf16 v[60:63], v[124:127], v[172:175], v[60:63]
	v_mfma_f32_16x16x32_bf16 v[56:59], v[136:139], v[172:175], v[56:59]
	v_mfma_f32_16x16x32_bf16 v[44:47], v[124:127], v[206:209], v[44:47]
	v_mfma_f32_16x16x32_bf16 v[40:43], v[136:139], v[206:209], v[40:43]
	v_mfma_f32_16x16x32_bf16 v[28:31], v[124:127], v[214:217], v[28:31]
	v_mfma_f32_16x16x32_bf16 v[24:27], v[136:139], v[214:217], v[24:27]
	v_mfma_f32_16x16x32_bf16 v[12:15], v[124:127], v[222:225], v[12:15]
	v_mfma_f32_16x16x32_bf16 v[8:11], v[136:139], v[222:225], v[8:11]
	v_mfma_f32_16x16x32_bf16 v[60:63], v[128:131], v[176:179], v[60:63]
	v_mfma_f32_16x16x32_bf16 v[56:59], v[140:143], v[176:179], v[56:59]
	v_mfma_f32_16x16x32_bf16 v[44:47], v[128:131], v[210:213], v[44:47]
	v_mfma_f32_16x16x32_bf16 v[40:43], v[140:143], v[210:213], v[40:43]
	v_mfma_f32_16x16x32_bf16 v[28:31], v[128:131], v[218:221], v[28:31]
	v_mfma_f32_16x16x32_bf16 v[24:27], v[140:143], v[218:221], v[24:27]
	v_mfma_f32_16x16x32_bf16 v[12:15], v[128:131], v[226:229], v[12:15]
	v_mfma_f32_16x16x32_bf16 v[8:11], v[140:143], v[226:229], v[8:11]
	s_setprio 0
	s_setprio 1
	v_mfma_f32_16x16x32_bf16 v[52:55], v[144:147], v[172:175], v[52:55]
	v_mfma_f32_16x16x32_bf16 v[48:51], v[152:155], v[172:175], v[48:51]
	v_mfma_f32_16x16x32_bf16 v[36:39], v[144:147], v[206:209], v[36:39]
	v_mfma_f32_16x16x32_bf16 v[32:35], v[152:155], v[206:209], v[32:35]
	v_mfma_f32_16x16x32_bf16 v[20:23], v[144:147], v[214:217], v[20:23]
	v_mfma_f32_16x16x32_bf16 v[16:19], v[152:155], v[214:217], v[16:19]
	v_mfma_f32_16x16x32_bf16 v[4:7], v[144:147], v[222:225], v[4:7]
	v_mfma_f32_16x16x32_bf16 v[0:3], v[152:155], v[222:225], v[0:3]
	v_mfma_f32_16x16x32_bf16 v[52:55], v[148:151], v[176:179], v[52:55]
	v_mfma_f32_16x16x32_bf16 v[48:51], v[156:159], v[176:179], v[48:51]
	v_mfma_f32_16x16x32_bf16 v[36:39], v[148:151], v[210:213], v[36:39]
	v_mfma_f32_16x16x32_bf16 v[32:35], v[156:159], v[210:213], v[32:35]
	s_setprio 2
	s_barrier
	v_mfma_f32_16x16x32_bf16 v[20:23], v[148:151], v[218:221], v[20:23]
	v_mfma_f32_16x16x32_bf16 v[16:19], v[156:159], v[218:221], v[16:19]
	v_mfma_f32_16x16x32_bf16 v[4:7], v[148:151], v[226:229], v[4:7]
	v_mfma_f32_16x16x32_bf16 v[0:3], v[156:159], v[226:229], v[0:3]
	s_setprio 0
	s_add_i32 s21, 0, 0x18000
	s_add_i32 s26, 0, 0x1c000
	v_add_u32_e32 v140, s21, v203
	v_add_u32_e32 v156, s26, v203
	ds_read_b128 v[124:127], v140
	ds_read_b128 v[128:131], v140 offset:1024
	ds_read_b128 v[136:139], v140 offset:2048
	ds_read_b128 v[140:143], v140 offset:3072
	ds_read_b128 v[144:147], v156
	ds_read_b128 v[148:151], v156 offset:1024
	ds_read_b128 v[152:155], v156 offset:2048
	ds_read_b128 v[156:159], v156 offset:3072
	s_add_u32 s8, s8, 0x40000
	s_addc_u32 s9, s9, 0
	s_mov_b32 m0, s76
	v_lshl_add_u64 v[236:237], s[8:9], 0, v[166:167]
	ds_read_b128 v[172:175], v204 offset:32768
	ds_read_b128 v[176:179], v204 offset:33792
	ds_read_b128 v[206:209], v204 offset:34816
	ds_read_b128 v[210:213], v204 offset:35840
	ds_read_b128 v[214:217], v204 offset:36864
	ds_read_b128 v[218:221], v204 offset:37888
	ds_read_b128 v[222:225], v204 offset:38912
	ds_read_b128 v[226:229], v204 offset:39936
	global_load_lds_dwordx4 v[236:237], off
	v_lshl_add_u64 v[236:237], s[8:9], 0, v[164:165]
	s_mov_b32 m0, s77
	s_nop 0
	global_load_lds_dwordx4 v[236:237], off
	s_waitcnt vmcnt(8)
	s_waitcnt lgkmcnt(0)
	s_barrier
	s_setprio 1
	s_waitcnt lgkmcnt(0)
	v_mfma_f32_16x16x32_bf16 v[132:135], v[124:127], v[172:175], v[132:135]
	v_mfma_f32_16x16x32_bf16 v[120:123], v[136:139], v[172:175], v[120:123]
	v_mfma_f32_16x16x32_bf16 v[108:111], v[124:127], v[206:209], v[108:111]
	v_mfma_f32_16x16x32_bf16 v[104:107], v[136:139], v[206:209], v[104:107]
	v_mfma_f32_16x16x32_bf16 v[92:95], v[124:127], v[214:217], v[92:95]
	v_mfma_f32_16x16x32_bf16 v[88:91], v[136:139], v[214:217], v[88:91]
	v_mfma_f32_16x16x32_bf16 v[76:79], v[124:127], v[222:225], v[76:79]
	v_mfma_f32_16x16x32_bf16 v[72:75], v[136:139], v[222:225], v[72:75]
	v_mfma_f32_16x16x32_bf16 v[132:135], v[128:131], v[176:179], v[132:135]
	v_mfma_f32_16x16x32_bf16 v[120:123], v[140:143], v[176:179], v[120:123]
	v_mfma_f32_16x16x32_bf16 v[108:111], v[128:131], v[210:213], v[108:111]
	v_mfma_f32_16x16x32_bf16 v[104:107], v[140:143], v[210:213], v[104:107]
	v_mfma_f32_16x16x32_bf16 v[92:95], v[128:131], v[218:221], v[92:95]
	v_mfma_f32_16x16x32_bf16 v[88:91], v[140:143], v[218:221], v[88:91]
	v_mfma_f32_16x16x32_bf16 v[76:79], v[128:131], v[226:229], v[76:79]
	v_mfma_f32_16x16x32_bf16 v[72:75], v[140:143], v[226:229], v[72:75]
	s_setprio 0
	s_setprio 1
	v_mfma_f32_16x16x32_bf16 v[116:119], v[144:147], v[172:175], v[116:119]
	v_mfma_f32_16x16x32_bf16 v[112:115], v[152:155], v[172:175], v[112:115]
	v_mfma_f32_16x16x32_bf16 v[100:103], v[144:147], v[206:209], v[100:103]
	v_mfma_f32_16x16x32_bf16 v[96:99], v[152:155], v[206:209], v[96:99]
	v_mfma_f32_16x16x32_bf16 v[84:87], v[144:147], v[214:217], v[84:87]
	v_mfma_f32_16x16x32_bf16 v[80:83], v[152:155], v[214:217], v[80:83]
	v_mfma_f32_16x16x32_bf16 v[68:71], v[144:147], v[222:225], v[68:71]
	v_mfma_f32_16x16x32_bf16 v[64:67], v[152:155], v[222:225], v[64:67]
	v_mfma_f32_16x16x32_bf16 v[116:119], v[148:151], v[176:179], v[116:119]
	v_mfma_f32_16x16x32_bf16 v[112:115], v[156:159], v[176:179], v[112:115]
	v_mfma_f32_16x16x32_bf16 v[100:103], v[148:151], v[210:213], v[100:103]
	v_mfma_f32_16x16x32_bf16 v[96:99], v[156:159], v[210:213], v[96:99]
	s_setprio 2
	s_barrier
; #define PG8_STAGE(bufoff, gbase, voff) do { _Pragma("unroll") for (int _i = 0; _i < 2; ++_i) \
;         __builtin_amdgcn_global_load_lds((const unsigned*)((const char*)(gbase) + (voff)[_i]), (PG8_LAS unsigned*)(lds + (bufoff) + ldsw + _i * 8192), 16, 0, 0); } while (0)
; #define PG8_LDA(dst, b, h) do { _Pragma("unroll") for (int m = 0; m < 4; ++m) _Pragma("unroll") for (int k = 0; k < 2; ++k) dst[m][k] = *(const PG8_LAS bf16x8*)(lds + PG8_SA(b, h) + aoff + m * 2048 + k * 1024); } while (0)
; #define PG8_MMA(ai, bj, At, Bt) do { __builtin_amdgcn_s_setprio(1); _Pragma("unroll") for (int m = 0; m < 4; ++m) _Pragma("unroll") for (int n = 0; n < 2; ++n) _Pragma("unroll") for (int k = 0; k < 2; ++k) \
;         acc[ai][bj][m][n] = __builtin_amdgcn_mfma_f32_16x16x32_bf16(Bt[n][k], At[m][k], acc[ai][bj][m][n], 0, 0, 0); __builtin_amdgcn_s_setprio(0); } while (0)
; #define PG8_WAIT_V(n) asm volatile("s_waitcnt vmcnt(" #n ")" ::: "memory")
; #define PG8_WAIT_L(n) asm volatile("s_waitcnt lgkmcnt(" #n ")" ::: "memory")
; #define PG8_BAR __builtin_amdgcn_s_barrier()
; #define PG8_SCHED __builtin_amdgcn_sched_barrier(0)
; template <class Epi, class Sched, bool ALIGN_EPI = false, bool SP2 = false>
; __device__ __forceinline__ void gemm_phase(PG8_LAS unsigned char* lds, const Gemm g, const Sched& S, const Epi& E, int wv) {
;     ...
;             PG8_LDA(At, 1, 1); PG8_STAGE(PG8_SB(1, 0), b3, voffB); PG8_STAGE(PG8_SB(1, 1), b3 + hstep, voffB); PG8_STAGE(PG8_SA(1, 0), a3, voffA);
;             PG8_WAIT_V(8); PG8_WAIT_L(0); PG8_BAR; PG8_MMA(1, 0, At, B0); PG8_MMA(1, 1, At, B1); PG8_BAR; PG8_SCHED;
;     ...
;         if constexpr (ALIGN_EPI) { if (wr == 0) PG8_BAR; }
	v_mfma_f32_16x16x32_bf16 v[84:87], v[148:151], v[218:221], v[84:87]
	v_mfma_f32_16x16x32_bf16 v[80:83], v[156:159], v[218:221], v[80:83]
	v_mfma_f32_16x16x32_bf16 v[68:71], v[148:151], v[226:229], v[68:71]
	v_mfma_f32_16x16x32_bf16 v[64:67], v[156:159], v[226:229], v[64:67]
	s_setprio 0
	s_add_i32 s8, s21, s31
	v_lshl_add_u64 v[180:181], v[180:181], 0, s[74:75]
	s_mov_b32 m0, s8
	ds_read_b128 v[172:175], v204 offset:49152
	ds_read_b128 v[176:179], v204 offset:50176
	ds_read_b128 v[206:209], v204 offset:51200
	ds_read_b128 v[210:213], v204 offset:52224
	ds_read_b128 v[214:217], v204 offset:53248
	ds_read_b128 v[218:221], v204 offset:54272
	ds_read_b128 v[222:225], v204 offset:55296
	ds_read_b128 v[226:229], v204 offset:56320
	global_load_lds_dwordx4 v[180:181], off
	s_add_i32 m0, s8, 0x2000
	s_add_u32 s6, s6, 0x40080
	v_lshl_add_u64 v[180:181], v[230:231], 0, s[74:75]
	s_addc_u32 s7, s7, 0
	s_add_i32 s8, s26, s31
	global_load_lds_dwordx4 v[180:181], off
	v_lshl_add_u64 v[180:181], s[6:7], 0, v[160:161]
	s_mov_b32 m0, s8
	s_nop 0
	global_load_lds_dwordx4 v[180:181], off
	v_lshl_add_u64 v[180:181], s[6:7], 0, v[162:163]
	s_add_i32 m0, s8, 0x2000
	s_nop 0
	global_load_lds_dwordx4 v[180:181], off
	v_lshl_add_u64 v[180:181], v[232:233], 0, s[74:75]
	s_mov_b32 m0, s95
	s_nop 0
	global_load_lds_dwordx4 v[180:181], off
	v_lshl_add_u64 v[180:181], v[234:235], 0, s[74:75]
	s_mov_b32 m0, s54
	s_nop 0
	global_load_lds_dwordx4 v[180:181], off
	s_waitcnt vmcnt(8)
	s_waitcnt lgkmcnt(0)
	s_barrier
	s_setprio 1
	s_waitcnt lgkmcnt(0)
	v_mfma_f32_16x16x32_bf16 v[60:63], v[124:127], v[172:175], v[60:63]
	v_mfma_f32_16x16x32_bf16 v[56:59], v[136:139], v[172:175], v[56:59]
	v_mfma_f32_16x16x32_bf16 v[44:47], v[124:127], v[206:209], v[44:47]
	v_mfma_f32_16x16x32_bf16 v[40:43], v[136:139], v[206:209], v[40:43]
	v_mfma_f32_16x16x32_bf16 v[28:31], v[124:127], v[214:217], v[28:31]
	v_mfma_f32_16x16x32_bf16 v[24:27], v[136:139], v[214:217], v[24:27]
	v_mfma_f32_16x16x32_bf16 v[12:15], v[124:127], v[222:225], v[12:15]
	v_mfma_f32_16x16x32_bf16 v[8:11], v[136:139], v[222:225], v[8:11]
	v_mfma_f32_16x16x32_bf16 v[60:63], v[128:131], v[176:179], v[60:63]
	v_mfma_f32_16x16x32_bf16 v[56:59], v[140:143], v[176:179], v[56:59]
	v_mfma_f32_16x16x32_bf16 v[44:47], v[128:131], v[210:213], v[44:47]
	v_mfma_f32_16x16x32_bf16 v[40:43], v[140:143], v[210:213], v[40:43]
	v_mfma_f32_16x16x32_bf16 v[28:31], v[128:131], v[218:221], v[28:31]
	v_mfma_f32_16x16x32_bf16 v[24:27], v[140:143], v[218:221], v[24:27]
	v_mfma_f32_16x16x32_bf16 v[12:15], v[128:131], v[226:229], v[12:15]
	v_mfma_f32_16x16x32_bf16 v[8:11], v[140:143], v[226:229], v[8:11]
	s_setprio 0
	s_setprio 1
	v_mfma_f32_16x16x32_bf16 v[52:55], v[144:147], v[172:175], v[52:55]
	v_mfma_f32_16x16x32_bf16 v[48:51], v[152:155], v[172:175], v[48:51]
	v_mfma_f32_16x16x32_bf16 v[36:39], v[144:147], v[206:209], v[36:39]
	v_mfma_f32_16x16x32_bf16 v[32:35], v[152:155], v[206:209], v[32:35]
	v_mfma_f32_16x16x32_bf16 v[20:23], v[144:147], v[214:217], v[20:23]
	v_mfma_f32_16x16x32_bf16 v[16:19], v[152:155], v[214:217], v[16:19]
	v_mfma_f32_16x16x32_bf16 v[4:7], v[144:147], v[222:225], v[4:7]
	v_mfma_f32_16x16x32_bf16 v[0:3], v[152:155], v[222:225], v[0:3]
	v_mfma_f32_16x16x32_bf16 v[52:55], v[148:151], v[176:179], v[52:55]
	v_mfma_f32_16x16x32_bf16 v[48:51], v[156:159], v[176:179], v[48:51]
	v_mfma_f32_16x16x32_bf16 v[36:39], v[148:151], v[210:213], v[36:39]
	v_mfma_f32_16x16x32_bf16 v[32:35], v[156:159], v[210:213], v[32:35]
	s_setprio 2
	s_barrier
	v_mfma_f32_16x16x32_bf16 v[20:23], v[148:151], v[218:221], v[20:23]
	v_mfma_f32_16x16x32_bf16 v[16:19], v[156:159], v[218:221], v[16:19]
	v_mfma_f32_16x16x32_bf16 v[4:7], v[148:151], v[226:229], v[4:7]
	v_mfma_f32_16x16x32_bf16 v[0:3], v[156:159], v[226:229], v[0:3]
	s_setprio 0
	s_add_i32 vcc_hi, vcc_hi, 2
	s_add_u32 s4, s4, 0x100
	s_addc_u32 s5, s5, 0
	s_add_u32 s91, s91, 0x100
	s_addc_u32 vcc_lo, vcc_lo, 0
	s_cmp_gt_u32 vcc_hi, 13
	s_cbranch_scc0 .LBB0_2281
	s_and_b64 vcc, exec, s[44:45]
	s_cbranch_vccz .LBB0_2284
	s_barrier
